# v37 + xbc conv-weight prefetch + attention O stores via LDS transpose (dwordx4) + MFMA blocks in m-outer serpentine order + nt stores in the P9/P13 residual epilogues
# speedup vs baseline: 1.0031x; 1.0031x over previous
; #define PG8_STAGE(bufoff, gbase, voff) do { _Pragma("unroll") for (int _i = 0; _i < 2; ++_i) \
;         __builtin_amdgcn_global_load_lds((const unsigned*)((const char*)(gbase) + (voff)[_i]), (PG8_LAS unsigned*)(lds + (bufoff) + ldsw + _i * 8192), 16, 0, 0); } while (0)
; #define PG8_LDA(dst, b, h) do { _Pragma("unroll") for (int m = 0; m < 4; ++m) _Pragma("unroll") for (int k = 0; k < 2; ++k) dst[m][k] = *(const PG8_LAS bf16x8*)(lds + PG8_SA(b, h) + aoff + m * 2048 + k * 1024); } while (0)
; #define PG8_LDB(dst, b, h) do { _Pragma("unroll") for (int n = 0; n < 2; ++n) _Pragma("unroll") for (int k = 0; k < 2; ++k) dst[n][k] = *(const PG8_LAS bf16x8*)(lds + PG8_SB(b, h) + boff + n * 2048 + k * 1024); } while (0)
; #define PG8_WAIT_V(n) asm volatile("s_waitcnt vmcnt(" #n ")" ::: "memory")
; #define PG8_WAIT_L(n) asm volatile("s_waitcnt lgkmcnt(" #n ")" ::: "memory")
; #define PG8_BAR __builtin_amdgcn_s_barrier()
; #define PG8_SCHED __builtin_amdgcn_sched_barrier(0)
; template <class Epi, class Sched, bool ALIGN_EPI = false, bool SP2 = false>
; __device__ __forceinline__ void gemm_phase(PG8_LAS unsigned char* lds, const Gemm g, const Sched& S, const Epi& E, int tid_in) {
;     ...
;             PG8_LDB(B0, 0, 0); PG8_LDB(B1, 0, 1); PG8_SCHED; PG8_LDA(At, 0, 0); PG8_STAGE(PG8_SA(1, 1), a1 + hstepA, voffA);
;             PG8_WAIT_V(8); PG8_WAIT_L(0); PG8_BAR; PG8_MMA(0, 0, At, B0); PG8_MMA(0, 1, At, B1); PG8_BAR; PG8_SCHED;
;             PG8_LDA(At, 0, 1); PG8_STAGE(PG8_SB(0, 0), b2, voffB); PG8_STAGE(PG8_SB(0, 1), b2 + hstep, voffB); PG8_STAGE(PG8_SA(0, 0), a2, voffA);
;             PG8_WAIT_V(8); PG8_WAIT_L(0); PG8_BAR; PG8_MMA(1, 0, At, B0); PG8_MMA(1, 1, At, B1); PG8_BAR; PG8_SCHED;
.LBB0_158:
	ds_read_b128 v[112:115], v200
	ds_read_b128 v[116:119], v200 offset:1024
	ds_read_b128 v[136:139], v200 offset:2048
	ds_read_b128 v[140:143], v200 offset:3072
	ds_read_b128 v[172:175], v201
	ds_read_b128 v[176:179], v201 offset:1024
	ds_read_b128 v[180:183], v201 offset:2048
	ds_read_b128 v[184:187], v201 offset:3072
	s_add_u32 s42, s4, 0x100
	s_addc_u32 s43, s5, 0
	s_cmp_eq_u32 s48, 60
	s_cselect_b32 s47, s1, s43
	s_cselect_b32 s46, s19, s42
	s_cselect_b32 s45, s31, s41
	s_cselect_b32 s44, s33, s35
	s_add_i32 m0, s71, 0xc000
	ds_read_b128 v[188:191], v202
	ds_read_b128 v[192:195], v202 offset:1024
	ds_read_b128 v[208:211], v202 offset:2048
	ds_read_b128 v[212:215], v202 offset:3072
	ds_read_b128 v[216:219], v202 offset:4096
	ds_read_b128 v[220:223], v202 offset:5120
	ds_read_b128 v[224:227], v202 offset:6144
	ds_read_b128 v[228:231], v202 offset:7168
	global_load_lds_dwordx4 v160, s[4:5]
	s_add_i32 m0, s71, 0xe000
	s_nop 0
	global_load_lds_dwordx4 v162, s[4:5]
	s_waitcnt vmcnt(8)
	s_waitcnt lgkmcnt(0)
	s_barrier
	s_setprio 1
	s_waitcnt lgkmcnt(0)
	v_mfma_f32_16x16x32_bf16 v[132:135], v[112:115], v[188:191], v[132:135]
	v_mfma_f32_16x16x32_bf16 v[132:135], v[116:119], v[192:195], v[132:135]
	v_mfma_f32_16x16x32_bf16 v[128:131], v[140:143], v[192:195], v[128:131]
	v_mfma_f32_16x16x32_bf16 v[128:131], v[136:139], v[188:191], v[128:131]
	v_mfma_f32_16x16x32_bf16 v[120:123], v[136:139], v[208:211], v[120:123]
	v_mfma_f32_16x16x32_bf16 v[120:123], v[140:143], v[212:215], v[120:123]
	v_mfma_f32_16x16x32_bf16 v[124:127], v[116:119], v[212:215], v[124:127]
	v_mfma_f32_16x16x32_bf16 v[124:127], v[112:115], v[208:211], v[124:127]
	v_mfma_f32_16x16x32_bf16 v[108:111], v[112:115], v[216:219], v[108:111]
	v_mfma_f32_16x16x32_bf16 v[108:111], v[116:119], v[220:223], v[108:111]
	v_mfma_f32_16x16x32_bf16 v[104:107], v[140:143], v[220:223], v[104:107]
	v_mfma_f32_16x16x32_bf16 v[104:107], v[136:139], v[216:219], v[104:107]
	v_mfma_f32_16x16x32_bf16 v[96:99], v[136:139], v[224:227], v[96:99]
	v_mfma_f32_16x16x32_bf16 v[96:99], v[140:143], v[228:231], v[96:99]
	v_mfma_f32_16x16x32_bf16 v[100:103], v[116:119], v[228:231], v[100:103]
	v_mfma_f32_16x16x32_bf16 v[100:103], v[112:115], v[224:227], v[100:103]
	s_setprio 0
	s_setprio 1
	v_mfma_f32_16x16x32_bf16 v[60:63], v[172:175], v[188:191], v[60:63]
	v_mfma_f32_16x16x32_bf16 v[60:63], v[176:179], v[192:195], v[60:63]
	v_mfma_f32_16x16x32_bf16 v[56:59], v[184:187], v[192:195], v[56:59]
	v_mfma_f32_16x16x32_bf16 v[56:59], v[180:183], v[188:191], v[56:59]
	v_mfma_f32_16x16x32_bf16 v[48:51], v[180:183], v[208:211], v[48:51]
	v_mfma_f32_16x16x32_bf16 v[48:51], v[184:187], v[212:215], v[48:51]
	v_mfma_f32_16x16x32_bf16 v[52:55], v[176:179], v[212:215], v[52:55]
	v_mfma_f32_16x16x32_bf16 v[52:55], v[172:175], v[208:211], v[52:55]
	v_mfma_f32_16x16x32_bf16 v[44:47], v[172:175], v[216:219], v[44:47]
	v_mfma_f32_16x16x32_bf16 v[44:47], v[176:179], v[220:223], v[44:47]
	v_mfma_f32_16x16x32_bf16 v[40:43], v[184:187], v[220:223], v[40:43]
	v_mfma_f32_16x16x32_bf16 v[40:43], v[180:183], v[216:219], v[40:43]
	v_mfma_f32_16x16x32_bf16 v[32:35], v[180:183], v[224:227], v[32:35]
	v_mfma_f32_16x16x32_bf16 v[32:35], v[184:187], v[228:231], v[32:35]
	v_mfma_f32_16x16x32_bf16 v[36:39], v[176:179], v[228:231], v[36:39]
	v_mfma_f32_16x16x32_bf16 v[36:39], v[172:175], v[224:227], v[36:39]
	s_setprio 0
	s_barrier
	s_add_u32 s98, s44, 0x80
	s_addc_u32 s99, s45, 0
	s_add_u32 s100, s46, 0x80
	s_addc_u32 s101, s47, 0
	s_add_i32 s4, s91, s70
	s_mov_b32 m0, s4
	ds_read_b128 v[188:191], v202 offset:16384
	ds_read_b128 v[192:195], v202 offset:17408
	ds_read_b128 v[208:211], v202 offset:18432
	ds_read_b128 v[212:215], v202 offset:19456
	ds_read_b128 v[216:219], v202 offset:20480
	ds_read_b128 v[220:223], v202 offset:21504
	ds_read_b128 v[224:227], v202 offset:22528
	ds_read_b128 v[228:231], v202 offset:23552
	global_load_lds_dwordx4 v146, s[44:45]
	s_add_i32 m0, s4, 0x2000
	s_add_u32 s4, s44, 0x100000
	s_addc_u32 s5, s45, 0
	s_add_i32 s49, s92, s70
	global_load_lds_dwordx4 v150, s[44:45]
	s_mov_b32 m0, s49
	s_nop 0
	global_load_lds_dwordx4 v146, s[4:5]
	s_add_i32 m0, s49, 0x2000
	s_nop 0
	global_load_lds_dwordx4 v150, s[4:5]
	s_mov_b32 m0, s71
	s_nop 0
	global_load_lds_dwordx4 v144, s[46:47]
	s_mov_b32 m0, s72
	s_nop 0
	global_load_lds_dwordx4 v148, s[46:47]
	s_waitcnt vmcnt(8)
	s_waitcnt lgkmcnt(0)
	s_barrier
	s_setprio 1
	s_waitcnt lgkmcnt(0)
	v_mfma_f32_16x16x32_bf16 v[92:95], v[112:115], v[188:191], v[92:95]
	v_mfma_f32_16x16x32_bf16 v[92:95], v[116:119], v[192:195], v[92:95]
	v_mfma_f32_16x16x32_bf16 v[88:91], v[140:143], v[192:195], v[88:91]
	v_mfma_f32_16x16x32_bf16 v[88:91], v[136:139], v[188:191], v[88:91]
	v_mfma_f32_16x16x32_bf16 v[80:83], v[136:139], v[208:211], v[80:83]
	v_mfma_f32_16x16x32_bf16 v[80:83], v[140:143], v[212:215], v[80:83]
	v_mfma_f32_16x16x32_bf16 v[84:87], v[116:119], v[212:215], v[84:87]
	v_mfma_f32_16x16x32_bf16 v[84:87], v[112:115], v[208:211], v[84:87]
	v_mfma_f32_16x16x32_bf16 v[76:79], v[112:115], v[216:219], v[76:79]
	v_mfma_f32_16x16x32_bf16 v[76:79], v[116:119], v[220:223], v[76:79]
	v_mfma_f32_16x16x32_bf16 v[72:75], v[140:143], v[220:223], v[72:75]
	v_mfma_f32_16x16x32_bf16 v[72:75], v[136:139], v[216:219], v[72:75]
	v_mfma_f32_16x16x32_bf16 v[64:67], v[136:139], v[224:227], v[64:67]
	v_mfma_f32_16x16x32_bf16 v[64:67], v[140:143], v[228:231], v[64:67]
	v_mfma_f32_16x16x32_bf16 v[68:71], v[116:119], v[228:231], v[68:71]
	v_mfma_f32_16x16x32_bf16 v[68:71], v[112:115], v[224:227], v[68:71]
	s_setprio 0
	s_setprio 1
	v_mfma_f32_16x16x32_bf16 v[28:31], v[172:175], v[188:191], v[28:31]
	v_mfma_f32_16x16x32_bf16 v[28:31], v[176:179], v[192:195], v[28:31]
	v_mfma_f32_16x16x32_bf16 v[24:27], v[184:187], v[192:195], v[24:27]
	v_mfma_f32_16x16x32_bf16 v[24:27], v[180:183], v[188:191], v[24:27]
	v_mfma_f32_16x16x32_bf16 v[16:19], v[180:183], v[208:211], v[16:19]
	v_mfma_f32_16x16x32_bf16 v[16:19], v[184:187], v[212:215], v[16:19]
	v_mfma_f32_16x16x32_bf16 v[20:23], v[176:179], v[212:215], v[20:23]
	v_mfma_f32_16x16x32_bf16 v[20:23], v[172:175], v[208:211], v[20:23]
	v_mfma_f32_16x16x32_bf16 v[12:15], v[172:175], v[216:219], v[12:15]
	v_mfma_f32_16x16x32_bf16 v[12:15], v[176:179], v[220:223], v[12:15]
	v_mfma_f32_16x16x32_bf16 v[8:11], v[184:187], v[220:223], v[8:11]
	v_mfma_f32_16x16x32_bf16 v[8:11], v[180:183], v[216:219], v[8:11]
	v_mfma_f32_16x16x32_bf16 v[0:3], v[180:183], v[224:227], v[0:3]
	v_mfma_f32_16x16x32_bf16 v[0:3], v[184:187], v[228:231], v[0:3]
	v_mfma_f32_16x16x32_bf16 v[4:7], v[176:179], v[228:231], v[4:7]
	v_mfma_f32_16x16x32_bf16 v[4:7], v[172:175], v[224:227], v[4:7]
	s_setprio 0
	s_barrier
; #define PG8_STAGE(bufoff, gbase, voff) do { _Pragma("unroll") for (int _i = 0; _i < 2; ++_i) \
;         __builtin_amdgcn_global_load_lds((const unsigned*)((const char*)(gbase) + (voff)[_i]), (PG8_LAS unsigned*)(lds + (bufoff) + ldsw + _i * 8192), 16, 0, 0); } while (0)
; #define PG8_LDA(dst, b, h) do { _Pragma("unroll") for (int m = 0; m < 4; ++m) _Pragma("unroll") for (int k = 0; k < 2; ++k) dst[m][k] = *(const PG8_LAS bf16x8*)(lds + PG8_SA(b, h) + aoff + m * 2048 + k * 1024); } while (0)
; #define PG8_LDB(dst, b, h) do { _Pragma("unroll") for (int n = 0; n < 2; ++n) _Pragma("unroll") for (int k = 0; k < 2; ++k) dst[n][k] = *(const PG8_LAS bf16x8*)(lds + PG8_SB(b, h) + boff + n * 2048 + k * 1024); } while (0)
; #define PG8_WAIT_V(n) asm volatile("s_waitcnt vmcnt(" #n ")" ::: "memory")
; #define PG8_WAIT_L(n) asm volatile("s_waitcnt lgkmcnt(" #n ")" ::: "memory")
; #define PG8_BAR __builtin_amdgcn_s_barrier()
; #define PG8_SCHED __builtin_amdgcn_sched_barrier(0)
; template <class Epi, class Sched, bool ALIGN_EPI = false, bool SP2 = false>
; __device__ __forceinline__ void gemm_phase(PG8_LAS unsigned char* lds, const Gemm g, const Sched& S, const Epi& E, int tid_in) {
;     ...
;             PG8_LDB(B0, 1, 0); PG8_LDB(B1, 1, 1); PG8_SCHED; PG8_LDA(At, 1, 0); PG8_STAGE(PG8_SA(0, 1), a2 + hstepA, voffA);
;             PG8_WAIT_V(8); PG8_WAIT_L(0); PG8_BAR; PG8_MMA(0, 0, At, B0); PG8_MMA(0, 1, At, B1); PG8_BAR; PG8_SCHED;
;             PG8_LDA(At, 1, 1); PG8_STAGE(PG8_SB(1, 0), b3, voffB); PG8_STAGE(PG8_SB(1, 1), b3 + hstep, voffB); PG8_STAGE(PG8_SA(1, 0), a3, voffA);
;             PG8_WAIT_V(8); PG8_WAIT_L(0); PG8_BAR; PG8_MMA(1, 0, At, B0); PG8_MMA(1, 1, At, B1); PG8_BAR; PG8_SCHED;
	s_add_i32 s49, 0, 0x18000
	s_add_i32 s50, 0, 0x1c000
	v_add_u32_e32 v140, s49, v197
	v_add_u32_e32 v152, s50, v197
	ds_read_b128 v[112:115], v140
	ds_read_b128 v[116:119], v140 offset:1024
	ds_read_b128 v[136:139], v140 offset:2048
	ds_read_b128 v[140:143], v140 offset:3072
	ds_read_b128 v[172:175], v152
	ds_read_b128 v[176:179], v152 offset:1024
	ds_read_b128 v[180:183], v152 offset:2048
	ds_read_b128 v[184:187], v152 offset:3072
	s_add_u32 s4, s46, 0x8000
	s_addc_u32 s5, s47, 0
	s_mov_b32 m0, s73
	ds_read_b128 v[188:191], v202 offset:32768
	ds_read_b128 v[192:195], v202 offset:33792
	ds_read_b128 v[208:211], v202 offset:34816
	ds_read_b128 v[212:215], v202 offset:35840
	ds_read_b128 v[216:219], v202 offset:36864
	ds_read_b128 v[220:223], v202 offset:37888
	ds_read_b128 v[224:227], v202 offset:38912
	ds_read_b128 v[228:231], v202 offset:39936
	global_load_lds_dwordx4 v144, s[4:5]
	s_mov_b32 m0, s74
	s_nop 0
	global_load_lds_dwordx4 v148, s[4:5]
	s_waitcnt vmcnt(8)
	s_waitcnt lgkmcnt(0)
	s_barrier
	s_setprio 1
	s_waitcnt lgkmcnt(0)
	v_mfma_f32_16x16x32_bf16 v[132:135], v[112:115], v[188:191], v[132:135]
	v_mfma_f32_16x16x32_bf16 v[132:135], v[116:119], v[192:195], v[132:135]
	v_mfma_f32_16x16x32_bf16 v[128:131], v[140:143], v[192:195], v[128:131]
	v_mfma_f32_16x16x32_bf16 v[128:131], v[136:139], v[188:191], v[128:131]
	v_mfma_f32_16x16x32_bf16 v[120:123], v[136:139], v[208:211], v[120:123]
	v_mfma_f32_16x16x32_bf16 v[120:123], v[140:143], v[212:215], v[120:123]
	v_mfma_f32_16x16x32_bf16 v[124:127], v[116:119], v[212:215], v[124:127]
	v_mfma_f32_16x16x32_bf16 v[124:127], v[112:115], v[208:211], v[124:127]
	v_mfma_f32_16x16x32_bf16 v[108:111], v[112:115], v[216:219], v[108:111]
	v_mfma_f32_16x16x32_bf16 v[108:111], v[116:119], v[220:223], v[108:111]
	v_mfma_f32_16x16x32_bf16 v[104:107], v[140:143], v[220:223], v[104:107]
	v_mfma_f32_16x16x32_bf16 v[104:107], v[136:139], v[216:219], v[104:107]
	v_mfma_f32_16x16x32_bf16 v[96:99], v[136:139], v[224:227], v[96:99]
	v_mfma_f32_16x16x32_bf16 v[96:99], v[140:143], v[228:231], v[96:99]
	v_mfma_f32_16x16x32_bf16 v[100:103], v[116:119], v[228:231], v[100:103]
	v_mfma_f32_16x16x32_bf16 v[100:103], v[112:115], v[224:227], v[100:103]
	s_setprio 0
	s_setprio 1
	v_mfma_f32_16x16x32_bf16 v[60:63], v[172:175], v[188:191], v[60:63]
	v_mfma_f32_16x16x32_bf16 v[60:63], v[176:179], v[192:195], v[60:63]
	v_mfma_f32_16x16x32_bf16 v[56:59], v[184:187], v[192:195], v[56:59]
	v_mfma_f32_16x16x32_bf16 v[56:59], v[180:183], v[188:191], v[56:59]
	v_mfma_f32_16x16x32_bf16 v[48:51], v[180:183], v[208:211], v[48:51]
	v_mfma_f32_16x16x32_bf16 v[48:51], v[184:187], v[212:215], v[48:51]
	v_mfma_f32_16x16x32_bf16 v[52:55], v[176:179], v[212:215], v[52:55]
	v_mfma_f32_16x16x32_bf16 v[52:55], v[172:175], v[208:211], v[52:55]
	v_mfma_f32_16x16x32_bf16 v[44:47], v[172:175], v[216:219], v[44:47]
	v_mfma_f32_16x16x32_bf16 v[44:47], v[176:179], v[220:223], v[44:47]
	v_mfma_f32_16x16x32_bf16 v[40:43], v[184:187], v[220:223], v[40:43]
	v_mfma_f32_16x16x32_bf16 v[40:43], v[180:183], v[216:219], v[40:43]
	v_mfma_f32_16x16x32_bf16 v[32:35], v[180:183], v[224:227], v[32:35]
	v_mfma_f32_16x16x32_bf16 v[32:35], v[184:187], v[228:231], v[32:35]
	v_mfma_f32_16x16x32_bf16 v[36:39], v[176:179], v[228:231], v[36:39]
	v_mfma_f32_16x16x32_bf16 v[36:39], v[172:175], v[224:227], v[36:39]
	s_setprio 0
	s_barrier
	s_add_i32 s4, s49, s70
	s_mov_b32 m0, s4
	ds_read_b128 v[188:191], v202 offset:49152
	ds_read_b128 v[192:195], v202 offset:50176
	ds_read_b128 v[208:211], v202 offset:51200
	ds_read_b128 v[212:215], v202 offset:52224
	ds_read_b128 v[216:219], v202 offset:53248
	ds_read_b128 v[220:223], v202 offset:54272
	ds_read_b128 v[224:227], v202 offset:55296
	ds_read_b128 v[228:231], v202 offset:56320
	global_load_lds_dwordx4 v146, s[98:99]
	s_add_i32 m0, s4, 0x2000
	s_add_u32 s4, s44, 0x100080
	s_addc_u32 s5, s45, 0
	s_add_i32 s44, s50, s70
	global_load_lds_dwordx4 v150, s[98:99]
	s_mov_b32 m0, s44
	s_nop 0
	global_load_lds_dwordx4 v146, s[4:5]
	s_add_i32 m0, s44, 0x2000
	s_nop 0
	global_load_lds_dwordx4 v150, s[4:5]
	s_mov_b32 m0, s79
	s_nop 0
	global_load_lds_dwordx4 v144, s[100:101]
	s_mov_b32 m0, s61
	s_nop 0
	global_load_lds_dwordx4 v148, s[100:101]
	s_waitcnt vmcnt(8)
	s_waitcnt lgkmcnt(0)
	s_barrier
	s_setprio 1
	s_waitcnt lgkmcnt(0)
	v_mfma_f32_16x16x32_bf16 v[92:95], v[112:115], v[188:191], v[92:95]
	v_mfma_f32_16x16x32_bf16 v[92:95], v[116:119], v[192:195], v[92:95]
	v_mfma_f32_16x16x32_bf16 v[88:91], v[140:143], v[192:195], v[88:91]
	v_mfma_f32_16x16x32_bf16 v[88:91], v[136:139], v[188:191], v[88:91]
	v_mfma_f32_16x16x32_bf16 v[80:83], v[136:139], v[208:211], v[80:83]
	v_mfma_f32_16x16x32_bf16 v[80:83], v[140:143], v[212:215], v[80:83]
	v_mfma_f32_16x16x32_bf16 v[84:87], v[116:119], v[212:215], v[84:87]
	v_mfma_f32_16x16x32_bf16 v[84:87], v[112:115], v[208:211], v[84:87]
	v_mfma_f32_16x16x32_bf16 v[76:79], v[112:115], v[216:219], v[76:79]
	v_mfma_f32_16x16x32_bf16 v[76:79], v[116:119], v[220:223], v[76:79]
	v_mfma_f32_16x16x32_bf16 v[72:75], v[140:143], v[220:223], v[72:75]
	v_mfma_f32_16x16x32_bf16 v[72:75], v[136:139], v[216:219], v[72:75]
	v_mfma_f32_16x16x32_bf16 v[64:67], v[136:139], v[224:227], v[64:67]
	v_mfma_f32_16x16x32_bf16 v[64:67], v[140:143], v[228:231], v[64:67]
	v_mfma_f32_16x16x32_bf16 v[68:71], v[116:119], v[228:231], v[68:71]
	v_mfma_f32_16x16x32_bf16 v[68:71], v[112:115], v[224:227], v[68:71]
	s_setprio 0
	s_setprio 1
	v_mfma_f32_16x16x32_bf16 v[28:31], v[172:175], v[188:191], v[28:31]
	v_mfma_f32_16x16x32_bf16 v[28:31], v[176:179], v[192:195], v[28:31]
	v_mfma_f32_16x16x32_bf16 v[24:27], v[184:187], v[192:195], v[24:27]
	v_mfma_f32_16x16x32_bf16 v[24:27], v[180:183], v[188:191], v[24:27]
	v_mfma_f32_16x16x32_bf16 v[16:19], v[180:183], v[208:211], v[16:19]
	v_mfma_f32_16x16x32_bf16 v[16:19], v[184:187], v[212:215], v[16:19]
	v_mfma_f32_16x16x32_bf16 v[20:23], v[176:179], v[212:215], v[20:23]
	v_mfma_f32_16x16x32_bf16 v[20:23], v[172:175], v[208:211], v[20:23]
	v_mfma_f32_16x16x32_bf16 v[12:15], v[172:175], v[216:219], v[12:15]
	v_mfma_f32_16x16x32_bf16 v[12:15], v[176:179], v[220:223], v[12:15]
	v_mfma_f32_16x16x32_bf16 v[8:11], v[184:187], v[220:223], v[8:11]
	v_mfma_f32_16x16x32_bf16 v[8:11], v[180:183], v[216:219], v[8:11]
	v_mfma_f32_16x16x32_bf16 v[0:3], v[180:183], v[224:227], v[0:3]
	v_mfma_f32_16x16x32_bf16 v[0:3], v[184:187], v[228:231], v[0:3]
	v_mfma_f32_16x16x32_bf16 v[4:7], v[176:179], v[228:231], v[4:7]
	v_mfma_f32_16x16x32_bf16 v[4:7], v[172:175], v[224:227], v[4:7]
	s_setprio 0
	s_barrier
	s_add_i32 s48, s48, 2
	s_add_u32 s35, s35, 0x100
	s_addc_u32 s41, s41, 0
	s_cmp_gt_u32 s48, 61
	s_mov_b64 s[4:5], s[42:43]
	s_cbranch_scc0 .LBB0_158
	s_and_b64 vcc, exec, s[24:25]
	s_cbranch_vccnz .LBB0_163
	v_lshl_add_u32 v172, s0, 8, v198
	s_cmpk_lg_i32 s40, 0x48
	s_mov_b64 s[4:5], -1
	s_cbranch_scc1 .LBB0_164

; #define PG8_STAGE(bufoff, gbase, voff) do { _Pragma("unroll") for (int _i = 0; _i < 2; ++_i) \
;         __builtin_amdgcn_global_load_lds((const unsigned*)((const char*)(gbase) + (voff)[_i]), (PG8_LAS unsigned*)(lds + (bufoff) + ldsw + _i * 8192), 16, 0, 0); } while (0)
; #define PG8_LDA(dst, b, h) do { _Pragma("unroll") for (int m = 0; m < 4; ++m) _Pragma("unroll") for (int k = 0; k < 2; ++k) dst[m][k] = *(const PG8_LAS bf16x8*)(lds + PG8_SA(b, h) + aoff + m * 2048 + k * 1024); } while (0)
; #define PG8_LDB(dst, b, h) do { _Pragma("unroll") for (int n = 0; n < 2; ++n) _Pragma("unroll") for (int k = 0; k < 2; ++k) dst[n][k] = *(const PG8_LAS bf16x8*)(lds + PG8_SB(b, h) + boff + n * 2048 + k * 1024); } while (0)
; #define PG8_WAIT_V(n) asm volatile("s_waitcnt vmcnt(" #n ")" ::: "memory")
; #define PG8_WAIT_L(n) asm volatile("s_waitcnt lgkmcnt(" #n ")" ::: "memory")
; #define PG8_BAR __builtin_amdgcn_s_barrier()
; #define PG8_SCHED __builtin_amdgcn_sched_barrier(0)
; template <class Epi, class Sched, bool ALIGN_EPI = false, bool SP2 = false>
; __device__ __forceinline__ void gemm_phase(PG8_LAS unsigned char* lds, const Gemm g, const Sched& S, const Epi& E, int tid_in) {
;     ...
;             PG8_LDB(B0, 0, 0); PG8_LDB(B1, 0, 1); PG8_SCHED; PG8_LDA(At, 0, 0); PG8_STAGE(PG8_SA(1, 1), a1 + hstepA, voffA);
;             PG8_WAIT_V(8); PG8_WAIT_L(0); PG8_BAR; PG8_MMA(0, 0, At, B0); PG8_MMA(0, 1, At, B1); PG8_BAR; PG8_SCHED;
;             PG8_LDA(At, 0, 1); PG8_STAGE(PG8_SB(0, 0), b2, voffB); PG8_STAGE(PG8_SB(0, 1), b2 + hstep, voffB); PG8_STAGE(PG8_SA(0, 0), a2, voffA);
;             PG8_WAIT_V(8); PG8_WAIT_L(0); PG8_BAR; PG8_MMA(1, 0, At, B0); PG8_MMA(1, 1, At, B1); PG8_BAR; PG8_SCHED;
.LBB0_927:
	ds_read_b128 v[144:147], v151
	ds_read_b128 v[154:157], v151 offset:1024
	ds_read_b128 v[158:161], v151 offset:2048
	ds_read_b128 v[162:165], v151 offset:3072
	ds_read_b128 v[166:169], v152
	ds_read_b128 v[170:173], v152 offset:1024
	ds_read_b128 v[174:177], v152 offset:2048
	ds_read_b128 v[178:181], v152 offset:3072
	s_add_u32 s24, s22, 0xffe00080
	s_addc_u32 s25, s23, -1
	s_cmpk_eq_i32 s50, 0x7c
	s_cselect_b32 s27, s15, s25
	s_cselect_b32 s26, s46, s24
	s_cselect_b32 s25, s13, s49
	s_cselect_b32 s24, s47, s48
	s_add_i32 m0, s21, 0xc000
	ds_read_b128 v[182:185], v153
	ds_read_b128 v[186:189], v153 offset:1024
	ds_read_b128 v[190:193], v153 offset:2048
	ds_read_b128 v[194:197], v153 offset:3072
	ds_read_b128 v[198:201], v153 offset:4096
	ds_read_b128 v[202:205], v153 offset:5120
	ds_read_b128 v[206:209], v153 offset:6144
	ds_read_b128 v[210:213], v153 offset:7168
	global_load_lds_dwordx4 v136, s[22:23]
	s_add_i32 m0, s21, 0xe000
	s_nop 0
	global_load_lds_dwordx4 v138, s[22:23]
	s_waitcnt vmcnt(8)
	s_waitcnt lgkmcnt(0)
	s_barrier
	s_setprio 1
	s_waitcnt lgkmcnt(0)
	v_mfma_f32_16x16x32_bf16 v[124:127], v[144:147], v[182:185], v[124:127]
	v_mfma_f32_16x16x32_bf16 v[124:127], v[154:157], v[186:189], v[124:127]
	v_mfma_f32_16x16x32_bf16 v[120:123], v[162:165], v[186:189], v[120:123]
	v_mfma_f32_16x16x32_bf16 v[120:123], v[158:161], v[182:185], v[120:123]
	v_mfma_f32_16x16x32_bf16 v[104:107], v[158:161], v[190:193], v[104:107]
	v_mfma_f32_16x16x32_bf16 v[104:107], v[162:165], v[194:197], v[104:107]
	v_mfma_f32_16x16x32_bf16 v[108:111], v[154:157], v[194:197], v[108:111]
	v_mfma_f32_16x16x32_bf16 v[108:111], v[144:147], v[190:193], v[108:111]
	v_mfma_f32_16x16x32_bf16 v[92:95], v[144:147], v[198:201], v[92:95]
	v_mfma_f32_16x16x32_bf16 v[92:95], v[154:157], v[202:205], v[92:95]
	v_mfma_f32_16x16x32_bf16 v[88:91], v[162:165], v[202:205], v[88:91]
	v_mfma_f32_16x16x32_bf16 v[88:91], v[158:161], v[198:201], v[88:91]
	v_mfma_f32_16x16x32_bf16 v[72:75], v[158:161], v[206:209], v[72:75]
	v_mfma_f32_16x16x32_bf16 v[72:75], v[162:165], v[210:213], v[72:75]
	v_mfma_f32_16x16x32_bf16 v[76:79], v[154:157], v[210:213], v[76:79]
	v_mfma_f32_16x16x32_bf16 v[76:79], v[144:147], v[206:209], v[76:79]
	s_setprio 0
	s_setprio 1
	v_mfma_f32_16x16x32_bf16 v[116:119], v[166:169], v[182:185], v[116:119]
	v_mfma_f32_16x16x32_bf16 v[116:119], v[170:173], v[186:189], v[116:119]
	v_mfma_f32_16x16x32_bf16 v[112:115], v[178:181], v[186:189], v[112:115]
	v_mfma_f32_16x16x32_bf16 v[112:115], v[174:177], v[182:185], v[112:115]
	v_mfma_f32_16x16x32_bf16 v[96:99], v[174:177], v[190:193], v[96:99]
	v_mfma_f32_16x16x32_bf16 v[96:99], v[178:181], v[194:197], v[96:99]
	v_mfma_f32_16x16x32_bf16 v[100:103], v[170:173], v[194:197], v[100:103]
	v_mfma_f32_16x16x32_bf16 v[100:103], v[166:169], v[190:193], v[100:103]
	v_mfma_f32_16x16x32_bf16 v[84:87], v[166:169], v[198:201], v[84:87]
	v_mfma_f32_16x16x32_bf16 v[84:87], v[170:173], v[202:205], v[84:87]
	v_mfma_f32_16x16x32_bf16 v[80:83], v[178:181], v[202:205], v[80:83]
	v_mfma_f32_16x16x32_bf16 v[80:83], v[174:177], v[198:201], v[80:83]
	v_mfma_f32_16x16x32_bf16 v[64:67], v[174:177], v[206:209], v[64:67]
	v_mfma_f32_16x16x32_bf16 v[64:67], v[178:181], v[210:213], v[64:67]
	v_mfma_f32_16x16x32_bf16 v[68:71], v[170:173], v[210:213], v[68:71]
	v_mfma_f32_16x16x32_bf16 v[68:71], v[166:169], v[206:209], v[68:71]
	s_setprio 0
	s_barrier
	s_add_u32 s98, s24, 0x80
	s_addc_u32 s99, s25, 0
	s_add_u32 s100, s26, 0x80
	s_addc_u32 s101, s27, 0
	s_add_i32 s51, s43, s34
	s_mov_b32 m0, s51
	ds_read_b128 v[182:185], v153 offset:16384
	ds_read_b128 v[186:189], v153 offset:17408
	ds_read_b128 v[190:193], v153 offset:18432
	ds_read_b128 v[194:197], v153 offset:19456
	ds_read_b128 v[198:201], v153 offset:20480
	ds_read_b128 v[202:205], v153 offset:21504
	ds_read_b128 v[206:209], v153 offset:22528
	ds_read_b128 v[210:213], v153 offset:23552
	global_load_lds_dwordx4 v130, s[24:25]
	s_add_i32 m0, s51, 0x2000
	s_add_u32 s52, s24, 0x200000
	s_addc_u32 s53, s25, 0
	s_add_i32 s51, s44, s34
	global_load_lds_dwordx4 v134, s[24:25]
	s_mov_b32 m0, s51
	s_nop 0
	global_load_lds_dwordx4 v130, s[52:53]
	s_add_i32 m0, s51, 0x2000
	s_nop 0
	global_load_lds_dwordx4 v134, s[52:53]
	s_mov_b32 m0, s21
	s_nop 0
	global_load_lds_dwordx4 v128, s[26:27]
	s_mov_b32 m0, s35
	s_nop 0
	global_load_lds_dwordx4 v132, s[26:27]
	s_waitcnt vmcnt(8)
	s_waitcnt lgkmcnt(0)
	s_barrier
	s_setprio 1
	s_waitcnt lgkmcnt(0)
	v_mfma_f32_16x16x32_bf16 v[60:63], v[144:147], v[182:185], v[60:63]
	v_mfma_f32_16x16x32_bf16 v[60:63], v[154:157], v[186:189], v[60:63]
	v_mfma_f32_16x16x32_bf16 v[56:59], v[162:165], v[186:189], v[56:59]
	v_mfma_f32_16x16x32_bf16 v[56:59], v[158:161], v[182:185], v[56:59]
	v_mfma_f32_16x16x32_bf16 v[40:43], v[158:161], v[190:193], v[40:43]
	v_mfma_f32_16x16x32_bf16 v[40:43], v[162:165], v[194:197], v[40:43]
	v_mfma_f32_16x16x32_bf16 v[44:47], v[154:157], v[194:197], v[44:47]
	v_mfma_f32_16x16x32_bf16 v[44:47], v[144:147], v[190:193], v[44:47]
	v_mfma_f32_16x16x32_bf16 v[28:31], v[144:147], v[198:201], v[28:31]
	v_mfma_f32_16x16x32_bf16 v[28:31], v[154:157], v[202:205], v[28:31]
	v_mfma_f32_16x16x32_bf16 v[24:27], v[162:165], v[202:205], v[24:27]
	v_mfma_f32_16x16x32_bf16 v[24:27], v[158:161], v[198:201], v[24:27]
	v_mfma_f32_16x16x32_bf16 v[8:11], v[158:161], v[206:209], v[8:11]
	v_mfma_f32_16x16x32_bf16 v[8:11], v[162:165], v[210:213], v[8:11]
	v_mfma_f32_16x16x32_bf16 v[12:15], v[154:157], v[210:213], v[12:15]
	v_mfma_f32_16x16x32_bf16 v[12:15], v[144:147], v[206:209], v[12:15]
	s_setprio 0
	s_setprio 1
	v_mfma_f32_16x16x32_bf16 v[52:55], v[166:169], v[182:185], v[52:55]
	v_mfma_f32_16x16x32_bf16 v[52:55], v[170:173], v[186:189], v[52:55]
	v_mfma_f32_16x16x32_bf16 v[48:51], v[178:181], v[186:189], v[48:51]
	v_mfma_f32_16x16x32_bf16 v[48:51], v[174:177], v[182:185], v[48:51]
	v_mfma_f32_16x16x32_bf16 v[32:35], v[174:177], v[190:193], v[32:35]
	v_mfma_f32_16x16x32_bf16 v[32:35], v[178:181], v[194:197], v[32:35]
	v_mfma_f32_16x16x32_bf16 v[36:39], v[170:173], v[194:197], v[36:39]
	v_mfma_f32_16x16x32_bf16 v[36:39], v[166:169], v[190:193], v[36:39]
	v_mfma_f32_16x16x32_bf16 v[20:23], v[166:169], v[198:201], v[20:23]
	v_mfma_f32_16x16x32_bf16 v[20:23], v[170:173], v[202:205], v[20:23]
	v_mfma_f32_16x16x32_bf16 v[16:19], v[178:181], v[202:205], v[16:19]
	v_mfma_f32_16x16x32_bf16 v[16:19], v[174:177], v[198:201], v[16:19]
	v_mfma_f32_16x16x32_bf16 v[0:3], v[174:177], v[206:209], v[0:3]
	v_mfma_f32_16x16x32_bf16 v[0:3], v[178:181], v[210:213], v[0:3]
	v_mfma_f32_16x16x32_bf16 v[4:7], v[170:173], v[210:213], v[4:7]
	v_mfma_f32_16x16x32_bf16 v[4:7], v[166:169], v[206:209], v[4:7]
	s_setprio 0
	s_barrier
; #define PG8_STAGE(bufoff, gbase, voff) do { _Pragma("unroll") for (int _i = 0; _i < 2; ++_i) \
;         __builtin_amdgcn_global_load_lds((const unsigned*)((const char*)(gbase) + (voff)[_i]), (PG8_LAS unsigned*)(lds + (bufoff) + ldsw + _i * 8192), 16, 0, 0); } while (0)
; #define PG8_LDA(dst, b, h) do { _Pragma("unroll") for (int m = 0; m < 4; ++m) _Pragma("unroll") for (int k = 0; k < 2; ++k) dst[m][k] = *(const PG8_LAS bf16x8*)(lds + PG8_SA(b, h) + aoff + m * 2048 + k * 1024); } while (0)
; #define PG8_LDB(dst, b, h) do { _Pragma("unroll") for (int n = 0; n < 2; ++n) _Pragma("unroll") for (int k = 0; k < 2; ++k) dst[n][k] = *(const PG8_LAS bf16x8*)(lds + PG8_SB(b, h) + boff + n * 2048 + k * 1024); } while (0)
; #define PG8_WAIT_V(n) asm volatile("s_waitcnt vmcnt(" #n ")" ::: "memory")
; #define PG8_WAIT_L(n) asm volatile("s_waitcnt lgkmcnt(" #n ")" ::: "memory")
; #define PG8_BAR __builtin_amdgcn_s_barrier()
; #define PG8_SCHED __builtin_amdgcn_sched_barrier(0)
; template <class Epi, class Sched, bool ALIGN_EPI = false, bool SP2 = false>
; __device__ __forceinline__ void gemm_phase(PG8_LAS unsigned char* lds, const Gemm g, const Sched& S, const Epi& E, int tid_in) {
;     ...
;             PG8_LDB(B0, 1, 0); PG8_LDB(B1, 1, 1); PG8_SCHED; PG8_LDA(At, 1, 0); PG8_STAGE(PG8_SA(0, 1), a2 + hstepA, voffA);
;             PG8_WAIT_V(8); PG8_WAIT_L(0); PG8_BAR; PG8_MMA(0, 0, At, B0); PG8_MMA(0, 1, At, B1); PG8_BAR; PG8_SCHED;
;             PG8_LDA(At, 1, 1); PG8_STAGE(PG8_SB(1, 0), b3, voffB); PG8_STAGE(PG8_SB(1, 1), b3 + hstep, voffB); PG8_STAGE(PG8_SA(1, 0), a3, voffA);
;             PG8_WAIT_V(8); PG8_WAIT_L(0); PG8_BAR; PG8_MMA(1, 0, At, B0); PG8_MMA(1, 1, At, B1); PG8_BAR; PG8_SCHED;
	s_add_i32 s51, 0, 0x18000
	s_add_i32 s52, 0, 0x1c000
	v_add_u32_e32 v162, s51, v149
	v_add_u32_e32 v178, s52, v149
	ds_read_b128 v[144:147], v162
	ds_read_b128 v[154:157], v162 offset:1024
	ds_read_b128 v[158:161], v162 offset:2048
	ds_read_b128 v[162:165], v162 offset:3072
	ds_read_b128 v[166:169], v178
	ds_read_b128 v[170:173], v178 offset:1024
	ds_read_b128 v[174:177], v178 offset:2048
	ds_read_b128 v[178:181], v178 offset:3072
	s_add_u32 s26, s26, 0x200000
	s_addc_u32 s27, s27, 0
	s_mov_b32 m0, s36
	ds_read_b128 v[182:185], v153 offset:32768
	ds_read_b128 v[186:189], v153 offset:33792
	ds_read_b128 v[190:193], v153 offset:34816
	ds_read_b128 v[194:197], v153 offset:35840
	ds_read_b128 v[198:201], v153 offset:36864
	ds_read_b128 v[202:205], v153 offset:37888
	ds_read_b128 v[206:209], v153 offset:38912
	ds_read_b128 v[210:213], v153 offset:39936
	global_load_lds_dwordx4 v128, s[26:27]
	s_mov_b32 m0, s37
	s_nop 0
	global_load_lds_dwordx4 v132, s[26:27]
	s_waitcnt vmcnt(8)
	s_waitcnt lgkmcnt(0)
	s_barrier
	s_setprio 1
	s_waitcnt lgkmcnt(0)
	v_mfma_f32_16x16x32_bf16 v[124:127], v[144:147], v[182:185], v[124:127]
	v_mfma_f32_16x16x32_bf16 v[124:127], v[154:157], v[186:189], v[124:127]
	v_mfma_f32_16x16x32_bf16 v[120:123], v[162:165], v[186:189], v[120:123]
	v_mfma_f32_16x16x32_bf16 v[120:123], v[158:161], v[182:185], v[120:123]
	v_mfma_f32_16x16x32_bf16 v[104:107], v[158:161], v[190:193], v[104:107]
	v_mfma_f32_16x16x32_bf16 v[104:107], v[162:165], v[194:197], v[104:107]
	v_mfma_f32_16x16x32_bf16 v[108:111], v[154:157], v[194:197], v[108:111]
	v_mfma_f32_16x16x32_bf16 v[108:111], v[144:147], v[190:193], v[108:111]
	v_mfma_f32_16x16x32_bf16 v[92:95], v[144:147], v[198:201], v[92:95]
	v_mfma_f32_16x16x32_bf16 v[92:95], v[154:157], v[202:205], v[92:95]
	v_mfma_f32_16x16x32_bf16 v[88:91], v[162:165], v[202:205], v[88:91]
	v_mfma_f32_16x16x32_bf16 v[88:91], v[158:161], v[198:201], v[88:91]
	v_mfma_f32_16x16x32_bf16 v[72:75], v[158:161], v[206:209], v[72:75]
	v_mfma_f32_16x16x32_bf16 v[72:75], v[162:165], v[210:213], v[72:75]
	v_mfma_f32_16x16x32_bf16 v[76:79], v[154:157], v[210:213], v[76:79]
	v_mfma_f32_16x16x32_bf16 v[76:79], v[144:147], v[206:209], v[76:79]
	s_setprio 0
	s_setprio 1
	v_mfma_f32_16x16x32_bf16 v[116:119], v[166:169], v[182:185], v[116:119]
	v_mfma_f32_16x16x32_bf16 v[116:119], v[170:173], v[186:189], v[116:119]
	v_mfma_f32_16x16x32_bf16 v[112:115], v[178:181], v[186:189], v[112:115]
	v_mfma_f32_16x16x32_bf16 v[112:115], v[174:177], v[182:185], v[112:115]
	v_mfma_f32_16x16x32_bf16 v[96:99], v[174:177], v[190:193], v[96:99]
	v_mfma_f32_16x16x32_bf16 v[96:99], v[178:181], v[194:197], v[96:99]
	v_mfma_f32_16x16x32_bf16 v[100:103], v[170:173], v[194:197], v[100:103]
	v_mfma_f32_16x16x32_bf16 v[100:103], v[166:169], v[190:193], v[100:103]
	v_mfma_f32_16x16x32_bf16 v[84:87], v[166:169], v[198:201], v[84:87]
	v_mfma_f32_16x16x32_bf16 v[84:87], v[170:173], v[202:205], v[84:87]
	v_mfma_f32_16x16x32_bf16 v[80:83], v[178:181], v[202:205], v[80:83]
	v_mfma_f32_16x16x32_bf16 v[80:83], v[174:177], v[198:201], v[80:83]
	v_mfma_f32_16x16x32_bf16 v[64:67], v[174:177], v[206:209], v[64:67]
	v_mfma_f32_16x16x32_bf16 v[64:67], v[178:181], v[210:213], v[64:67]
	v_mfma_f32_16x16x32_bf16 v[68:71], v[170:173], v[210:213], v[68:71]
	v_mfma_f32_16x16x32_bf16 v[68:71], v[166:169], v[206:209], v[68:71]
	s_setprio 0
	s_barrier
	s_add_i32 s26, s51, s34
	s_mov_b32 m0, s26
	ds_read_b128 v[182:185], v153 offset:49152
	ds_read_b128 v[186:189], v153 offset:50176
	ds_read_b128 v[190:193], v153 offset:51200
	ds_read_b128 v[194:197], v153 offset:52224
	ds_read_b128 v[198:201], v153 offset:53248
	ds_read_b128 v[202:205], v153 offset:54272
	ds_read_b128 v[206:209], v153 offset:55296
	ds_read_b128 v[210:213], v153 offset:56320
	global_load_lds_dwordx4 v130, s[98:99]
	s_add_i32 m0, s26, 0x2000
	s_add_u32 s24, s24, 0x200080
	s_addc_u32 s25, s25, 0
	s_add_i32 s26, s52, s34
	global_load_lds_dwordx4 v134, s[98:99]
	s_mov_b32 m0, s26
	s_nop 0
	global_load_lds_dwordx4 v130, s[24:25]
	s_add_i32 m0, s26, 0x2000
	s_nop 0
	global_load_lds_dwordx4 v134, s[24:25]
	s_mov_b32 m0, s40
	s_nop 0
	global_load_lds_dwordx4 v128, s[100:101]
	s_mov_b32 m0, s41
	s_nop 0
	global_load_lds_dwordx4 v132, s[100:101]
	s_waitcnt vmcnt(8)
	s_waitcnt lgkmcnt(0)
	s_barrier
	s_setprio 1
	s_waitcnt lgkmcnt(0)
	v_mfma_f32_16x16x32_bf16 v[60:63], v[144:147], v[182:185], v[60:63]
	v_mfma_f32_16x16x32_bf16 v[60:63], v[154:157], v[186:189], v[60:63]
	v_mfma_f32_16x16x32_bf16 v[56:59], v[162:165], v[186:189], v[56:59]
	v_mfma_f32_16x16x32_bf16 v[56:59], v[158:161], v[182:185], v[56:59]
	v_mfma_f32_16x16x32_bf16 v[40:43], v[158:161], v[190:193], v[40:43]
	v_mfma_f32_16x16x32_bf16 v[40:43], v[162:165], v[194:197], v[40:43]
	v_mfma_f32_16x16x32_bf16 v[44:47], v[154:157], v[194:197], v[44:47]
	v_mfma_f32_16x16x32_bf16 v[44:47], v[144:147], v[190:193], v[44:47]
	v_mfma_f32_16x16x32_bf16 v[28:31], v[144:147], v[198:201], v[28:31]
	v_mfma_f32_16x16x32_bf16 v[28:31], v[154:157], v[202:205], v[28:31]
	v_mfma_f32_16x16x32_bf16 v[24:27], v[162:165], v[202:205], v[24:27]
	v_mfma_f32_16x16x32_bf16 v[24:27], v[158:161], v[198:201], v[24:27]
	v_mfma_f32_16x16x32_bf16 v[8:11], v[158:161], v[206:209], v[8:11]
	v_mfma_f32_16x16x32_bf16 v[8:11], v[162:165], v[210:213], v[8:11]
	v_mfma_f32_16x16x32_bf16 v[12:15], v[154:157], v[210:213], v[12:15]
	v_mfma_f32_16x16x32_bf16 v[12:15], v[144:147], v[206:209], v[12:15]
	s_setprio 0
	s_setprio 1
	v_mfma_f32_16x16x32_bf16 v[52:55], v[166:169], v[182:185], v[52:55]
	v_mfma_f32_16x16x32_bf16 v[52:55], v[170:173], v[186:189], v[52:55]
	v_mfma_f32_16x16x32_bf16 v[48:51], v[178:181], v[186:189], v[48:51]
	v_mfma_f32_16x16x32_bf16 v[48:51], v[174:177], v[182:185], v[48:51]
	v_mfma_f32_16x16x32_bf16 v[32:35], v[174:177], v[190:193], v[32:35]
	v_mfma_f32_16x16x32_bf16 v[32:35], v[178:181], v[194:197], v[32:35]
	v_mfma_f32_16x16x32_bf16 v[36:39], v[170:173], v[194:197], v[36:39]
	v_mfma_f32_16x16x32_bf16 v[36:39], v[166:169], v[190:193], v[36:39]
	v_mfma_f32_16x16x32_bf16 v[20:23], v[166:169], v[198:201], v[20:23]
	v_mfma_f32_16x16x32_bf16 v[20:23], v[170:173], v[202:205], v[20:23]
	v_mfma_f32_16x16x32_bf16 v[16:19], v[178:181], v[202:205], v[16:19]
	v_mfma_f32_16x16x32_bf16 v[16:19], v[174:177], v[198:201], v[16:19]
	v_mfma_f32_16x16x32_bf16 v[0:3], v[174:177], v[206:209], v[0:3]
	v_mfma_f32_16x16x32_bf16 v[0:3], v[178:181], v[210:213], v[0:3]
	v_mfma_f32_16x16x32_bf16 v[4:7], v[170:173], v[210:213], v[4:7]
	v_mfma_f32_16x16x32_bf16 v[4:7], v[166:169], v[206:209], v[4:7]
	s_setprio 0
	s_barrier
	s_add_i32 s50, s50, 2
	s_add_u32 s22, s22, 0x100
	s_addc_u32 s23, s23, 0
	s_add_u32 s48, s48, 0x100
	s_addc_u32 s49, s49, 0
	s_cmpk_gt_u32 s50, 0x7d
	s_cbranch_scc0 .LBB0_927
	s_and_b64 vcc, exec, s[10:11]
	s_cbranch_vccz .LBB0_930
	s_barrier

; #define PG8_STAGE(bufoff, gbase, voff) do { _Pragma("unroll") for (int _i = 0; _i < 2; ++_i) \
;         __builtin_amdgcn_global_load_lds((const unsigned*)((const char*)(gbase) + (voff)[_i]), (PG8_LAS unsigned*)(lds + (bufoff) + ldsw + _i * 8192), 16, 0, 0); } while (0)
; #define PG8_LDA(dst, b, h) do { _Pragma("unroll") for (int m = 0; m < 4; ++m) _Pragma("unroll") for (int k = 0; k < 2; ++k) dst[m][k] = *(const PG8_LAS bf16x8*)(lds + PG8_SA(b, h) + aoff + m * 2048 + k * 1024); } while (0)
; #define PG8_LDB(dst, b, h) do { _Pragma("unroll") for (int n = 0; n < 2; ++n) _Pragma("unroll") for (int k = 0; k < 2; ++k) dst[n][k] = *(const PG8_LAS bf16x8*)(lds + PG8_SB(b, h) + boff + n * 2048 + k * 1024); } while (0)
; #define PG8_WAIT_V(n) asm volatile("s_waitcnt vmcnt(" #n ")" ::: "memory")
; #define PG8_WAIT_L(n) asm volatile("s_waitcnt lgkmcnt(" #n ")" ::: "memory")
; #define PG8_BAR __builtin_amdgcn_s_barrier()
; #define PG8_SCHED __builtin_amdgcn_sched_barrier(0)
; template <class Epi, class Sched, bool ALIGN_EPI = false, bool SP2 = false>
; __device__ __forceinline__ void gemm_phase(PG8_LAS unsigned char* lds, const Gemm g, const Sched& S, const Epi& E, int tid_in) {
;     ...
;             PG8_LDB(B0, 0, 0); PG8_LDB(B1, 0, 1); PG8_SCHED; PG8_LDA(At, 0, 0); PG8_STAGE(PG8_SA(1, 1), a1 + hstepA, voffA);
;             PG8_WAIT_V(8); PG8_WAIT_L(0); PG8_BAR; PG8_MMA(0, 0, At, B0); PG8_MMA(0, 1, At, B1); PG8_BAR; PG8_SCHED;
;             PG8_LDA(At, 0, 1); PG8_STAGE(PG8_SB(0, 0), b2, voffB); PG8_STAGE(PG8_SB(0, 1), b2 + hstep, voffB); PG8_STAGE(PG8_SA(0, 0), a2, voffA);
;             PG8_WAIT_V(8); PG8_WAIT_L(0); PG8_BAR; PG8_MMA(1, 0, At, B0); PG8_MMA(1, 1, At, B1); PG8_BAR; PG8_SCHED;
.LBB0_952:
	ds_read_b128 v[144:147], v155
	ds_read_b128 v[148:151], v155 offset:1024
	ds_read_b128 v[158:161], v155 offset:2048
	ds_read_b128 v[162:165], v155 offset:3072
	ds_read_b128 v[166:169], v156
	ds_read_b128 v[170:173], v156 offset:1024
	ds_read_b128 v[174:177], v156 offset:2048
	ds_read_b128 v[178:181], v156 offset:3072
	s_add_u32 s28, s26, 0xfff00080
	s_addc_u32 s29, s27, -1
	s_cmp_eq_u32 s54, 60
	s_cselect_b32 s31, s19, s29
	s_cselect_b32 s30, s50, s28
	s_cselect_b32 s29, s17, s53
	s_cselect_b32 s28, s51, s52
	s_add_i32 m0, s25, 0xc000
	ds_read_b128 v[182:185], v157
	ds_read_b128 v[186:189], v157 offset:1024
	ds_read_b128 v[190:193], v157 offset:2048
	ds_read_b128 v[194:197], v157 offset:3072
	ds_read_b128 v[198:201], v157 offset:4096
	ds_read_b128 v[202:205], v157 offset:5120
	ds_read_b128 v[206:209], v157 offset:6144
	ds_read_b128 v[210:213], v157 offset:7168
	global_load_lds_dwordx4 v136, s[26:27]
	s_add_i32 m0, s25, 0xe000
	s_nop 0
	global_load_lds_dwordx4 v138, s[26:27]
	s_waitcnt vmcnt(8)
	s_waitcnt lgkmcnt(0)
	s_barrier
	s_setprio 1
	s_waitcnt lgkmcnt(0)
	v_mfma_f32_16x16x32_bf16 v[124:127], v[144:147], v[182:185], v[124:127]
	v_mfma_f32_16x16x32_bf16 v[124:127], v[148:151], v[186:189], v[124:127]
	v_mfma_f32_16x16x32_bf16 v[120:123], v[162:165], v[186:189], v[120:123]
	v_mfma_f32_16x16x32_bf16 v[120:123], v[158:161], v[182:185], v[120:123]
	v_mfma_f32_16x16x32_bf16 v[104:107], v[158:161], v[190:193], v[104:107]
	v_mfma_f32_16x16x32_bf16 v[104:107], v[162:165], v[194:197], v[104:107]
	v_mfma_f32_16x16x32_bf16 v[108:111], v[148:151], v[194:197], v[108:111]
	v_mfma_f32_16x16x32_bf16 v[108:111], v[144:147], v[190:193], v[108:111]
	v_mfma_f32_16x16x32_bf16 v[92:95], v[144:147], v[198:201], v[92:95]
	v_mfma_f32_16x16x32_bf16 v[92:95], v[148:151], v[202:205], v[92:95]
	v_mfma_f32_16x16x32_bf16 v[88:91], v[162:165], v[202:205], v[88:91]
	v_mfma_f32_16x16x32_bf16 v[88:91], v[158:161], v[198:201], v[88:91]
	v_mfma_f32_16x16x32_bf16 v[72:75], v[158:161], v[206:209], v[72:75]
	v_mfma_f32_16x16x32_bf16 v[72:75], v[162:165], v[210:213], v[72:75]
	v_mfma_f32_16x16x32_bf16 v[76:79], v[148:151], v[210:213], v[76:79]
	v_mfma_f32_16x16x32_bf16 v[76:79], v[144:147], v[206:209], v[76:79]
	s_setprio 0
	s_setprio 1
	v_mfma_f32_16x16x32_bf16 v[116:119], v[166:169], v[182:185], v[116:119]
	v_mfma_f32_16x16x32_bf16 v[116:119], v[170:173], v[186:189], v[116:119]
	v_mfma_f32_16x16x32_bf16 v[112:115], v[178:181], v[186:189], v[112:115]
	v_mfma_f32_16x16x32_bf16 v[112:115], v[174:177], v[182:185], v[112:115]
	v_mfma_f32_16x16x32_bf16 v[96:99], v[174:177], v[190:193], v[96:99]
	v_mfma_f32_16x16x32_bf16 v[96:99], v[178:181], v[194:197], v[96:99]
	v_mfma_f32_16x16x32_bf16 v[100:103], v[170:173], v[194:197], v[100:103]
	v_mfma_f32_16x16x32_bf16 v[100:103], v[166:169], v[190:193], v[100:103]
	v_mfma_f32_16x16x32_bf16 v[84:87], v[166:169], v[198:201], v[84:87]
	v_mfma_f32_16x16x32_bf16 v[84:87], v[170:173], v[202:205], v[84:87]
	v_mfma_f32_16x16x32_bf16 v[80:83], v[178:181], v[202:205], v[80:83]
	v_mfma_f32_16x16x32_bf16 v[80:83], v[174:177], v[198:201], v[80:83]
	v_mfma_f32_16x16x32_bf16 v[64:67], v[174:177], v[206:209], v[64:67]
	v_mfma_f32_16x16x32_bf16 v[64:67], v[178:181], v[210:213], v[64:67]
	v_mfma_f32_16x16x32_bf16 v[68:71], v[170:173], v[210:213], v[68:71]
	v_mfma_f32_16x16x32_bf16 v[68:71], v[166:169], v[206:209], v[68:71]
	s_setprio 0
	s_barrier
	s_add_u32 s98, s28, 0x80
	s_addc_u32 s99, s29, 0
	s_add_u32 s100, s30, 0x80
	s_addc_u32 s101, s31, 0
	s_add_i32 s55, s47, s38
	s_mov_b32 m0, s55
	ds_read_b128 v[182:185], v157 offset:16384
	ds_read_b128 v[186:189], v157 offset:17408
	ds_read_b128 v[190:193], v157 offset:18432
	ds_read_b128 v[194:197], v157 offset:19456
	ds_read_b128 v[198:201], v157 offset:20480
	ds_read_b128 v[202:205], v157 offset:21504
	ds_read_b128 v[206:209], v157 offset:22528
	ds_read_b128 v[210:213], v157 offset:23552
	global_load_lds_dwordx4 v130, s[28:29]
	s_add_i32 m0, s55, 0x2000
	s_add_u32 s56, s28, 0x100000
	s_addc_u32 s57, s29, 0
	s_add_i32 s55, s48, s38
	global_load_lds_dwordx4 v134, s[28:29]
	s_mov_b32 m0, s55
	s_nop 0
	global_load_lds_dwordx4 v130, s[56:57]
	s_add_i32 m0, s55, 0x2000
	s_nop 0
	global_load_lds_dwordx4 v134, s[56:57]
	s_mov_b32 m0, s25
	s_nop 0
	global_load_lds_dwordx4 v128, s[30:31]
	s_mov_b32 m0, s39
	s_nop 0
	global_load_lds_dwordx4 v132, s[30:31]
	s_waitcnt vmcnt(8)
	s_waitcnt lgkmcnt(0)
	s_barrier
	s_setprio 1
	s_waitcnt lgkmcnt(0)
	v_mfma_f32_16x16x32_bf16 v[60:63], v[144:147], v[182:185], v[60:63]
	v_mfma_f32_16x16x32_bf16 v[60:63], v[148:151], v[186:189], v[60:63]
	v_mfma_f32_16x16x32_bf16 v[56:59], v[162:165], v[186:189], v[56:59]
	v_mfma_f32_16x16x32_bf16 v[56:59], v[158:161], v[182:185], v[56:59]
	v_mfma_f32_16x16x32_bf16 v[40:43], v[158:161], v[190:193], v[40:43]
	v_mfma_f32_16x16x32_bf16 v[40:43], v[162:165], v[194:197], v[40:43]
	v_mfma_f32_16x16x32_bf16 v[44:47], v[148:151], v[194:197], v[44:47]
	v_mfma_f32_16x16x32_bf16 v[44:47], v[144:147], v[190:193], v[44:47]
	v_mfma_f32_16x16x32_bf16 v[28:31], v[144:147], v[198:201], v[28:31]
	v_mfma_f32_16x16x32_bf16 v[28:31], v[148:151], v[202:205], v[28:31]
	v_mfma_f32_16x16x32_bf16 v[24:27], v[162:165], v[202:205], v[24:27]
	v_mfma_f32_16x16x32_bf16 v[24:27], v[158:161], v[198:201], v[24:27]
	v_mfma_f32_16x16x32_bf16 v[8:11], v[158:161], v[206:209], v[8:11]
	v_mfma_f32_16x16x32_bf16 v[8:11], v[162:165], v[210:213], v[8:11]
	v_mfma_f32_16x16x32_bf16 v[12:15], v[148:151], v[210:213], v[12:15]
	v_mfma_f32_16x16x32_bf16 v[12:15], v[144:147], v[206:209], v[12:15]
	s_setprio 0
	s_setprio 1
	v_mfma_f32_16x16x32_bf16 v[52:55], v[166:169], v[182:185], v[52:55]
	v_mfma_f32_16x16x32_bf16 v[52:55], v[170:173], v[186:189], v[52:55]
	v_mfma_f32_16x16x32_bf16 v[48:51], v[178:181], v[186:189], v[48:51]
	v_mfma_f32_16x16x32_bf16 v[48:51], v[174:177], v[182:185], v[48:51]
	v_mfma_f32_16x16x32_bf16 v[32:35], v[174:177], v[190:193], v[32:35]
	v_mfma_f32_16x16x32_bf16 v[32:35], v[178:181], v[194:197], v[32:35]
	v_mfma_f32_16x16x32_bf16 v[36:39], v[170:173], v[194:197], v[36:39]
	v_mfma_f32_16x16x32_bf16 v[36:39], v[166:169], v[190:193], v[36:39]
	v_mfma_f32_16x16x32_bf16 v[20:23], v[166:169], v[198:201], v[20:23]
	v_mfma_f32_16x16x32_bf16 v[20:23], v[170:173], v[202:205], v[20:23]
	v_mfma_f32_16x16x32_bf16 v[16:19], v[178:181], v[202:205], v[16:19]
	v_mfma_f32_16x16x32_bf16 v[16:19], v[174:177], v[198:201], v[16:19]
	v_mfma_f32_16x16x32_bf16 v[0:3], v[174:177], v[206:209], v[0:3]
	v_mfma_f32_16x16x32_bf16 v[0:3], v[178:181], v[210:213], v[0:3]
	v_mfma_f32_16x16x32_bf16 v[4:7], v[170:173], v[210:213], v[4:7]
	v_mfma_f32_16x16x32_bf16 v[4:7], v[166:169], v[206:209], v[4:7]
	s_setprio 0
	s_barrier
; #define PG8_STAGE(bufoff, gbase, voff) do { _Pragma("unroll") for (int _i = 0; _i < 2; ++_i) \
;         __builtin_amdgcn_global_load_lds((const unsigned*)((const char*)(gbase) + (voff)[_i]), (PG8_LAS unsigned*)(lds + (bufoff) + ldsw + _i * 8192), 16, 0, 0); } while (0)
; #define PG8_LDA(dst, b, h) do { _Pragma("unroll") for (int m = 0; m < 4; ++m) _Pragma("unroll") for (int k = 0; k < 2; ++k) dst[m][k] = *(const PG8_LAS bf16x8*)(lds + PG8_SA(b, h) + aoff + m * 2048 + k * 1024); } while (0)
; #define PG8_LDB(dst, b, h) do { _Pragma("unroll") for (int n = 0; n < 2; ++n) _Pragma("unroll") for (int k = 0; k < 2; ++k) dst[n][k] = *(const PG8_LAS bf16x8*)(lds + PG8_SB(b, h) + boff + n * 2048 + k * 1024); } while (0)
; #define PG8_WAIT_V(n) asm volatile("s_waitcnt vmcnt(" #n ")" ::: "memory")
; #define PG8_WAIT_L(n) asm volatile("s_waitcnt lgkmcnt(" #n ")" ::: "memory")
; #define PG8_BAR __builtin_amdgcn_s_barrier()
; #define PG8_SCHED __builtin_amdgcn_sched_barrier(0)
; template <class Epi, class Sched, bool ALIGN_EPI = false, bool SP2 = false>
; __device__ __forceinline__ void gemm_phase(PG8_LAS unsigned char* lds, const Gemm g, const Sched& S, const Epi& E, int tid_in) {
;     ...
;             PG8_LDB(B0, 1, 0); PG8_LDB(B1, 1, 1); PG8_SCHED; PG8_LDA(At, 1, 0); PG8_STAGE(PG8_SA(0, 1), a2 + hstepA, voffA);
;             PG8_WAIT_V(8); PG8_WAIT_L(0); PG8_BAR; PG8_MMA(0, 0, At, B0); PG8_MMA(0, 1, At, B1); PG8_BAR; PG8_SCHED;
;             PG8_LDA(At, 1, 1); PG8_STAGE(PG8_SB(1, 0), b3, voffB); PG8_STAGE(PG8_SB(1, 1), b3 + hstep, voffB); PG8_STAGE(PG8_SA(1, 0), a3, voffA);
;             PG8_WAIT_V(8); PG8_WAIT_L(0); PG8_BAR; PG8_MMA(1, 0, At, B0); PG8_MMA(1, 1, At, B1); PG8_BAR; PG8_SCHED;
	s_add_i32 s55, 0, 0x18000
	s_add_i32 s56, 0, 0x1c000
	v_add_u32_e32 v162, s55, v153
	v_add_u32_e32 v178, s56, v153
	ds_read_b128 v[144:147], v162
	ds_read_b128 v[148:151], v162 offset:1024
	ds_read_b128 v[158:161], v162 offset:2048
	ds_read_b128 v[162:165], v162 offset:3072
	ds_read_b128 v[166:169], v178
	ds_read_b128 v[170:173], v178 offset:1024
	ds_read_b128 v[174:177], v178 offset:2048
	ds_read_b128 v[178:181], v178 offset:3072
	s_add_u32 s30, s30, 0x100000
	s_addc_u32 s31, s31, 0
	s_mov_b32 m0, s40
	ds_read_b128 v[182:185], v157 offset:32768
	ds_read_b128 v[186:189], v157 offset:33792
	ds_read_b128 v[190:193], v157 offset:34816
	ds_read_b128 v[194:197], v157 offset:35840
	ds_read_b128 v[198:201], v157 offset:36864
	ds_read_b128 v[202:205], v157 offset:37888
	ds_read_b128 v[206:209], v157 offset:38912
	ds_read_b128 v[210:213], v157 offset:39936
	global_load_lds_dwordx4 v128, s[30:31]
	s_mov_b32 m0, s41
	s_nop 0
	global_load_lds_dwordx4 v132, s[30:31]
	s_waitcnt vmcnt(8)
	s_waitcnt lgkmcnt(0)
	s_barrier
	s_setprio 1
	s_waitcnt lgkmcnt(0)
	v_mfma_f32_16x16x32_bf16 v[124:127], v[144:147], v[182:185], v[124:127]
	v_mfma_f32_16x16x32_bf16 v[124:127], v[148:151], v[186:189], v[124:127]
	v_mfma_f32_16x16x32_bf16 v[120:123], v[162:165], v[186:189], v[120:123]
	v_mfma_f32_16x16x32_bf16 v[120:123], v[158:161], v[182:185], v[120:123]
	v_mfma_f32_16x16x32_bf16 v[104:107], v[158:161], v[190:193], v[104:107]
	v_mfma_f32_16x16x32_bf16 v[104:107], v[162:165], v[194:197], v[104:107]
	v_mfma_f32_16x16x32_bf16 v[108:111], v[148:151], v[194:197], v[108:111]
	v_mfma_f32_16x16x32_bf16 v[108:111], v[144:147], v[190:193], v[108:111]
	v_mfma_f32_16x16x32_bf16 v[92:95], v[144:147], v[198:201], v[92:95]
	v_mfma_f32_16x16x32_bf16 v[92:95], v[148:151], v[202:205], v[92:95]
	v_mfma_f32_16x16x32_bf16 v[88:91], v[162:165], v[202:205], v[88:91]
	v_mfma_f32_16x16x32_bf16 v[88:91], v[158:161], v[198:201], v[88:91]
	v_mfma_f32_16x16x32_bf16 v[72:75], v[158:161], v[206:209], v[72:75]
	v_mfma_f32_16x16x32_bf16 v[72:75], v[162:165], v[210:213], v[72:75]
	v_mfma_f32_16x16x32_bf16 v[76:79], v[148:151], v[210:213], v[76:79]
	v_mfma_f32_16x16x32_bf16 v[76:79], v[144:147], v[206:209], v[76:79]
	s_setprio 0
	s_setprio 1
	v_mfma_f32_16x16x32_bf16 v[116:119], v[166:169], v[182:185], v[116:119]
	v_mfma_f32_16x16x32_bf16 v[116:119], v[170:173], v[186:189], v[116:119]
	v_mfma_f32_16x16x32_bf16 v[112:115], v[178:181], v[186:189], v[112:115]
	v_mfma_f32_16x16x32_bf16 v[112:115], v[174:177], v[182:185], v[112:115]
	v_mfma_f32_16x16x32_bf16 v[96:99], v[174:177], v[190:193], v[96:99]
	v_mfma_f32_16x16x32_bf16 v[96:99], v[178:181], v[194:197], v[96:99]
	v_mfma_f32_16x16x32_bf16 v[100:103], v[170:173], v[194:197], v[100:103]
	v_mfma_f32_16x16x32_bf16 v[100:103], v[166:169], v[190:193], v[100:103]
	v_mfma_f32_16x16x32_bf16 v[84:87], v[166:169], v[198:201], v[84:87]
	v_mfma_f32_16x16x32_bf16 v[84:87], v[170:173], v[202:205], v[84:87]
	v_mfma_f32_16x16x32_bf16 v[80:83], v[178:181], v[202:205], v[80:83]
	v_mfma_f32_16x16x32_bf16 v[80:83], v[174:177], v[198:201], v[80:83]
	v_mfma_f32_16x16x32_bf16 v[64:67], v[174:177], v[206:209], v[64:67]
	v_mfma_f32_16x16x32_bf16 v[64:67], v[178:181], v[210:213], v[64:67]
	v_mfma_f32_16x16x32_bf16 v[68:71], v[170:173], v[210:213], v[68:71]
	v_mfma_f32_16x16x32_bf16 v[68:71], v[166:169], v[206:209], v[68:71]
	s_setprio 0
	s_barrier
	s_add_i32 s30, s55, s38
	s_mov_b32 m0, s30
	ds_read_b128 v[182:185], v157 offset:49152
	ds_read_b128 v[186:189], v157 offset:50176
	ds_read_b128 v[190:193], v157 offset:51200
	ds_read_b128 v[194:197], v157 offset:52224
	ds_read_b128 v[198:201], v157 offset:53248
	ds_read_b128 v[202:205], v157 offset:54272
	ds_read_b128 v[206:209], v157 offset:55296
	ds_read_b128 v[210:213], v157 offset:56320
	global_load_lds_dwordx4 v130, s[98:99]
	s_add_i32 m0, s30, 0x2000
	s_add_u32 s28, s28, 0x100080
	s_addc_u32 s29, s29, 0
	s_add_i32 s30, s56, s38
	global_load_lds_dwordx4 v134, s[98:99]
	s_mov_b32 m0, s30
	s_nop 0
	global_load_lds_dwordx4 v130, s[28:29]
	s_add_i32 m0, s30, 0x2000
	s_nop 0
	global_load_lds_dwordx4 v134, s[28:29]
	s_mov_b32 m0, s44
	s_nop 0
	global_load_lds_dwordx4 v128, s[100:101]
	s_mov_b32 m0, s45
	s_nop 0
	global_load_lds_dwordx4 v132, s[100:101]
	s_waitcnt vmcnt(8)
	s_waitcnt lgkmcnt(0)
	s_barrier
	s_setprio 1
	s_waitcnt lgkmcnt(0)
	v_mfma_f32_16x16x32_bf16 v[60:63], v[144:147], v[182:185], v[60:63]
	v_mfma_f32_16x16x32_bf16 v[60:63], v[148:151], v[186:189], v[60:63]
	v_mfma_f32_16x16x32_bf16 v[56:59], v[162:165], v[186:189], v[56:59]
	v_mfma_f32_16x16x32_bf16 v[56:59], v[158:161], v[182:185], v[56:59]
	v_mfma_f32_16x16x32_bf16 v[40:43], v[158:161], v[190:193], v[40:43]
	v_mfma_f32_16x16x32_bf16 v[40:43], v[162:165], v[194:197], v[40:43]
	v_mfma_f32_16x16x32_bf16 v[44:47], v[148:151], v[194:197], v[44:47]
	v_mfma_f32_16x16x32_bf16 v[44:47], v[144:147], v[190:193], v[44:47]
	v_mfma_f32_16x16x32_bf16 v[28:31], v[144:147], v[198:201], v[28:31]
	v_mfma_f32_16x16x32_bf16 v[28:31], v[148:151], v[202:205], v[28:31]
	v_mfma_f32_16x16x32_bf16 v[24:27], v[162:165], v[202:205], v[24:27]
	v_mfma_f32_16x16x32_bf16 v[24:27], v[158:161], v[198:201], v[24:27]
	v_mfma_f32_16x16x32_bf16 v[8:11], v[158:161], v[206:209], v[8:11]
	v_mfma_f32_16x16x32_bf16 v[8:11], v[162:165], v[210:213], v[8:11]
	v_mfma_f32_16x16x32_bf16 v[12:15], v[148:151], v[210:213], v[12:15]
	v_mfma_f32_16x16x32_bf16 v[12:15], v[144:147], v[206:209], v[12:15]
	s_setprio 0
	s_setprio 1
	v_mfma_f32_16x16x32_bf16 v[52:55], v[166:169], v[182:185], v[52:55]
	v_mfma_f32_16x16x32_bf16 v[52:55], v[170:173], v[186:189], v[52:55]
	v_mfma_f32_16x16x32_bf16 v[48:51], v[178:181], v[186:189], v[48:51]
	v_mfma_f32_16x16x32_bf16 v[48:51], v[174:177], v[182:185], v[48:51]
	v_mfma_f32_16x16x32_bf16 v[32:35], v[174:177], v[190:193], v[32:35]
	v_mfma_f32_16x16x32_bf16 v[32:35], v[178:181], v[194:197], v[32:35]
	v_mfma_f32_16x16x32_bf16 v[36:39], v[170:173], v[194:197], v[36:39]
	v_mfma_f32_16x16x32_bf16 v[36:39], v[166:169], v[190:193], v[36:39]
	v_mfma_f32_16x16x32_bf16 v[20:23], v[166:169], v[198:201], v[20:23]
	v_mfma_f32_16x16x32_bf16 v[20:23], v[170:173], v[202:205], v[20:23]
	v_mfma_f32_16x16x32_bf16 v[16:19], v[178:181], v[202:205], v[16:19]
	v_mfma_f32_16x16x32_bf16 v[16:19], v[174:177], v[198:201], v[16:19]
	v_mfma_f32_16x16x32_bf16 v[0:3], v[174:177], v[206:209], v[0:3]
	v_mfma_f32_16x16x32_bf16 v[0:3], v[178:181], v[210:213], v[0:3]
	v_mfma_f32_16x16x32_bf16 v[4:7], v[170:173], v[210:213], v[4:7]
	v_mfma_f32_16x16x32_bf16 v[4:7], v[166:169], v[206:209], v[4:7]
	s_setprio 0
	s_barrier
	s_add_i32 s54, s54, 2
	s_add_u32 s26, s26, 0x100
	s_addc_u32 s27, s27, 0
	s_add_u32 s52, s52, 0x100
	s_addc_u32 s53, s53, 0
	s_cmp_gt_u32 s54, 61
	s_cbranch_scc0 .LBB0_952
	s_and_b64 vcc, exec, s[12:13]
	s_cbranch_vccz .LBB0_955
	s_barrier

; #define PG8_STAGE(bufoff, gbase, voff) do { _Pragma("unroll") for (int _i = 0; _i < 2; ++_i) \
;         __builtin_amdgcn_global_load_lds((const unsigned*)((const char*)(gbase) + (voff)[_i]), (PG8_LAS unsigned*)(lds + (bufoff) + ldsw + _i * 8192), 16, 0, 0); } while (0)
; #define PG8_LDA(dst, b, h) do { _Pragma("unroll") for (int m = 0; m < 4; ++m) _Pragma("unroll") for (int k = 0; k < 2; ++k) dst[m][k] = *(const PG8_LAS bf16x8*)(lds + PG8_SA(b, h) + aoff + m * 2048 + k * 1024); } while (0)
; #define PG8_LDB(dst, b, h) do { _Pragma("unroll") for (int n = 0; n < 2; ++n) _Pragma("unroll") for (int k = 0; k < 2; ++k) dst[n][k] = *(const PG8_LAS bf16x8*)(lds + PG8_SB(b, h) + boff + n * 2048 + k * 1024); } while (0)
; #define PG8_WAIT_V(n) asm volatile("s_waitcnt vmcnt(" #n ")" ::: "memory")
; #define PG8_WAIT_L(n) asm volatile("s_waitcnt lgkmcnt(" #n ")" ::: "memory")
; #define PG8_BAR __builtin_amdgcn_s_barrier()
; #define PG8_SCHED __builtin_amdgcn_sched_barrier(0)
; template <class Epi, class Sched, bool ALIGN_EPI = false, bool SP2 = false>
; __device__ __forceinline__ void gemm_phase(PG8_LAS unsigned char* lds, const Gemm g, const Sched& S, const Epi& E, int tid_in) {
;     ...
;             PG8_LDB(B0, 0, 0); PG8_LDB(B1, 0, 1); PG8_SCHED; PG8_LDA(At, 0, 0); PG8_STAGE(PG8_SA(1, 1), a1 + hstepA, voffA);
;             PG8_WAIT_V(8); PG8_WAIT_L(0); PG8_BAR; PG8_MMA(0, 0, At, B0); PG8_MMA(0, 1, At, B1); PG8_BAR; PG8_SCHED;
;             PG8_LDA(At, 0, 1); PG8_STAGE(PG8_SB(0, 0), b2, voffB); PG8_STAGE(PG8_SB(0, 1), b2 + hstep, voffB); PG8_STAGE(PG8_SA(0, 0), a2, voffA);
;             PG8_WAIT_V(8); PG8_WAIT_L(0); PG8_BAR; PG8_MMA(1, 0, At, B0); PG8_MMA(1, 1, At, B1); PG8_BAR; PG8_SCHED;
.LBB0_1031:
	ds_read_b128 v[128:131], v167
	ds_read_b128 v[132:135], v167 offset:1024
	ds_read_b128 v[152:155], v167 offset:2048
	ds_read_b128 v[156:159], v167 offset:3072
	ds_read_b128 v[160:163], v168
	ds_read_b128 v[170:173], v168 offset:1024
	ds_read_b128 v[174:177], v168 offset:2048
	ds_read_b128 v[178:181], v168 offset:3072
	s_add_u32 s36, s34, 0xfff00080
	s_addc_u32 s37, s35, -1
	s_cmp_eq_u32 s61, 60
	s_cselect_b32 s39, s25, s37
	s_cselect_b32 s38, s57, s36
	s_cselect_b32 s37, s23, s60
	s_cselect_b32 s36, s58, s59
	s_add_i32 m0, s31, 0xc000
	ds_read_b128 v[182:185], v169
	ds_read_b128 v[186:189], v169 offset:1024
	ds_read_b128 v[190:193], v169 offset:2048
	ds_read_b128 v[194:197], v169 offset:3072
	ds_read_b128 v[198:201], v169 offset:4096
	ds_read_b128 v[202:205], v169 offset:5120
	ds_read_b128 v[206:209], v169 offset:6144
	ds_read_b128 v[210:213], v169 offset:7168
	global_load_lds_dwordx4 v144, s[34:35]
	s_add_i32 m0, s31, 0xe000
	s_nop 0
	global_load_lds_dwordx4 v146, s[34:35]
	s_waitcnt vmcnt(8)
	s_waitcnt lgkmcnt(0)
	s_barrier
	s_setprio 1
	s_waitcnt lgkmcnt(0)
	v_mfma_f32_16x16x32_bf16 v[124:127], v[128:131], v[182:185], v[124:127]
	v_mfma_f32_16x16x32_bf16 v[124:127], v[132:135], v[186:189], v[124:127]
	v_mfma_f32_16x16x32_bf16 v[120:123], v[156:159], v[186:189], v[120:123]
	v_mfma_f32_16x16x32_bf16 v[120:123], v[152:155], v[182:185], v[120:123]
	v_mfma_f32_16x16x32_bf16 v[112:115], v[152:155], v[190:193], v[112:115]
	v_mfma_f32_16x16x32_bf16 v[112:115], v[156:159], v[194:197], v[112:115]
	v_mfma_f32_16x16x32_bf16 v[116:119], v[132:135], v[194:197], v[116:119]
	v_mfma_f32_16x16x32_bf16 v[116:119], v[128:131], v[190:193], v[116:119]
	v_mfma_f32_16x16x32_bf16 v[108:111], v[128:131], v[198:201], v[108:111]
	v_mfma_f32_16x16x32_bf16 v[108:111], v[132:135], v[202:205], v[108:111]
	v_mfma_f32_16x16x32_bf16 v[104:107], v[156:159], v[202:205], v[104:107]
	v_mfma_f32_16x16x32_bf16 v[104:107], v[152:155], v[198:201], v[104:107]
	v_mfma_f32_16x16x32_bf16 v[96:99], v[152:155], v[206:209], v[96:99]
	v_mfma_f32_16x16x32_bf16 v[96:99], v[156:159], v[210:213], v[96:99]
	v_mfma_f32_16x16x32_bf16 v[100:103], v[132:135], v[210:213], v[100:103]
	v_mfma_f32_16x16x32_bf16 v[100:103], v[128:131], v[206:209], v[100:103]
	s_setprio 0
	s_setprio 1
	v_mfma_f32_16x16x32_bf16 v[68:71], v[160:163], v[182:185], v[68:71]
	v_mfma_f32_16x16x32_bf16 v[68:71], v[170:173], v[186:189], v[68:71]
	v_mfma_f32_16x16x32_bf16 v[60:63], v[178:181], v[186:189], v[60:63]
	v_mfma_f32_16x16x32_bf16 v[60:63], v[174:177], v[182:185], v[60:63]
	v_mfma_f32_16x16x32_bf16 v[48:51], v[174:177], v[190:193], v[48:51]
	v_mfma_f32_16x16x32_bf16 v[48:51], v[178:181], v[194:197], v[48:51]
	v_mfma_f32_16x16x32_bf16 v[52:55], v[170:173], v[194:197], v[52:55]
	v_mfma_f32_16x16x32_bf16 v[52:55], v[160:163], v[190:193], v[52:55]
	v_mfma_f32_16x16x32_bf16 v[44:47], v[160:163], v[198:201], v[44:47]
	v_mfma_f32_16x16x32_bf16 v[44:47], v[170:173], v[202:205], v[44:47]
	v_mfma_f32_16x16x32_bf16 v[40:43], v[178:181], v[202:205], v[40:43]
	v_mfma_f32_16x16x32_bf16 v[40:43], v[174:177], v[198:201], v[40:43]
	v_mfma_f32_16x16x32_bf16 v[32:35], v[174:177], v[206:209], v[32:35]
	v_mfma_f32_16x16x32_bf16 v[32:35], v[178:181], v[210:213], v[32:35]
	v_mfma_f32_16x16x32_bf16 v[36:39], v[170:173], v[210:213], v[36:39]
	v_mfma_f32_16x16x32_bf16 v[36:39], v[160:163], v[206:209], v[36:39]
	s_setprio 0
	s_barrier
	s_add_u32 s98, s36, 0x80
	s_addc_u32 s99, s37, 0
	s_add_u32 s100, s38, 0x80
	s_addc_u32 s101, s39, 0
	s_add_i32 s62, s54, s43
	s_mov_b32 m0, s62
	ds_read_b128 v[182:185], v169 offset:16384
	ds_read_b128 v[186:189], v169 offset:17408
	ds_read_b128 v[190:193], v169 offset:18432
	ds_read_b128 v[194:197], v169 offset:19456
	ds_read_b128 v[198:201], v169 offset:20480
	ds_read_b128 v[202:205], v169 offset:21504
	ds_read_b128 v[206:209], v169 offset:22528
	ds_read_b128 v[210:213], v169 offset:23552
	global_load_lds_dwordx4 v138, s[36:37]
	s_add_i32 m0, s62, 0x2000
	s_add_u32 s62, s36, 0x100000
	s_addc_u32 s63, s37, 0
	s_add_i32 s64, s55, s43
	global_load_lds_dwordx4 v142, s[36:37]
	s_mov_b32 m0, s64
	s_nop 0
	global_load_lds_dwordx4 v138, s[62:63]
	s_add_i32 m0, s64, 0x2000
	s_nop 0
	global_load_lds_dwordx4 v142, s[62:63]
	s_mov_b32 m0, s31
	s_nop 0
	global_load_lds_dwordx4 v136, s[38:39]
	s_mov_b32 m0, s44
	s_nop 0
	global_load_lds_dwordx4 v140, s[38:39]
	s_waitcnt vmcnt(8)
	s_waitcnt lgkmcnt(0)
	s_barrier
	s_setprio 1
	s_waitcnt lgkmcnt(0)
	v_mfma_f32_16x16x32_bf16 v[92:95], v[128:131], v[182:185], v[92:95]
	v_mfma_f32_16x16x32_bf16 v[92:95], v[132:135], v[186:189], v[92:95]
	v_mfma_f32_16x16x32_bf16 v[88:91], v[156:159], v[186:189], v[88:91]
	v_mfma_f32_16x16x32_bf16 v[88:91], v[152:155], v[182:185], v[88:91]
	v_mfma_f32_16x16x32_bf16 v[80:83], v[152:155], v[190:193], v[80:83]
	v_mfma_f32_16x16x32_bf16 v[80:83], v[156:159], v[194:197], v[80:83]
	v_mfma_f32_16x16x32_bf16 v[84:87], v[132:135], v[194:197], v[84:87]
	v_mfma_f32_16x16x32_bf16 v[84:87], v[128:131], v[190:193], v[84:87]
	v_mfma_f32_16x16x32_bf16 v[76:79], v[128:131], v[198:201], v[76:79]
	v_mfma_f32_16x16x32_bf16 v[76:79], v[132:135], v[202:205], v[76:79]
	v_mfma_f32_16x16x32_bf16 v[72:75], v[156:159], v[202:205], v[72:75]
	v_mfma_f32_16x16x32_bf16 v[72:75], v[152:155], v[198:201], v[72:75]
	v_mfma_f32_16x16x32_bf16 v[56:59], v[152:155], v[206:209], v[56:59]
	v_mfma_f32_16x16x32_bf16 v[56:59], v[156:159], v[210:213], v[56:59]
	v_mfma_f32_16x16x32_bf16 v[64:67], v[132:135], v[210:213], v[64:67]
	v_mfma_f32_16x16x32_bf16 v[64:67], v[128:131], v[206:209], v[64:67]
	s_setprio 0
	s_setprio 1
	v_mfma_f32_16x16x32_bf16 v[28:31], v[160:163], v[182:185], v[28:31]
	v_mfma_f32_16x16x32_bf16 v[28:31], v[170:173], v[186:189], v[28:31]
	v_mfma_f32_16x16x32_bf16 v[24:27], v[178:181], v[186:189], v[24:27]
	v_mfma_f32_16x16x32_bf16 v[24:27], v[174:177], v[182:185], v[24:27]
	v_mfma_f32_16x16x32_bf16 v[16:19], v[174:177], v[190:193], v[16:19]
	v_mfma_f32_16x16x32_bf16 v[16:19], v[178:181], v[194:197], v[16:19]
	v_mfma_f32_16x16x32_bf16 v[20:23], v[170:173], v[194:197], v[20:23]
	v_mfma_f32_16x16x32_bf16 v[20:23], v[160:163], v[190:193], v[20:23]
	v_mfma_f32_16x16x32_bf16 v[12:15], v[160:163], v[198:201], v[12:15]
	v_mfma_f32_16x16x32_bf16 v[12:15], v[170:173], v[202:205], v[12:15]
	v_mfma_f32_16x16x32_bf16 v[8:11], v[178:181], v[202:205], v[8:11]
	v_mfma_f32_16x16x32_bf16 v[8:11], v[174:177], v[198:201], v[8:11]
	v_mfma_f32_16x16x32_bf16 v[0:3], v[174:177], v[206:209], v[0:3]
	v_mfma_f32_16x16x32_bf16 v[0:3], v[178:181], v[210:213], v[0:3]
	v_mfma_f32_16x16x32_bf16 v[4:7], v[170:173], v[210:213], v[4:7]
	v_mfma_f32_16x16x32_bf16 v[4:7], v[160:163], v[206:209], v[4:7]
	s_setprio 0
	s_barrier
; #define PG8_STAGE(bufoff, gbase, voff) do { _Pragma("unroll") for (int _i = 0; _i < 2; ++_i) \
;         __builtin_amdgcn_global_load_lds((const unsigned*)((const char*)(gbase) + (voff)[_i]), (PG8_LAS unsigned*)(lds + (bufoff) + ldsw + _i * 8192), 16, 0, 0); } while (0)
; #define PG8_LDA(dst, b, h) do { _Pragma("unroll") for (int m = 0; m < 4; ++m) _Pragma("unroll") for (int k = 0; k < 2; ++k) dst[m][k] = *(const PG8_LAS bf16x8*)(lds + PG8_SA(b, h) + aoff + m * 2048 + k * 1024); } while (0)
; #define PG8_LDB(dst, b, h) do { _Pragma("unroll") for (int n = 0; n < 2; ++n) _Pragma("unroll") for (int k = 0; k < 2; ++k) dst[n][k] = *(const PG8_LAS bf16x8*)(lds + PG8_SB(b, h) + boff + n * 2048 + k * 1024); } while (0)
; #define PG8_WAIT_V(n) asm volatile("s_waitcnt vmcnt(" #n ")" ::: "memory")
; #define PG8_WAIT_L(n) asm volatile("s_waitcnt lgkmcnt(" #n ")" ::: "memory")
; #define PG8_BAR __builtin_amdgcn_s_barrier()
; #define PG8_SCHED __builtin_amdgcn_sched_barrier(0)
; template <class Epi, class Sched, bool ALIGN_EPI = false, bool SP2 = false>
; __device__ __forceinline__ void gemm_phase(PG8_LAS unsigned char* lds, const Gemm g, const Sched& S, const Epi& E, int tid_in) {
;     ...
;             PG8_LDB(B0, 1, 0); PG8_LDB(B1, 1, 1); PG8_SCHED; PG8_LDA(At, 1, 0); PG8_STAGE(PG8_SA(0, 1), a2 + hstepA, voffA);
;             PG8_WAIT_V(8); PG8_WAIT_L(0); PG8_BAR; PG8_MMA(0, 0, At, B0); PG8_MMA(0, 1, At, B1); PG8_BAR; PG8_SCHED;
;             PG8_LDA(At, 1, 1); PG8_STAGE(PG8_SB(1, 0), b3, voffB); PG8_STAGE(PG8_SB(1, 1), b3 + hstep, voffB); PG8_STAGE(PG8_SA(1, 0), a3, voffA);
;             PG8_WAIT_V(8); PG8_WAIT_L(0); PG8_BAR; PG8_MMA(1, 0, At, B0); PG8_MMA(1, 1, At, B1); PG8_BAR; PG8_SCHED;
	s_add_i32 s62, 0, 0x18000
	s_add_i32 s63, 0, 0x1c000
	v_add_u32_e32 v156, s62, v165
	v_add_u32_e32 v178, s63, v165
	ds_read_b128 v[128:131], v156
	ds_read_b128 v[132:135], v156 offset:1024
	ds_read_b128 v[152:155], v156 offset:2048
	ds_read_b128 v[156:159], v156 offset:3072
	ds_read_b128 v[160:163], v178
	ds_read_b128 v[170:173], v178 offset:1024
	ds_read_b128 v[174:177], v178 offset:2048
	ds_read_b128 v[178:181], v178 offset:3072
	s_add_u32 s38, s38, 0x100000
	s_addc_u32 s39, s39, 0
	s_mov_b32 m0, s45
	ds_read_b128 v[182:185], v169 offset:32768
	ds_read_b128 v[186:189], v169 offset:33792
	ds_read_b128 v[190:193], v169 offset:34816
	ds_read_b128 v[194:197], v169 offset:35840
	ds_read_b128 v[198:201], v169 offset:36864
	ds_read_b128 v[202:205], v169 offset:37888
	ds_read_b128 v[206:209], v169 offset:38912
	ds_read_b128 v[210:213], v169 offset:39936
	global_load_lds_dwordx4 v136, s[38:39]
	s_mov_b32 m0, s46
	s_nop 0
	global_load_lds_dwordx4 v140, s[38:39]
	s_waitcnt vmcnt(8)
	s_waitcnt lgkmcnt(0)
	s_barrier
	s_setprio 1
	s_waitcnt lgkmcnt(0)
	v_mfma_f32_16x16x32_bf16 v[124:127], v[128:131], v[182:185], v[124:127]
	v_mfma_f32_16x16x32_bf16 v[124:127], v[132:135], v[186:189], v[124:127]
	v_mfma_f32_16x16x32_bf16 v[120:123], v[156:159], v[186:189], v[120:123]
	v_mfma_f32_16x16x32_bf16 v[120:123], v[152:155], v[182:185], v[120:123]
	v_mfma_f32_16x16x32_bf16 v[112:115], v[152:155], v[190:193], v[112:115]
	v_mfma_f32_16x16x32_bf16 v[112:115], v[156:159], v[194:197], v[112:115]
	v_mfma_f32_16x16x32_bf16 v[116:119], v[132:135], v[194:197], v[116:119]
	v_mfma_f32_16x16x32_bf16 v[116:119], v[128:131], v[190:193], v[116:119]
	v_mfma_f32_16x16x32_bf16 v[108:111], v[128:131], v[198:201], v[108:111]
	v_mfma_f32_16x16x32_bf16 v[108:111], v[132:135], v[202:205], v[108:111]
	v_mfma_f32_16x16x32_bf16 v[104:107], v[156:159], v[202:205], v[104:107]
	v_mfma_f32_16x16x32_bf16 v[104:107], v[152:155], v[198:201], v[104:107]
	v_mfma_f32_16x16x32_bf16 v[96:99], v[152:155], v[206:209], v[96:99]
	v_mfma_f32_16x16x32_bf16 v[96:99], v[156:159], v[210:213], v[96:99]
	v_mfma_f32_16x16x32_bf16 v[100:103], v[132:135], v[210:213], v[100:103]
	v_mfma_f32_16x16x32_bf16 v[100:103], v[128:131], v[206:209], v[100:103]
	s_setprio 0
	s_setprio 1
	v_mfma_f32_16x16x32_bf16 v[68:71], v[160:163], v[182:185], v[68:71]
	v_mfma_f32_16x16x32_bf16 v[68:71], v[170:173], v[186:189], v[68:71]
	v_mfma_f32_16x16x32_bf16 v[60:63], v[178:181], v[186:189], v[60:63]
	v_mfma_f32_16x16x32_bf16 v[60:63], v[174:177], v[182:185], v[60:63]
	v_mfma_f32_16x16x32_bf16 v[48:51], v[174:177], v[190:193], v[48:51]
	v_mfma_f32_16x16x32_bf16 v[48:51], v[178:181], v[194:197], v[48:51]
	v_mfma_f32_16x16x32_bf16 v[52:55], v[170:173], v[194:197], v[52:55]
	v_mfma_f32_16x16x32_bf16 v[52:55], v[160:163], v[190:193], v[52:55]
	v_mfma_f32_16x16x32_bf16 v[44:47], v[160:163], v[198:201], v[44:47]
	v_mfma_f32_16x16x32_bf16 v[44:47], v[170:173], v[202:205], v[44:47]
	v_mfma_f32_16x16x32_bf16 v[40:43], v[178:181], v[202:205], v[40:43]
	v_mfma_f32_16x16x32_bf16 v[40:43], v[174:177], v[198:201], v[40:43]
	v_mfma_f32_16x16x32_bf16 v[32:35], v[174:177], v[206:209], v[32:35]
	v_mfma_f32_16x16x32_bf16 v[32:35], v[178:181], v[210:213], v[32:35]
	v_mfma_f32_16x16x32_bf16 v[36:39], v[170:173], v[210:213], v[36:39]
	v_mfma_f32_16x16x32_bf16 v[36:39], v[160:163], v[206:209], v[36:39]
	s_setprio 0
	s_barrier
	s_add_i32 s38, s62, s43
	s_mov_b32 m0, s38
	ds_read_b128 v[182:185], v169 offset:49152
	ds_read_b128 v[186:189], v169 offset:50176
	ds_read_b128 v[190:193], v169 offset:51200
	ds_read_b128 v[194:197], v169 offset:52224
	ds_read_b128 v[198:201], v169 offset:53248
	ds_read_b128 v[202:205], v169 offset:54272
	ds_read_b128 v[206:209], v169 offset:55296
	ds_read_b128 v[210:213], v169 offset:56320
	global_load_lds_dwordx4 v138, s[98:99]
	s_add_i32 m0, s38, 0x2000
	s_add_u32 s36, s36, 0x100080
	s_addc_u32 s37, s37, 0
	s_add_i32 s38, s63, s43
	global_load_lds_dwordx4 v142, s[98:99]
	s_mov_b32 m0, s38
	s_nop 0
	global_load_lds_dwordx4 v138, s[36:37]
	s_add_i32 m0, s38, 0x2000
	s_nop 0
	global_load_lds_dwordx4 v142, s[36:37]
	s_mov_b32 m0, s51
	s_nop 0
	global_load_lds_dwordx4 v136, s[100:101]
	s_mov_b32 m0, s52
	s_nop 0
	global_load_lds_dwordx4 v140, s[100:101]
	s_waitcnt vmcnt(8)
	s_waitcnt lgkmcnt(0)
	s_barrier
	s_setprio 1
	s_waitcnt lgkmcnt(0)
	v_mfma_f32_16x16x32_bf16 v[92:95], v[128:131], v[182:185], v[92:95]
	v_mfma_f32_16x16x32_bf16 v[92:95], v[132:135], v[186:189], v[92:95]
	v_mfma_f32_16x16x32_bf16 v[88:91], v[156:159], v[186:189], v[88:91]
	v_mfma_f32_16x16x32_bf16 v[88:91], v[152:155], v[182:185], v[88:91]
	v_mfma_f32_16x16x32_bf16 v[80:83], v[152:155], v[190:193], v[80:83]
	v_mfma_f32_16x16x32_bf16 v[80:83], v[156:159], v[194:197], v[80:83]
	v_mfma_f32_16x16x32_bf16 v[84:87], v[132:135], v[194:197], v[84:87]
	v_mfma_f32_16x16x32_bf16 v[84:87], v[128:131], v[190:193], v[84:87]
	v_mfma_f32_16x16x32_bf16 v[76:79], v[128:131], v[198:201], v[76:79]
	v_mfma_f32_16x16x32_bf16 v[76:79], v[132:135], v[202:205], v[76:79]
	v_mfma_f32_16x16x32_bf16 v[72:75], v[156:159], v[202:205], v[72:75]
	v_mfma_f32_16x16x32_bf16 v[72:75], v[152:155], v[198:201], v[72:75]
	v_mfma_f32_16x16x32_bf16 v[56:59], v[152:155], v[206:209], v[56:59]
	v_mfma_f32_16x16x32_bf16 v[56:59], v[156:159], v[210:213], v[56:59]
	v_mfma_f32_16x16x32_bf16 v[64:67], v[132:135], v[210:213], v[64:67]
	v_mfma_f32_16x16x32_bf16 v[64:67], v[128:131], v[206:209], v[64:67]
	s_setprio 0
	s_setprio 1
	v_mfma_f32_16x16x32_bf16 v[28:31], v[160:163], v[182:185], v[28:31]
	v_mfma_f32_16x16x32_bf16 v[28:31], v[170:173], v[186:189], v[28:31]
	v_mfma_f32_16x16x32_bf16 v[24:27], v[178:181], v[186:189], v[24:27]
	v_mfma_f32_16x16x32_bf16 v[24:27], v[174:177], v[182:185], v[24:27]
	v_mfma_f32_16x16x32_bf16 v[16:19], v[174:177], v[190:193], v[16:19]
	v_mfma_f32_16x16x32_bf16 v[16:19], v[178:181], v[194:197], v[16:19]
	v_mfma_f32_16x16x32_bf16 v[20:23], v[170:173], v[194:197], v[20:23]
	v_mfma_f32_16x16x32_bf16 v[20:23], v[160:163], v[190:193], v[20:23]
	v_mfma_f32_16x16x32_bf16 v[12:15], v[160:163], v[198:201], v[12:15]
	v_mfma_f32_16x16x32_bf16 v[12:15], v[170:173], v[202:205], v[12:15]
	v_mfma_f32_16x16x32_bf16 v[8:11], v[178:181], v[202:205], v[8:11]
	v_mfma_f32_16x16x32_bf16 v[8:11], v[174:177], v[198:201], v[8:11]
	v_mfma_f32_16x16x32_bf16 v[0:3], v[174:177], v[206:209], v[0:3]
	v_mfma_f32_16x16x32_bf16 v[0:3], v[178:181], v[210:213], v[0:3]
	v_mfma_f32_16x16x32_bf16 v[4:7], v[170:173], v[210:213], v[4:7]
	v_mfma_f32_16x16x32_bf16 v[4:7], v[160:163], v[206:209], v[4:7]
	s_setprio 0
	s_barrier
	s_add_i32 s61, s61, 2
	s_add_u32 s34, s34, 0x100
	s_addc_u32 s35, s35, 0
	s_add_u32 s59, s59, 0x100
	s_addc_u32 s60, s60, 0
	s_cmp_gt_u32 s61, 61
	s_cbranch_scc0 .LBB0_1031
	s_and_b64 vcc, exec, s[10:11]
	s_cbranch_vccz .LBB0_1034
	s_barrier
;     __device__ __forceinline__ void operator()(const f32x4 (&acc)[2][2][4][2], const Unit& u, int wr, int wc, int fr, int fq) const {
;         const int row0 = u.pm * BM + wr * 64 + fr, col0 = u.pn * BM + wc * 32 + 8 * fq;
;         const float* g = gate + (size_t)(u.pm >> 4) * 24576;
; #pragma unroll
;         for (int bj = 0; bj < 2; ++bj) { const int col = col0 + bj * HALF; const f32x4 g0 = *(const f32x4*)(g + col), g1 = *(const f32x4*)(g + col + 4);
; #pragma unroll
;             for (int ai = 0; ai < 2; ++ai)
; #pragma unroll
;                 for (int m = 0; m < 4; ++m) { const size_t off = (size_t)(row0 + ai * HALF + m * 16) * 4096 + col;
;                     const f32x4 x0 = *(const f32x4*)(base + off), x1 = *(const f32x4*)(base + off + 4);
;                     *(f32x4*)(out + off) = x0 * alpha + g0 * acc[ai][bj][m][0]; *(f32x4*)(out + off + 4) = x1 * alpha + g1 * acc[ai][bj][m][1]; } }
.LBB0_1034:
	v_lshl_add_u32 v222, s30, 8, v164
	v_lshl_or_b32 v223, s56, 8, v166
	v_readlane_b32 s56, v254, 0
	s_ashr_i32 s23, s30, 4
	v_readlane_b32 s57, v254, 1
	s_mul_hi_i32 s25, s23, 0x18000
	s_mul_i32 s23, s23, 0x18000
	v_lshl_add_u32 v222, v222, 12, v223
	v_lshlrev_b32_e32 v223, 2, v223
	s_mov_b64 s[36:37], s[56:57]
	s_add_u32 s34, s49, s23
	s_addc_u32 s35, s50, s25
	v_lshlrev_b32_e32 v160, 2, v222
	global_load_dwordx4 v[128:131], v223, s[34:35]
	global_load_dwordx4 v[132:135], v223, s[34:35] offset:16
	global_load_dwordx4 v[152:155], v223, s[34:35] offset:512
	global_load_dwordx4 v[156:159], v223, s[34:35] offset:528
	v_add_u32_e32 v161, 0x40000, v160
	v_add_u32_e32 v162, 0x80000, v160
	v_add_u32_e32 v163, 0xc0000, v160
	v_add_u32_e32 v170, 0x200000, v160
	v_add_u32_e32 v171, 0x240000, v160
	v_add_u32_e32 v172, 0x280000, v160
	v_add_u32_e32 v173, 0x2c0000, v160
	global_load_dwordx4 v[174:177], v160, s[36:37]
	global_load_dwordx4 v[178:181], v160, s[36:37] offset:16
	global_load_dwordx4 v[182:185], v161, s[36:37]
	global_load_dwordx4 v[186:189], v161, s[36:37] offset:16
	global_load_dwordx4 v[190:193], v162, s[36:37]
	global_load_dwordx4 v[194:197], v162, s[36:37] offset:16
	global_load_dwordx4 v[198:201], v163, s[36:37]
	global_load_dwordx4 v[202:205], v163, s[36:37] offset:16
	global_load_dwordx4 v[206:209], v170, s[36:37]
	global_load_dwordx4 v[210:213], v170, s[36:37] offset:16
	global_load_dwordx4 v[214:217], v171, s[36:37]
	global_load_dwordx4 v[218:221], v171, s[36:37] offset:16
	s_andn2_b64 vcc, exec, s[2:3]
	s_mov_b64 s[2:3], -1
	v_readlane_b32 s58, v254, 2
	v_readlane_b32 s59, v254, 3
	v_readlane_b32 s60, v254, 4
	v_readlane_b32 s61, v254, 5
	v_readlane_b32 s62, v254, 6
	v_readlane_b32 s63, v254, 7
	v_readlane_b32 s64, v254, 8
	v_readlane_b32 s65, v254, 9
	v_readlane_b32 s66, v254, 10
	v_readlane_b32 s67, v254, 11
	v_readlane_b32 s68, v254, 12
	v_readlane_b32 s69, v254, 13
	v_readlane_b32 s70, v254, 14
	v_readlane_b32 s71, v254, 15
	s_waitcnt vmcnt(10)
	v_pk_mul_f32 v[176:177], v[176:177], s[14:15] op_sel_hi:[1,0]
	v_pk_mul_f32 v[174:175], v[174:175], s[14:15] op_sel_hi:[1,0]
	v_pk_mul_f32 v[180:181], v[180:181], s[14:15] op_sel_hi:[1,0]
	v_pk_mul_f32 v[178:179], v[178:179], s[14:15] op_sel_hi:[1,0]
	v_pk_fma_f32 v[126:127], v[126:127], v[130:131], v[176:177]
	v_pk_fma_f32 v[124:125], v[124:125], v[128:129], v[174:175]
	v_pk_fma_f32 v[122:123], v[122:123], v[134:135], v[180:181]
	v_pk_fma_f32 v[120:121], v[120:121], v[132:133], v[178:179]
	global_store_dwordx4 v160, v[124:127], s[6:7] nt
	global_store_dwordx4 v160, v[120:123], s[6:7] offset:16 nt
	global_load_dwordx4 v[174:177], v172, s[36:37]
	global_load_dwordx4 v[178:181], v172, s[36:37] offset:16
	s_waitcnt vmcnt(12)
	v_pk_mul_f32 v[184:185], v[184:185], s[14:15] op_sel_hi:[1,0]
	v_pk_mul_f32 v[182:183], v[182:183], s[14:15] op_sel_hi:[1,0]
	v_pk_mul_f32 v[188:189], v[188:189], s[14:15] op_sel_hi:[1,0]
	v_pk_mul_f32 v[186:187], v[186:187], s[14:15] op_sel_hi:[1,0]
	v_pk_fma_f32 v[118:119], v[118:119], v[130:131], v[184:185]
	v_pk_fma_f32 v[116:117], v[116:117], v[128:129], v[182:183]
	v_pk_fma_f32 v[114:115], v[114:115], v[134:135], v[188:189]
	v_pk_fma_f32 v[112:113], v[112:113], v[132:133], v[186:187]
	global_store_dwordx4 v161, v[116:119], s[6:7] nt
	global_store_dwordx4 v161, v[112:115], s[6:7] offset:16 nt
	global_load_dwordx4 v[182:185], v173, s[36:37]
	global_load_dwordx4 v[186:189], v173, s[36:37] offset:16
	s_waitcnt vmcnt(14)
	v_pk_mul_f32 v[192:193], v[192:193], s[14:15] op_sel_hi:[1,0]
	v_pk_mul_f32 v[190:191], v[190:191], s[14:15] op_sel_hi:[1,0]
	v_pk_mul_f32 v[196:197], v[196:197], s[14:15] op_sel_hi:[1,0]
	v_pk_mul_f32 v[194:195], v[194:195], s[14:15] op_sel_hi:[1,0]
	v_pk_fma_f32 v[110:111], v[110:111], v[130:131], v[192:193]
	v_pk_fma_f32 v[108:109], v[108:109], v[128:129], v[190:191]
	v_pk_fma_f32 v[106:107], v[106:107], v[134:135], v[196:197]
	v_pk_fma_f32 v[104:105], v[104:105], v[132:133], v[194:195]
	global_store_dwordx4 v162, v[108:111], s[6:7] nt
	global_store_dwordx4 v162, v[104:107], s[6:7] offset:16 nt
	global_load_dwordx4 v[190:193], v160, s[36:37] offset:512
	global_load_dwordx4 v[194:197], v160, s[36:37] offset:528
	s_waitcnt vmcnt(16)
	v_pk_mul_f32 v[200:201], v[200:201], s[14:15] op_sel_hi:[1,0]
	v_pk_mul_f32 v[198:199], v[198:199], s[14:15] op_sel_hi:[1,0]
	v_pk_mul_f32 v[204:205], v[204:205], s[14:15] op_sel_hi:[1,0]
	v_pk_mul_f32 v[202:203], v[202:203], s[14:15] op_sel_hi:[1,0]
	v_pk_fma_f32 v[102:103], v[102:103], v[130:131], v[200:201]
	v_pk_fma_f32 v[100:101], v[100:101], v[128:129], v[198:199]
	v_pk_fma_f32 v[98:99], v[98:99], v[134:135], v[204:205]
	v_pk_fma_f32 v[96:97], v[96:97], v[132:133], v[202:203]
	global_store_dwordx4 v163, v[100:103], s[6:7] nt
	global_store_dwordx4 v163, v[96:99], s[6:7] offset:16 nt
	global_load_dwordx4 v[198:201], v161, s[36:37] offset:512
	global_load_dwordx4 v[202:205], v161, s[36:37] offset:528
	s_waitcnt vmcnt(18)
	v_pk_mul_f32 v[208:209], v[208:209], s[14:15] op_sel_hi:[1,0]
	v_pk_mul_f32 v[206:207], v[206:207], s[14:15] op_sel_hi:[1,0]
	v_pk_mul_f32 v[212:213], v[212:213], s[14:15] op_sel_hi:[1,0]
	v_pk_mul_f32 v[210:211], v[210:211], s[14:15] op_sel_hi:[1,0]
	v_pk_fma_f32 v[94:95], v[94:95], v[130:131], v[208:209]
	v_pk_fma_f32 v[92:93], v[92:93], v[128:129], v[206:207]
	v_pk_fma_f32 v[90:91], v[90:91], v[134:135], v[212:213]
	v_pk_fma_f32 v[88:89], v[88:89], v[132:133], v[210:211]
	global_store_dwordx4 v170, v[92:95], s[6:7] nt
	global_store_dwordx4 v170, v[88:91], s[6:7] offset:16 nt
	global_load_dwordx4 v[206:209], v162, s[36:37] offset:512
	global_load_dwordx4 v[210:213], v162, s[36:37] offset:528
	s_waitcnt vmcnt(20)
;     __device__ __forceinline__ void operator()(const f32x4 (&acc)[2][2][4][2], const Unit& u, int wr, int wc, int fr, int fq) const {
;     ...
;         for (int bj = 0; bj < 2; ++bj) { const int col = col0 + bj * HALF; const f32x4 g0 = *(const f32x4*)(g + col), g1 = *(const f32x4*)(g + col + 4);
; #pragma unroll
;             for (int ai = 0; ai < 2; ++ai)
; #pragma unroll
;                 for (int m = 0; m < 4; ++m) { const size_t off = (size_t)(row0 + ai * HALF + m * 16) * 4096 + col;
;                     const f32x4 x0 = *(const f32x4*)(base + off), x1 = *(const f32x4*)(base + off + 4);
;                     *(f32x4*)(out + off) = x0 * alpha + g0 * acc[ai][bj][m][0]; *(f32x4*)(out + off + 4) = x1 * alpha + g1 * acc[ai][bj][m][1]; } }
	v_pk_mul_f32 v[216:217], v[216:217], s[14:15] op_sel_hi:[1,0]
	v_pk_mul_f32 v[214:215], v[214:215], s[14:15] op_sel_hi:[1,0]
	v_pk_mul_f32 v[220:221], v[220:221], s[14:15] op_sel_hi:[1,0]
	v_pk_mul_f32 v[218:219], v[218:219], s[14:15] op_sel_hi:[1,0]
	v_pk_fma_f32 v[86:87], v[86:87], v[130:131], v[216:217]
	v_pk_fma_f32 v[84:85], v[84:85], v[128:129], v[214:215]
	v_pk_fma_f32 v[82:83], v[82:83], v[134:135], v[220:221]
	v_pk_fma_f32 v[80:81], v[80:81], v[132:133], v[218:219]
	global_store_dwordx4 v171, v[84:87], s[6:7] nt
	global_store_dwordx4 v171, v[80:83], s[6:7] offset:16 nt
	global_load_dwordx4 v[214:217], v163, s[36:37] offset:512
	global_load_dwordx4 v[218:221], v163, s[36:37] offset:528
	s_waitcnt vmcnt(20)
	v_pk_mul_f32 v[176:177], v[176:177], s[14:15] op_sel_hi:[1,0]
	v_pk_mul_f32 v[174:175], v[174:175], s[14:15] op_sel_hi:[1,0]
	v_pk_mul_f32 v[180:181], v[180:181], s[14:15] op_sel_hi:[1,0]
	v_pk_mul_f32 v[178:179], v[178:179], s[14:15] op_sel_hi:[1,0]
	v_pk_fma_f32 v[78:79], v[78:79], v[130:131], v[176:177]
	v_pk_fma_f32 v[76:77], v[76:77], v[128:129], v[174:175]
	v_pk_fma_f32 v[74:75], v[74:75], v[134:135], v[180:181]
	v_pk_fma_f32 v[72:73], v[72:73], v[132:133], v[178:179]
	global_store_dwordx4 v172, v[76:79], s[6:7] nt
	global_store_dwordx4 v172, v[72:75], s[6:7] offset:16 nt
	global_load_dwordx4 v[174:177], v170, s[36:37] offset:512
	global_load_dwordx4 v[178:181], v170, s[36:37] offset:528
	s_waitcnt vmcnt(20)
	v_pk_mul_f32 v[184:185], v[184:185], s[14:15] op_sel_hi:[1,0]
	v_pk_mul_f32 v[182:183], v[182:183], s[14:15] op_sel_hi:[1,0]
	v_pk_mul_f32 v[188:189], v[188:189], s[14:15] op_sel_hi:[1,0]
	v_pk_mul_f32 v[186:187], v[186:187], s[14:15] op_sel_hi:[1,0]
	v_pk_fma_f32 v[66:67], v[66:67], v[130:131], v[184:185]
	v_pk_fma_f32 v[64:65], v[64:65], v[128:129], v[182:183]
	v_pk_fma_f32 v[58:59], v[58:59], v[134:135], v[188:189]
	v_pk_fma_f32 v[56:57], v[56:57], v[132:133], v[186:187]
	global_store_dwordx4 v173, v[64:67], s[6:7] nt
	global_store_dwordx4 v173, v[56:59], s[6:7] offset:16 nt
	global_load_dwordx4 v[182:185], v171, s[36:37] offset:512
	global_load_dwordx4 v[186:189], v171, s[36:37] offset:528
	s_waitcnt vmcnt(20)
	v_pk_mul_f32 v[192:193], v[192:193], s[14:15] op_sel_hi:[1,0]
	v_pk_mul_f32 v[190:191], v[190:191], s[14:15] op_sel_hi:[1,0]
	v_pk_mul_f32 v[196:197], v[196:197], s[14:15] op_sel_hi:[1,0]
	v_pk_mul_f32 v[194:195], v[194:195], s[14:15] op_sel_hi:[1,0]
	v_pk_fma_f32 v[70:71], v[70:71], v[154:155], v[192:193]
	v_pk_fma_f32 v[68:69], v[68:69], v[152:153], v[190:191]
	v_pk_fma_f32 v[62:63], v[62:63], v[158:159], v[196:197]
	v_pk_fma_f32 v[60:61], v[60:61], v[156:157], v[194:195]
	global_store_dwordx4 v160, v[68:71], s[6:7] offset:512 nt
	global_store_dwordx4 v160, v[60:63], s[6:7] offset:528 nt
	global_load_dwordx4 v[190:193], v172, s[36:37] offset:512
	global_load_dwordx4 v[194:197], v172, s[36:37] offset:528
	s_waitcnt vmcnt(20)
	v_pk_mul_f32 v[200:201], v[200:201], s[14:15] op_sel_hi:[1,0]
	v_pk_mul_f32 v[198:199], v[198:199], s[14:15] op_sel_hi:[1,0]
	v_pk_mul_f32 v[204:205], v[204:205], s[14:15] op_sel_hi:[1,0]
	v_pk_mul_f32 v[202:203], v[202:203], s[14:15] op_sel_hi:[1,0]
	v_pk_fma_f32 v[54:55], v[54:55], v[154:155], v[200:201]
	v_pk_fma_f32 v[52:53], v[52:53], v[152:153], v[198:199]
	v_pk_fma_f32 v[50:51], v[50:51], v[158:159], v[204:205]
	v_pk_fma_f32 v[48:49], v[48:49], v[156:157], v[202:203]
	global_store_dwordx4 v161, v[52:55], s[6:7] offset:512 nt
	global_store_dwordx4 v161, v[48:51], s[6:7] offset:528 nt
	global_load_dwordx4 v[198:201], v173, s[36:37] offset:512
	global_load_dwordx4 v[202:205], v173, s[36:37] offset:528
	s_waitcnt vmcnt(20)
;     __device__ __forceinline__ void operator()(const f32x4 (&acc)[2][2][4][2], const Unit& u, int wr, int wc, int fr, int fq) const {
;     ...
;         for (int bj = 0; bj < 2; ++bj) { const int col = col0 + bj * HALF; const f32x4 g0 = *(const f32x4*)(g + col), g1 = *(const f32x4*)(g + col + 4);
; #pragma unroll
;             for (int ai = 0; ai < 2; ++ai)
; #pragma unroll
;                 for (int m = 0; m < 4; ++m) { const size_t off = (size_t)(row0 + ai * HALF + m * 16) * 4096 + col;
;                     const f32x4 x0 = *(const f32x4*)(base + off), x1 = *(const f32x4*)(base + off + 4);
;                     *(f32x4*)(out + off) = x0 * alpha + g0 * acc[ai][bj][m][0]; *(f32x4*)(out + off + 4) = x1 * alpha + g1 * acc[ai][bj][m][1]; } }
; template <class Epi, class Sched, bool ALIGN_EPI = false, bool SP2 = false>
; __device__ __forceinline__ void gemm_phase(PG8_LAS unsigned char* lds, const Gemm g, const Sched& S, const Epi& E, int tid_in) {
;     ...
;         if constexpr (!Epi::AFTER_DRAIN) { E(acc, cur, wr, wc, fr, fq); S.done(cur); }
;         if (!has_next) break;
	v_pk_mul_f32 v[208:209], v[208:209], s[14:15] op_sel_hi:[1,0]
	v_pk_mul_f32 v[206:207], v[206:207], s[14:15] op_sel_hi:[1,0]
	v_pk_mul_f32 v[212:213], v[212:213], s[14:15] op_sel_hi:[1,0]
	v_pk_mul_f32 v[210:211], v[210:211], s[14:15] op_sel_hi:[1,0]
	v_pk_fma_f32 v[46:47], v[46:47], v[154:155], v[208:209]
	v_pk_fma_f32 v[44:45], v[44:45], v[152:153], v[206:207]
	v_pk_fma_f32 v[42:43], v[42:43], v[158:159], v[212:213]
	v_pk_fma_f32 v[40:41], v[40:41], v[156:157], v[210:211]
	global_store_dwordx4 v162, v[44:47], s[6:7] offset:512 nt
	global_store_dwordx4 v162, v[40:43], s[6:7] offset:528 nt
	s_waitcnt vmcnt(18)
	v_pk_mul_f32 v[216:217], v[216:217], s[14:15] op_sel_hi:[1,0]
	v_pk_mul_f32 v[214:215], v[214:215], s[14:15] op_sel_hi:[1,0]
	v_pk_mul_f32 v[220:221], v[220:221], s[14:15] op_sel_hi:[1,0]
	v_pk_mul_f32 v[218:219], v[218:219], s[14:15] op_sel_hi:[1,0]
	v_pk_fma_f32 v[38:39], v[38:39], v[154:155], v[216:217]
	v_pk_fma_f32 v[36:37], v[36:37], v[152:153], v[214:215]
	v_pk_fma_f32 v[34:35], v[34:35], v[158:159], v[220:221]
	v_pk_fma_f32 v[32:33], v[32:33], v[156:157], v[218:219]
	global_store_dwordx4 v163, v[36:39], s[6:7] offset:512 nt
	global_store_dwordx4 v163, v[32:35], s[6:7] offset:528 nt
	s_waitcnt vmcnt(16)
	v_pk_mul_f32 v[176:177], v[176:177], s[14:15] op_sel_hi:[1,0]
	v_pk_mul_f32 v[174:175], v[174:175], s[14:15] op_sel_hi:[1,0]
	v_pk_mul_f32 v[180:181], v[180:181], s[14:15] op_sel_hi:[1,0]
	v_pk_mul_f32 v[178:179], v[178:179], s[14:15] op_sel_hi:[1,0]
	v_pk_fma_f32 v[30:31], v[30:31], v[154:155], v[176:177]
	v_pk_fma_f32 v[28:29], v[28:29], v[152:153], v[174:175]
	v_pk_fma_f32 v[26:27], v[26:27], v[158:159], v[180:181]
	v_pk_fma_f32 v[24:25], v[24:25], v[156:157], v[178:179]
	global_store_dwordx4 v170, v[28:31], s[6:7] offset:512 nt
	global_store_dwordx4 v170, v[24:27], s[6:7] offset:528 nt
	s_waitcnt vmcnt(14)
	v_pk_mul_f32 v[184:185], v[184:185], s[14:15] op_sel_hi:[1,0]
	v_pk_mul_f32 v[182:183], v[182:183], s[14:15] op_sel_hi:[1,0]
	v_pk_mul_f32 v[188:189], v[188:189], s[14:15] op_sel_hi:[1,0]
	v_pk_mul_f32 v[186:187], v[186:187], s[14:15] op_sel_hi:[1,0]
	v_pk_fma_f32 v[22:23], v[22:23], v[154:155], v[184:185]
	v_pk_fma_f32 v[20:21], v[20:21], v[152:153], v[182:183]
	v_pk_fma_f32 v[18:19], v[18:19], v[158:159], v[188:189]
	v_pk_fma_f32 v[16:17], v[16:17], v[156:157], v[186:187]
	global_store_dwordx4 v171, v[20:23], s[6:7] offset:512 nt
	global_store_dwordx4 v171, v[16:19], s[6:7] offset:528 nt
	s_waitcnt vmcnt(12)
	v_pk_mul_f32 v[192:193], v[192:193], s[14:15] op_sel_hi:[1,0]
	v_pk_mul_f32 v[190:191], v[190:191], s[14:15] op_sel_hi:[1,0]
	v_pk_mul_f32 v[196:197], v[196:197], s[14:15] op_sel_hi:[1,0]
	v_pk_mul_f32 v[194:195], v[194:195], s[14:15] op_sel_hi:[1,0]
	v_pk_fma_f32 v[14:15], v[14:15], v[154:155], v[192:193]
	v_pk_fma_f32 v[12:13], v[12:13], v[152:153], v[190:191]
	v_pk_fma_f32 v[10:11], v[10:11], v[158:159], v[196:197]
	v_pk_fma_f32 v[8:9], v[8:9], v[156:157], v[194:195]
	global_store_dwordx4 v172, v[12:15], s[6:7] offset:512 nt
	global_store_dwordx4 v172, v[8:11], s[6:7] offset:528 nt
	s_waitcnt vmcnt(10)
	v_pk_mul_f32 v[200:201], v[200:201], s[14:15] op_sel_hi:[1,0]
	v_pk_mul_f32 v[198:199], v[198:199], s[14:15] op_sel_hi:[1,0]
	v_pk_mul_f32 v[204:205], v[204:205], s[14:15] op_sel_hi:[1,0]
	v_pk_mul_f32 v[202:203], v[202:203], s[14:15] op_sel_hi:[1,0]
	v_pk_fma_f32 v[6:7], v[6:7], v[154:155], v[200:201]
	v_pk_fma_f32 v[4:5], v[4:5], v[152:153], v[198:199]
	v_pk_fma_f32 v[2:3], v[2:3], v[158:159], v[204:205]
	v_pk_fma_f32 v[0:1], v[0:1], v[156:157], v[202:203]
	global_store_dwordx4 v173, v[4:7], s[6:7] offset:512 nt
	global_store_dwordx4 v173, v[0:3], s[6:7] offset:528 nt
	s_cbranch_vccnz .LBB0_1023
	s_andn2_b64 vcc, exec, s[4:5]
	s_cbranch_vccnz .LBB0_1022
	s_barrier
	s_branch .LBB0_1022

; #define PG8_STAGE(bufoff, gbase, voff) do { _Pragma("unroll") for (int _i = 0; _i < 2; ++_i) \
;         __builtin_amdgcn_global_load_lds((const unsigned*)((const char*)(gbase) + (voff)[_i]), (PG8_LAS unsigned*)(lds + (bufoff) + ldsw + _i * 8192), 16, 0, 0); } while (0)
; #define PG8_LDA(dst, b, h) do { _Pragma("unroll") for (int m = 0; m < 4; ++m) _Pragma("unroll") for (int k = 0; k < 2; ++k) dst[m][k] = *(const PG8_LAS bf16x8*)(lds + PG8_SA(b, h) + aoff + m * 2048 + k * 1024); } while (0)
; #define PG8_LDB(dst, b, h) do { _Pragma("unroll") for (int n = 0; n < 2; ++n) _Pragma("unroll") for (int k = 0; k < 2; ++k) dst[n][k] = *(const PG8_LAS bf16x8*)(lds + PG8_SB(b, h) + boff + n * 2048 + k * 1024); } while (0)
; #define PG8_WAIT_V(n) asm volatile("s_waitcnt vmcnt(" #n ")" ::: "memory")
; #define PG8_WAIT_L(n) asm volatile("s_waitcnt lgkmcnt(" #n ")" ::: "memory")
; #define PG8_BAR __builtin_amdgcn_s_barrier()
; #define PG8_SCHED __builtin_amdgcn_sched_barrier(0)
; template <class Epi, class Sched, bool ALIGN_EPI = false, bool SP2 = false>
; __device__ __forceinline__ void gemm_phase(PG8_LAS unsigned char* lds, const Gemm g, const Sched& S, const Epi& E, int tid_in) {
;     ...
;             PG8_LDB(B0, 0, 0); PG8_LDB(B1, 0, 1); PG8_SCHED; PG8_LDA(At, 0, 0); PG8_STAGE(PG8_SA(1, 1), a1 + hstepA, voffA);
;             PG8_WAIT_V(8); PG8_WAIT_L(0); PG8_BAR; PG8_MMA(0, 0, At, B0); PG8_MMA(0, 1, At, B1); PG8_BAR; PG8_SCHED;
;             PG8_LDA(At, 0, 1); PG8_STAGE(PG8_SB(0, 0), b2, voffB); PG8_STAGE(PG8_SB(0, 1), b2 + hstep, voffB); PG8_STAGE(PG8_SA(0, 0), a2, voffA);
;             PG8_WAIT_V(8); PG8_WAIT_L(0); PG8_BAR; PG8_MMA(1, 0, At, B0); PG8_MMA(1, 1, At, B1); PG8_BAR; PG8_SCHED;
.LBB0_1162:
	ds_read_b128 v[128:131], v192
	ds_read_b128 v[132:135], v192 offset:1024
	ds_read_b128 v[136:139], v192 offset:2048
	ds_read_b128 v[140:143], v192 offset:3072
	ds_read_b128 v[160:163], v193
	ds_read_b128 v[164:167], v193 offset:1024
	ds_read_b128 v[168:171], v193 offset:2048
	ds_read_b128 v[172:175], v193 offset:3072
	s_add_u32 s38, s36, 0x100
	s_addc_u32 s39, s37, 0
	s_cmp_eq_u32 s69, 60
	s_cselect_b32 s43, s27, s39
	s_cselect_b32 s42, s35, s38
	s_cselect_b32 s41, s25, s68
	s_cselect_b32 s40, s66, s67
	s_add_i32 m0, s52, 0xc000
	ds_read_b128 v[176:179], v194
	ds_read_b128 v[180:183], v194 offset:1024
	ds_read_b128 v[184:187], v194 offset:2048
	ds_read_b128 v[196:199], v194 offset:3072
	ds_read_b128 v[200:203], v194 offset:4096
	ds_read_b128 v[204:207], v194 offset:5120
	ds_read_b128 v[208:211], v194 offset:6144
	ds_read_b128 v[212:215], v194 offset:7168
	global_load_lds_dwordx4 v152, s[36:37]
	s_add_i32 m0, s52, 0xe000
	s_nop 0
	global_load_lds_dwordx4 v154, s[36:37]
	s_waitcnt vmcnt(8)
	s_waitcnt lgkmcnt(0)
	s_barrier
	s_setprio 1
	s_waitcnt lgkmcnt(0)
	v_mfma_f32_16x16x32_bf16 v[92:95], v[128:131], v[176:179], v[92:95]
	v_mfma_f32_16x16x32_bf16 v[92:95], v[132:135], v[180:183], v[92:95]
	v_mfma_f32_16x16x32_bf16 v[28:31], v[140:143], v[180:183], v[28:31]
	v_mfma_f32_16x16x32_bf16 v[28:31], v[136:139], v[176:179], v[28:31]
	v_mfma_f32_16x16x32_bf16 v[24:27], v[136:139], v[184:187], v[24:27]
	v_mfma_f32_16x16x32_bf16 v[24:27], v[140:143], v[196:199], v[24:27]
	v_mfma_f32_16x16x32_bf16 v[88:91], v[132:135], v[196:199], v[88:91]
	v_mfma_f32_16x16x32_bf16 v[88:91], v[128:131], v[184:187], v[88:91]
	v_mfma_f32_16x16x32_bf16 v[116:119], v[128:131], v[200:203], v[116:119]
	v_mfma_f32_16x16x32_bf16 v[116:119], v[132:135], v[204:207], v[116:119]
	v_mfma_f32_16x16x32_bf16 v[52:55], v[140:143], v[204:207], v[52:55]
	v_mfma_f32_16x16x32_bf16 v[52:55], v[136:139], v[200:203], v[52:55]
	v_mfma_f32_16x16x32_bf16 v[44:47], v[136:139], v[208:211], v[44:47]
	v_mfma_f32_16x16x32_bf16 v[44:47], v[140:143], v[212:215], v[44:47]
	v_mfma_f32_16x16x32_bf16 v[108:111], v[132:135], v[212:215], v[108:111]
	v_mfma_f32_16x16x32_bf16 v[108:111], v[128:131], v[208:211], v[108:111]
	s_setprio 0
	s_setprio 1
	v_mfma_f32_16x16x32_bf16 v[84:87], v[160:163], v[176:179], v[84:87]
	v_mfma_f32_16x16x32_bf16 v[84:87], v[164:167], v[180:183], v[84:87]
	v_mfma_f32_16x16x32_bf16 v[20:23], v[172:175], v[180:183], v[20:23]
	v_mfma_f32_16x16x32_bf16 v[20:23], v[168:171], v[176:179], v[20:23]
	v_mfma_f32_16x16x32_bf16 v[0:3], v[168:171], v[184:187], v[0:3]
	v_mfma_f32_16x16x32_bf16 v[0:3], v[172:175], v[196:199], v[0:3]
	v_mfma_f32_16x16x32_bf16 v[64:67], v[164:167], v[196:199], v[64:67]
	v_mfma_f32_16x16x32_bf16 v[64:67], v[160:163], v[184:187], v[64:67]
	v_mfma_f32_16x16x32_bf16 v[124:127], v[160:163], v[200:203], v[124:127]
	v_mfma_f32_16x16x32_bf16 v[124:127], v[164:167], v[204:207], v[124:127]
	v_mfma_f32_16x16x32_bf16 v[60:63], v[172:175], v[204:207], v[60:63]
	v_mfma_f32_16x16x32_bf16 v[60:63], v[168:171], v[200:203], v[60:63]
	v_mfma_f32_16x16x32_bf16 v[56:59], v[168:171], v[208:211], v[56:59]
	v_mfma_f32_16x16x32_bf16 v[56:59], v[172:175], v[212:215], v[56:59]
	v_mfma_f32_16x16x32_bf16 v[120:123], v[164:167], v[212:215], v[120:123]
	v_mfma_f32_16x16x32_bf16 v[120:123], v[160:163], v[208:211], v[120:123]
	s_setprio 0
	s_barrier
	s_add_u32 s98, s40, 0x80
	s_addc_u32 s99, s41, 0
	s_add_u32 s100, s42, 0x80
	s_addc_u32 s101, s43, 0
	s_add_i32 s36, s62, s49
	s_mov_b32 m0, s36
	ds_read_b128 v[176:179], v194 offset:16384
	ds_read_b128 v[180:183], v194 offset:17408
	ds_read_b128 v[184:187], v194 offset:18432
	ds_read_b128 v[196:199], v194 offset:19456
	ds_read_b128 v[200:203], v194 offset:20480
	ds_read_b128 v[204:207], v194 offset:21504
	ds_read_b128 v[208:211], v194 offset:22528
	ds_read_b128 v[212:215], v194 offset:23552
	global_load_lds_dwordx4 v148, s[40:41]
	s_add_i32 m0, s36, 0x2000
	s_add_u32 s36, s40, 0x100000
	s_addc_u32 s37, s41, 0
	s_add_i32 s70, s63, s49
	global_load_lds_dwordx4 v144, s[40:41]
	s_mov_b32 m0, s70
	s_nop 0
	global_load_lds_dwordx4 v148, s[36:37]
	s_add_i32 m0, s70, 0x2000
	s_nop 0
	global_load_lds_dwordx4 v144, s[36:37]
	s_mov_b32 m0, s52
	s_nop 0
	global_load_lds_dwordx4 v150, s[42:43]
	s_mov_b32 m0, s53
	s_nop 0
	global_load_lds_dwordx4 v146, s[42:43]
	s_waitcnt vmcnt(8)
	s_waitcnt lgkmcnt(0)
	s_barrier
	s_setprio 1
	s_waitcnt lgkmcnt(0)
	v_mfma_f32_16x16x32_bf16 v[100:103], v[128:131], v[176:179], v[100:103]
	v_mfma_f32_16x16x32_bf16 v[100:103], v[132:135], v[180:183], v[100:103]
	v_mfma_f32_16x16x32_bf16 v[36:39], v[140:143], v[180:183], v[36:39]
	v_mfma_f32_16x16x32_bf16 v[36:39], v[136:139], v[176:179], v[36:39]
	v_mfma_f32_16x16x32_bf16 v[32:35], v[136:139], v[184:187], v[32:35]
	v_mfma_f32_16x16x32_bf16 v[32:35], v[140:143], v[196:199], v[32:35]
	v_mfma_f32_16x16x32_bf16 v[96:99], v[132:135], v[196:199], v[96:99]
	v_mfma_f32_16x16x32_bf16 v[96:99], v[128:131], v[184:187], v[96:99]
	v_mfma_f32_16x16x32_bf16 v[80:83], v[128:131], v[200:203], v[80:83]
	v_mfma_f32_16x16x32_bf16 v[80:83], v[132:135], v[204:207], v[80:83]
	v_mfma_f32_16x16x32_bf16 v[16:19], v[140:143], v[204:207], v[16:19]
	v_mfma_f32_16x16x32_bf16 v[16:19], v[136:139], v[200:203], v[16:19]
	v_mfma_f32_16x16x32_bf16 v[12:15], v[136:139], v[208:211], v[12:15]
	v_mfma_f32_16x16x32_bf16 v[12:15], v[140:143], v[212:215], v[12:15]
	v_mfma_f32_16x16x32_bf16 v[76:79], v[132:135], v[212:215], v[76:79]
	v_mfma_f32_16x16x32_bf16 v[76:79], v[128:131], v[208:211], v[76:79]
	s_setprio 0
	s_setprio 1
	v_mfma_f32_16x16x32_bf16 v[112:115], v[160:163], v[176:179], v[112:115]
	v_mfma_f32_16x16x32_bf16 v[112:115], v[164:167], v[180:183], v[112:115]
	v_mfma_f32_16x16x32_bf16 v[48:51], v[172:175], v[180:183], v[48:51]
	v_mfma_f32_16x16x32_bf16 v[48:51], v[168:171], v[176:179], v[48:51]
	v_mfma_f32_16x16x32_bf16 v[40:43], v[168:171], v[184:187], v[40:43]
	v_mfma_f32_16x16x32_bf16 v[40:43], v[172:175], v[196:199], v[40:43]
	v_mfma_f32_16x16x32_bf16 v[104:107], v[164:167], v[196:199], v[104:107]
	v_mfma_f32_16x16x32_bf16 v[104:107], v[160:163], v[184:187], v[104:107]
	v_mfma_f32_16x16x32_bf16 v[72:75], v[160:163], v[200:203], v[72:75]
	v_mfma_f32_16x16x32_bf16 v[72:75], v[164:167], v[204:207], v[72:75]
	v_mfma_f32_16x16x32_bf16 v[8:11], v[172:175], v[204:207], v[8:11]
	v_mfma_f32_16x16x32_bf16 v[8:11], v[168:171], v[200:203], v[8:11]
	v_mfma_f32_16x16x32_bf16 v[4:7], v[168:171], v[208:211], v[4:7]
	v_mfma_f32_16x16x32_bf16 v[4:7], v[172:175], v[212:215], v[4:7]
	v_mfma_f32_16x16x32_bf16 v[68:71], v[164:167], v[212:215], v[68:71]
	v_mfma_f32_16x16x32_bf16 v[68:71], v[160:163], v[208:211], v[68:71]
	s_setprio 0
	s_barrier
; #define PG8_STAGE(bufoff, gbase, voff) do { _Pragma("unroll") for (int _i = 0; _i < 2; ++_i) \
;         __builtin_amdgcn_global_load_lds((const unsigned*)((const char*)(gbase) + (voff)[_i]), (PG8_LAS unsigned*)(lds + (bufoff) + ldsw + _i * 8192), 16, 0, 0); } while (0)
; #define PG8_LDA(dst, b, h) do { _Pragma("unroll") for (int m = 0; m < 4; ++m) _Pragma("unroll") for (int k = 0; k < 2; ++k) dst[m][k] = *(const PG8_LAS bf16x8*)(lds + PG8_SA(b, h) + aoff + m * 2048 + k * 1024); } while (0)
; #define PG8_LDB(dst, b, h) do { _Pragma("unroll") for (int n = 0; n < 2; ++n) _Pragma("unroll") for (int k = 0; k < 2; ++k) dst[n][k] = *(const PG8_LAS bf16x8*)(lds + PG8_SB(b, h) + boff + n * 2048 + k * 1024); } while (0)
; #define PG8_WAIT_V(n) asm volatile("s_waitcnt vmcnt(" #n ")" ::: "memory")
; #define PG8_WAIT_L(n) asm volatile("s_waitcnt lgkmcnt(" #n ")" ::: "memory")
; #define PG8_BAR __builtin_amdgcn_s_barrier()
; #define PG8_SCHED __builtin_amdgcn_sched_barrier(0)
; template <class Epi, class Sched, bool ALIGN_EPI = false, bool SP2 = false>
; __device__ __forceinline__ void gemm_phase(PG8_LAS unsigned char* lds, const Gemm g, const Sched& S, const Epi& E, int tid_in) {
;     ...
;             PG8_LDB(B0, 1, 0); PG8_LDB(B1, 1, 1); PG8_SCHED; PG8_LDA(At, 1, 0); PG8_STAGE(PG8_SA(0, 1), a2 + hstepA, voffA);
;             PG8_WAIT_V(8); PG8_WAIT_L(0); PG8_BAR; PG8_MMA(0, 0, At, B0); PG8_MMA(0, 1, At, B1); PG8_BAR; PG8_SCHED;
;             PG8_LDA(At, 1, 1); PG8_STAGE(PG8_SB(1, 0), b3, voffB); PG8_STAGE(PG8_SB(1, 1), b3 + hstep, voffB); PG8_STAGE(PG8_SA(1, 0), a3, voffA);
;             PG8_WAIT_V(8); PG8_WAIT_L(0); PG8_BAR; PG8_MMA(1, 0, At, B0); PG8_MMA(1, 1, At, B1); PG8_BAR; PG8_SCHED;
	s_add_i32 s70, 0, 0x18000
	s_add_i32 s71, 0, 0x1c000
	v_add_u32_e32 v140, s70, v189
	v_add_u32_e32 v172, s71, v189
	ds_read_b128 v[128:131], v140
	ds_read_b128 v[132:135], v140 offset:1024
	ds_read_b128 v[136:139], v140 offset:2048
	ds_read_b128 v[140:143], v140 offset:3072
	ds_read_b128 v[160:163], v172
	ds_read_b128 v[164:167], v172 offset:1024
	ds_read_b128 v[168:171], v172 offset:2048
	ds_read_b128 v[172:175], v172 offset:3072
	s_add_u32 s36, s42, 0x8000
	s_addc_u32 s37, s43, 0
	s_mov_b32 m0, s54
	ds_read_b128 v[176:179], v194 offset:32768
	ds_read_b128 v[180:183], v194 offset:33792
	ds_read_b128 v[184:187], v194 offset:34816
	ds_read_b128 v[196:199], v194 offset:35840
	ds_read_b128 v[200:203], v194 offset:36864
	ds_read_b128 v[204:207], v194 offset:37888
	ds_read_b128 v[208:211], v194 offset:38912
	ds_read_b128 v[212:215], v194 offset:39936
	global_load_lds_dwordx4 v150, s[36:37]
	s_mov_b32 m0, s55
	s_nop 0
	global_load_lds_dwordx4 v146, s[36:37]
	s_waitcnt vmcnt(8)
	s_waitcnt lgkmcnt(0)
	s_barrier
	s_setprio 1
	s_waitcnt lgkmcnt(0)
	v_mfma_f32_16x16x32_bf16 v[92:95], v[128:131], v[176:179], v[92:95]
	v_mfma_f32_16x16x32_bf16 v[92:95], v[132:135], v[180:183], v[92:95]
	v_mfma_f32_16x16x32_bf16 v[28:31], v[140:143], v[180:183], v[28:31]
	v_mfma_f32_16x16x32_bf16 v[28:31], v[136:139], v[176:179], v[28:31]
	v_mfma_f32_16x16x32_bf16 v[24:27], v[136:139], v[184:187], v[24:27]
	v_mfma_f32_16x16x32_bf16 v[24:27], v[140:143], v[196:199], v[24:27]
	v_mfma_f32_16x16x32_bf16 v[88:91], v[132:135], v[196:199], v[88:91]
	v_mfma_f32_16x16x32_bf16 v[88:91], v[128:131], v[184:187], v[88:91]
	v_mfma_f32_16x16x32_bf16 v[116:119], v[128:131], v[200:203], v[116:119]
	v_mfma_f32_16x16x32_bf16 v[116:119], v[132:135], v[204:207], v[116:119]
	v_mfma_f32_16x16x32_bf16 v[52:55], v[140:143], v[204:207], v[52:55]
	v_mfma_f32_16x16x32_bf16 v[52:55], v[136:139], v[200:203], v[52:55]
	v_mfma_f32_16x16x32_bf16 v[44:47], v[136:139], v[208:211], v[44:47]
	v_mfma_f32_16x16x32_bf16 v[44:47], v[140:143], v[212:215], v[44:47]
	v_mfma_f32_16x16x32_bf16 v[108:111], v[132:135], v[212:215], v[108:111]
	v_mfma_f32_16x16x32_bf16 v[108:111], v[128:131], v[208:211], v[108:111]
	s_setprio 0
	s_setprio 1
	v_mfma_f32_16x16x32_bf16 v[84:87], v[160:163], v[176:179], v[84:87]
	v_mfma_f32_16x16x32_bf16 v[84:87], v[164:167], v[180:183], v[84:87]
	v_mfma_f32_16x16x32_bf16 v[20:23], v[172:175], v[180:183], v[20:23]
	v_mfma_f32_16x16x32_bf16 v[20:23], v[168:171], v[176:179], v[20:23]
	v_mfma_f32_16x16x32_bf16 v[0:3], v[168:171], v[184:187], v[0:3]
	v_mfma_f32_16x16x32_bf16 v[0:3], v[172:175], v[196:199], v[0:3]
	v_mfma_f32_16x16x32_bf16 v[64:67], v[164:167], v[196:199], v[64:67]
	v_mfma_f32_16x16x32_bf16 v[64:67], v[160:163], v[184:187], v[64:67]
	v_mfma_f32_16x16x32_bf16 v[124:127], v[160:163], v[200:203], v[124:127]
	v_mfma_f32_16x16x32_bf16 v[124:127], v[164:167], v[204:207], v[124:127]
	v_mfma_f32_16x16x32_bf16 v[60:63], v[172:175], v[204:207], v[60:63]
	v_mfma_f32_16x16x32_bf16 v[60:63], v[168:171], v[200:203], v[60:63]
	v_mfma_f32_16x16x32_bf16 v[56:59], v[168:171], v[208:211], v[56:59]
	v_mfma_f32_16x16x32_bf16 v[56:59], v[172:175], v[212:215], v[56:59]
	v_mfma_f32_16x16x32_bf16 v[120:123], v[164:167], v[212:215], v[120:123]
	v_mfma_f32_16x16x32_bf16 v[120:123], v[160:163], v[208:211], v[120:123]
	s_setprio 0
	s_barrier
	s_add_i32 s36, s70, s49
	s_mov_b32 m0, s36
	ds_read_b128 v[176:179], v194 offset:49152
	ds_read_b128 v[180:183], v194 offset:50176
	ds_read_b128 v[184:187], v194 offset:51200
	ds_read_b128 v[196:199], v194 offset:52224
	ds_read_b128 v[200:203], v194 offset:53248
	ds_read_b128 v[204:207], v194 offset:54272
	ds_read_b128 v[208:211], v194 offset:55296
	ds_read_b128 v[212:215], v194 offset:56320
	global_load_lds_dwordx4 v148, s[98:99]
	s_add_i32 m0, s36, 0x2000
	s_add_u32 s36, s40, 0x100080
	s_addc_u32 s37, s41, 0
	s_add_i32 s40, s71, s49
	global_load_lds_dwordx4 v144, s[98:99]
	s_mov_b32 m0, s40
	s_nop 0
	global_load_lds_dwordx4 v148, s[36:37]
	s_add_i32 m0, s40, 0x2000
	s_nop 0
	global_load_lds_dwordx4 v144, s[36:37]
	s_mov_b32 m0, s59
	s_nop 0
	global_load_lds_dwordx4 v150, s[100:101]
	s_mov_b32 m0, s60
	s_nop 0
	global_load_lds_dwordx4 v146, s[100:101]
	s_waitcnt vmcnt(8)
	s_waitcnt lgkmcnt(0)
	s_barrier
	s_setprio 1
	s_waitcnt lgkmcnt(0)
	v_mfma_f32_16x16x32_bf16 v[100:103], v[128:131], v[176:179], v[100:103]
	v_mfma_f32_16x16x32_bf16 v[100:103], v[132:135], v[180:183], v[100:103]
	v_mfma_f32_16x16x32_bf16 v[36:39], v[140:143], v[180:183], v[36:39]
	v_mfma_f32_16x16x32_bf16 v[36:39], v[136:139], v[176:179], v[36:39]
	v_mfma_f32_16x16x32_bf16 v[32:35], v[136:139], v[184:187], v[32:35]
	v_mfma_f32_16x16x32_bf16 v[32:35], v[140:143], v[196:199], v[32:35]
	v_mfma_f32_16x16x32_bf16 v[96:99], v[132:135], v[196:199], v[96:99]
	v_mfma_f32_16x16x32_bf16 v[96:99], v[128:131], v[184:187], v[96:99]
	v_mfma_f32_16x16x32_bf16 v[80:83], v[128:131], v[200:203], v[80:83]
	v_mfma_f32_16x16x32_bf16 v[80:83], v[132:135], v[204:207], v[80:83]
	v_mfma_f32_16x16x32_bf16 v[16:19], v[140:143], v[204:207], v[16:19]
	v_mfma_f32_16x16x32_bf16 v[16:19], v[136:139], v[200:203], v[16:19]
	v_mfma_f32_16x16x32_bf16 v[12:15], v[136:139], v[208:211], v[12:15]
	v_mfma_f32_16x16x32_bf16 v[12:15], v[140:143], v[212:215], v[12:15]
	v_mfma_f32_16x16x32_bf16 v[76:79], v[132:135], v[212:215], v[76:79]
	v_mfma_f32_16x16x32_bf16 v[76:79], v[128:131], v[208:211], v[76:79]
	s_setprio 0
	s_setprio 1
	v_mfma_f32_16x16x32_bf16 v[112:115], v[160:163], v[176:179], v[112:115]
	v_mfma_f32_16x16x32_bf16 v[112:115], v[164:167], v[180:183], v[112:115]
	v_mfma_f32_16x16x32_bf16 v[48:51], v[172:175], v[180:183], v[48:51]
	v_mfma_f32_16x16x32_bf16 v[48:51], v[168:171], v[176:179], v[48:51]
	v_mfma_f32_16x16x32_bf16 v[40:43], v[168:171], v[184:187], v[40:43]
	v_mfma_f32_16x16x32_bf16 v[40:43], v[172:175], v[196:199], v[40:43]
	v_mfma_f32_16x16x32_bf16 v[104:107], v[164:167], v[196:199], v[104:107]
	v_mfma_f32_16x16x32_bf16 v[104:107], v[160:163], v[184:187], v[104:107]
	v_mfma_f32_16x16x32_bf16 v[72:75], v[160:163], v[200:203], v[72:75]
	v_mfma_f32_16x16x32_bf16 v[72:75], v[164:167], v[204:207], v[72:75]
	v_mfma_f32_16x16x32_bf16 v[8:11], v[172:175], v[204:207], v[8:11]
	v_mfma_f32_16x16x32_bf16 v[8:11], v[168:171], v[200:203], v[8:11]
	v_mfma_f32_16x16x32_bf16 v[4:7], v[168:171], v[208:211], v[4:7]
	v_mfma_f32_16x16x32_bf16 v[4:7], v[172:175], v[212:215], v[4:7]
	v_mfma_f32_16x16x32_bf16 v[68:71], v[164:167], v[212:215], v[68:71]
	v_mfma_f32_16x16x32_bf16 v[68:71], v[160:163], v[208:211], v[68:71]
	s_setprio 0
	s_barrier
	s_add_i32 s69, s69, 2
	s_add_u32 s67, s67, 0x100
	s_addc_u32 s68, s68, 0
	s_cmp_gt_u32 s69, 61
	s_mov_b64 s[36:37], s[38:39]
	s_cbranch_scc0 .LBB0_1162
	s_and_b64 vcc, exec, s[10:11]
	s_cbranch_vccz .LBB0_1165
	s_barrier

; #define PG8_STAGE(bufoff, gbase, voff) do { _Pragma("unroll") for (int _i = 0; _i < 2; ++_i) \
;         __builtin_amdgcn_global_load_lds((const unsigned*)((const char*)(gbase) + (voff)[_i]), (PG8_LAS unsigned*)(lds + (bufoff) + ldsw + _i * 8192), 16, 0, 0); } while (0)
; #define PG8_LDA(dst, b, h) do { _Pragma("unroll") for (int m = 0; m < 4; ++m) _Pragma("unroll") for (int k = 0; k < 2; ++k) dst[m][k] = *(const PG8_LAS bf16x8*)(lds + PG8_SA(b, h) + aoff + m * 2048 + k * 1024); } while (0)
; #define PG8_LDB(dst, b, h) do { _Pragma("unroll") for (int n = 0; n < 2; ++n) _Pragma("unroll") for (int k = 0; k < 2; ++k) dst[n][k] = *(const PG8_LAS bf16x8*)(lds + PG8_SB(b, h) + boff + n * 2048 + k * 1024); } while (0)
; #define PG8_WAIT_V(n) asm volatile("s_waitcnt vmcnt(" #n ")" ::: "memory")
; #define PG8_WAIT_L(n) asm volatile("s_waitcnt lgkmcnt(" #n ")" ::: "memory")
; #define PG8_BAR __builtin_amdgcn_s_barrier()
; #define PG8_SCHED __builtin_amdgcn_sched_barrier(0)
; template <class Epi, class Sched, bool ALIGN_EPI = false, bool SP2 = false>
; __device__ __forceinline__ void gemm_phase(PG8_LAS unsigned char* lds, const Gemm g, const Sched& S, const Epi& E, int tid_in) {
;     ...
;             const char* a1 = cA + (size_t)(t + 1) * kstep;
;             const char* a2 = last ? nA : cA + (size_t)(t + 2) * kstep; const char* b2 = last ? nB : cB + (size_t)(t + 2) * kstep;
;             const char* a3 = a2 + kstep; const char* b3 = b2 + kstep;
;             if (last && has_next) S.a_ready(nxt);
;             if constexpr (SP2) {
;             PG8_LDB(B0, 0, 0); PG8_LDB(B1, 0, 1); PG8_SCHED; PG8_LDA(At, 0, 0); PG8_STAGE(PG8_SA(1, 1), a1 + hstepA, voffA);
;             PG8_WAIT_V(8); PG8_WAIT_L(0); PG8_BAR; PG8_MMA(0, 0, At, B0); PG8_MMA(0, 1, At, B1); PG8_BAR; PG8_SCHED;
;             PG8_LDA(At, 0, 1); PG8_STAGE(PG8_SB(0, 0), b2, voffB); PG8_STAGE(PG8_SB(0, 1), b2 + hstep, voffB); PG8_STAGE(PG8_SA(0, 0), a2, voffA);
;             PG8_WAIT_V(8); PG8_WAIT_L(0); PG8_BAR; PG8_MMA(1, 0, At, B0); PG8_MMA(1, 1, At, B1); PG8_BAR; PG8_SCHED;
.LBB0_1328:
	ds_read_b128 v[128:131], v191
	ds_read_b128 v[132:135], v191 offset:1024
	ds_read_b128 v[152:155], v191 offset:2048
	ds_read_b128 v[156:159], v191 offset:3072
	ds_read_b128 v[160:163], v192
	ds_read_b128 v[164:167], v192 offset:1024
	ds_read_b128 v[168:171], v192 offset:2048
	ds_read_b128 v[172:175], v192 offset:3072
	s_add_u32 s22, s20, 0x100
	s_addc_u32 s23, s21, 0
	s_cmpk_eq_i32 s53, 0xa8
	s_cselect_b32 s27, s5, s23
	s_cselect_b32 s26, s4, s22
	s_cselect_b32 s25, s19, s52
	s_cselect_b32 s24, s18, s51
	s_add_i32 m0, s34, 0xc000
	ds_read_b128 v[176:179], v193
	ds_read_b128 v[180:183], v193 offset:1024
	ds_read_b128 v[184:187], v193 offset:2048
	ds_read_b128 v[194:197], v193 offset:3072
	ds_read_b128 v[198:201], v193 offset:4096
	ds_read_b128 v[202:205], v193 offset:5120
	ds_read_b128 v[206:209], v193 offset:6144
	ds_read_b128 v[210:213], v193 offset:7168
	global_load_lds_dwordx4 v144, s[20:21]
	s_add_i32 m0, s34, 0xe000
	s_nop 0
	global_load_lds_dwordx4 v146, s[20:21]
	s_waitcnt vmcnt(8)
	s_waitcnt lgkmcnt(0)
	s_barrier
	s_setprio 1
	s_waitcnt lgkmcnt(0)
	v_mfma_f32_16x16x32_bf16 v[124:127], v[128:131], v[176:179], v[124:127]
	v_mfma_f32_16x16x32_bf16 v[124:127], v[132:135], v[180:183], v[124:127]
	v_mfma_f32_16x16x32_bf16 v[120:123], v[156:159], v[180:183], v[120:123]
	v_mfma_f32_16x16x32_bf16 v[120:123], v[152:155], v[176:179], v[120:123]
	v_mfma_f32_16x16x32_bf16 v[112:115], v[152:155], v[184:187], v[112:115]
	v_mfma_f32_16x16x32_bf16 v[112:115], v[156:159], v[194:197], v[112:115]
	v_mfma_f32_16x16x32_bf16 v[116:119], v[132:135], v[194:197], v[116:119]
	v_mfma_f32_16x16x32_bf16 v[116:119], v[128:131], v[184:187], v[116:119]
	v_mfma_f32_16x16x32_bf16 v[108:111], v[128:131], v[198:201], v[108:111]
	v_mfma_f32_16x16x32_bf16 v[108:111], v[132:135], v[202:205], v[108:111]
	v_mfma_f32_16x16x32_bf16 v[104:107], v[156:159], v[202:205], v[104:107]
	v_mfma_f32_16x16x32_bf16 v[104:107], v[152:155], v[198:201], v[104:107]
	v_mfma_f32_16x16x32_bf16 v[96:99], v[152:155], v[206:209], v[96:99]
	v_mfma_f32_16x16x32_bf16 v[96:99], v[156:159], v[210:213], v[96:99]
	v_mfma_f32_16x16x32_bf16 v[100:103], v[132:135], v[210:213], v[100:103]
	v_mfma_f32_16x16x32_bf16 v[100:103], v[128:131], v[206:209], v[100:103]
	s_setprio 0
	s_setprio 1
	v_mfma_f32_16x16x32_bf16 v[60:63], v[160:163], v[176:179], v[60:63]
	v_mfma_f32_16x16x32_bf16 v[60:63], v[164:167], v[180:183], v[60:63]
	v_mfma_f32_16x16x32_bf16 v[56:59], v[172:175], v[180:183], v[56:59]
	v_mfma_f32_16x16x32_bf16 v[56:59], v[168:171], v[176:179], v[56:59]
	v_mfma_f32_16x16x32_bf16 v[48:51], v[168:171], v[184:187], v[48:51]
	v_mfma_f32_16x16x32_bf16 v[48:51], v[172:175], v[194:197], v[48:51]
	v_mfma_f32_16x16x32_bf16 v[52:55], v[164:167], v[194:197], v[52:55]
	v_mfma_f32_16x16x32_bf16 v[52:55], v[160:163], v[184:187], v[52:55]
	v_mfma_f32_16x16x32_bf16 v[44:47], v[160:163], v[198:201], v[44:47]
	v_mfma_f32_16x16x32_bf16 v[44:47], v[164:167], v[202:205], v[44:47]
	v_mfma_f32_16x16x32_bf16 v[40:43], v[172:175], v[202:205], v[40:43]
	v_mfma_f32_16x16x32_bf16 v[40:43], v[168:171], v[198:201], v[40:43]
	v_mfma_f32_16x16x32_bf16 v[32:35], v[168:171], v[206:209], v[32:35]
	v_mfma_f32_16x16x32_bf16 v[32:35], v[172:175], v[210:213], v[32:35]
	v_mfma_f32_16x16x32_bf16 v[36:39], v[164:167], v[210:213], v[36:39]
	v_mfma_f32_16x16x32_bf16 v[36:39], v[160:163], v[206:209], v[36:39]
	s_setprio 0
	s_barrier
	s_add_u32 s98, s24, 0x80
	s_addc_u32 s99, s25, 0
	s_add_u32 s100, s26, 0x80
	s_addc_u32 s101, s27, 0
	s_add_i32 s20, s45, s33
	s_mov_b32 m0, s20
	ds_read_b128 v[176:179], v193 offset:16384
	ds_read_b128 v[180:183], v193 offset:17408
	ds_read_b128 v[184:187], v193 offset:18432
	ds_read_b128 v[194:197], v193 offset:19456
	ds_read_b128 v[198:201], v193 offset:20480
	ds_read_b128 v[202:205], v193 offset:21504
	ds_read_b128 v[206:209], v193 offset:22528
	ds_read_b128 v[210:213], v193 offset:23552
	global_load_lds_dwordx4 v138, s[24:25]
	s_add_i32 m0, s20, 0x2000
	s_add_u32 s20, s24, 0x2b0000
	s_addc_u32 s21, s25, 0
	s_add_i32 s54, s46, s33
	global_load_lds_dwordx4 v142, s[24:25]
	s_mov_b32 m0, s54
	s_nop 0
	global_load_lds_dwordx4 v138, s[20:21]
	s_add_i32 m0, s54, 0x2000
	s_nop 0
	global_load_lds_dwordx4 v142, s[20:21]
	s_mov_b32 m0, s34
	s_nop 0
	global_load_lds_dwordx4 v136, s[26:27]
	s_mov_b32 m0, s35
	s_nop 0
	global_load_lds_dwordx4 v140, s[26:27]
	s_waitcnt vmcnt(8)
	s_waitcnt lgkmcnt(0)
	s_barrier
	s_setprio 1
	s_waitcnt lgkmcnt(0)
	v_mfma_f32_16x16x32_bf16 v[92:95], v[128:131], v[176:179], v[92:95]
	v_mfma_f32_16x16x32_bf16 v[92:95], v[132:135], v[180:183], v[92:95]
	v_mfma_f32_16x16x32_bf16 v[88:91], v[156:159], v[180:183], v[88:91]
	v_mfma_f32_16x16x32_bf16 v[88:91], v[152:155], v[176:179], v[88:91]
	v_mfma_f32_16x16x32_bf16 v[80:83], v[152:155], v[184:187], v[80:83]
	v_mfma_f32_16x16x32_bf16 v[80:83], v[156:159], v[194:197], v[80:83]
	v_mfma_f32_16x16x32_bf16 v[84:87], v[132:135], v[194:197], v[84:87]
	v_mfma_f32_16x16x32_bf16 v[84:87], v[128:131], v[184:187], v[84:87]
	v_mfma_f32_16x16x32_bf16 v[76:79], v[128:131], v[198:201], v[76:79]
	v_mfma_f32_16x16x32_bf16 v[76:79], v[132:135], v[202:205], v[76:79]
	v_mfma_f32_16x16x32_bf16 v[72:75], v[156:159], v[202:205], v[72:75]
	v_mfma_f32_16x16x32_bf16 v[72:75], v[152:155], v[198:201], v[72:75]
	v_mfma_f32_16x16x32_bf16 v[64:67], v[152:155], v[206:209], v[64:67]
	v_mfma_f32_16x16x32_bf16 v[64:67], v[156:159], v[210:213], v[64:67]
	v_mfma_f32_16x16x32_bf16 v[68:71], v[132:135], v[210:213], v[68:71]
	v_mfma_f32_16x16x32_bf16 v[68:71], v[128:131], v[206:209], v[68:71]
	s_setprio 0
	s_setprio 1
	v_mfma_f32_16x16x32_bf16 v[28:31], v[160:163], v[176:179], v[28:31]
	v_mfma_f32_16x16x32_bf16 v[28:31], v[164:167], v[180:183], v[28:31]
	v_mfma_f32_16x16x32_bf16 v[24:27], v[172:175], v[180:183], v[24:27]
	v_mfma_f32_16x16x32_bf16 v[24:27], v[168:171], v[176:179], v[24:27]
	v_mfma_f32_16x16x32_bf16 v[16:19], v[168:171], v[184:187], v[16:19]
	v_mfma_f32_16x16x32_bf16 v[16:19], v[172:175], v[194:197], v[16:19]
	v_mfma_f32_16x16x32_bf16 v[20:23], v[164:167], v[194:197], v[20:23]
	v_mfma_f32_16x16x32_bf16 v[20:23], v[160:163], v[184:187], v[20:23]
	v_mfma_f32_16x16x32_bf16 v[12:15], v[160:163], v[198:201], v[12:15]
	v_mfma_f32_16x16x32_bf16 v[12:15], v[164:167], v[202:205], v[12:15]
	v_mfma_f32_16x16x32_bf16 v[8:11], v[172:175], v[202:205], v[8:11]
	v_mfma_f32_16x16x32_bf16 v[8:11], v[168:171], v[198:201], v[8:11]
	v_mfma_f32_16x16x32_bf16 v[0:3], v[168:171], v[206:209], v[0:3]
	v_mfma_f32_16x16x32_bf16 v[0:3], v[172:175], v[210:213], v[0:3]
	v_mfma_f32_16x16x32_bf16 v[4:7], v[164:167], v[210:213], v[4:7]
	v_mfma_f32_16x16x32_bf16 v[4:7], v[160:163], v[206:209], v[4:7]
	s_setprio 0
	s_barrier
; #define PG8_STAGE(bufoff, gbase, voff) do { _Pragma("unroll") for (int _i = 0; _i < 2; ++_i) \
;         __builtin_amdgcn_global_load_lds((const unsigned*)((const char*)(gbase) + (voff)[_i]), (PG8_LAS unsigned*)(lds + (bufoff) + ldsw + _i * 8192), 16, 0, 0); } while (0)
; #define PG8_LDA(dst, b, h) do { _Pragma("unroll") for (int m = 0; m < 4; ++m) _Pragma("unroll") for (int k = 0; k < 2; ++k) dst[m][k] = *(const PG8_LAS bf16x8*)(lds + PG8_SA(b, h) + aoff + m * 2048 + k * 1024); } while (0)
; #define PG8_LDB(dst, b, h) do { _Pragma("unroll") for (int n = 0; n < 2; ++n) _Pragma("unroll") for (int k = 0; k < 2; ++k) dst[n][k] = *(const PG8_LAS bf16x8*)(lds + PG8_SB(b, h) + boff + n * 2048 + k * 1024); } while (0)
; #define PG8_WAIT_V(n) asm volatile("s_waitcnt vmcnt(" #n ")" ::: "memory")
; #define PG8_WAIT_L(n) asm volatile("s_waitcnt lgkmcnt(" #n ")" ::: "memory")
; #define PG8_BAR __builtin_amdgcn_s_barrier()
; #define PG8_SCHED __builtin_amdgcn_sched_barrier(0)
; template <class Epi, class Sched, bool ALIGN_EPI = false, bool SP2 = false>
; __device__ __forceinline__ void gemm_phase(PG8_LAS unsigned char* lds, const Gemm g, const Sched& S, const Epi& E, int tid_in) {
;     ...
;             PG8_LDB(B0, 1, 0); PG8_LDB(B1, 1, 1); PG8_SCHED; PG8_LDA(At, 1, 0); PG8_STAGE(PG8_SA(0, 1), a2 + hstepA, voffA);
;             PG8_WAIT_V(8); PG8_WAIT_L(0); PG8_BAR; PG8_MMA(0, 0, At, B0); PG8_MMA(0, 1, At, B1); PG8_BAR; PG8_SCHED;
;             PG8_LDA(At, 1, 1); PG8_STAGE(PG8_SB(1, 0), b3, voffB); PG8_STAGE(PG8_SB(1, 1), b3 + hstep, voffB); PG8_STAGE(PG8_SA(1, 0), a3, voffA);
;             PG8_WAIT_V(8); PG8_WAIT_L(0); PG8_BAR; PG8_MMA(1, 0, At, B0); PG8_MMA(1, 1, At, B1); PG8_BAR; PG8_SCHED;
	s_add_i32 s54, 0, 0x18000
	s_add_i32 s55, 0, 0x1c000
	v_add_u32_e32 v156, s54, v189
	v_add_u32_e32 v172, s55, v189
	ds_read_b128 v[128:131], v156
	ds_read_b128 v[132:135], v156 offset:1024
	ds_read_b128 v[152:155], v156 offset:2048
	ds_read_b128 v[156:159], v156 offset:3072
	ds_read_b128 v[160:163], v172
	ds_read_b128 v[164:167], v172 offset:1024
	ds_read_b128 v[168:171], v172 offset:2048
	ds_read_b128 v[172:175], v172 offset:3072
	s_add_u32 s20, s26, 0x2b0000
	s_addc_u32 s21, s27, 0
	s_mov_b32 m0, s36
	ds_read_b128 v[176:179], v193 offset:32768
	ds_read_b128 v[180:183], v193 offset:33792
	ds_read_b128 v[184:187], v193 offset:34816
	ds_read_b128 v[194:197], v193 offset:35840
	ds_read_b128 v[198:201], v193 offset:36864
	ds_read_b128 v[202:205], v193 offset:37888
	ds_read_b128 v[206:209], v193 offset:38912
	ds_read_b128 v[210:213], v193 offset:39936
	global_load_lds_dwordx4 v136, s[20:21]
	s_mov_b32 m0, s37
	s_nop 0
	global_load_lds_dwordx4 v140, s[20:21]
	s_waitcnt vmcnt(8)
	s_waitcnt lgkmcnt(0)
	s_barrier
	s_setprio 1
	s_waitcnt lgkmcnt(0)
	v_mfma_f32_16x16x32_bf16 v[124:127], v[128:131], v[176:179], v[124:127]
	v_mfma_f32_16x16x32_bf16 v[124:127], v[132:135], v[180:183], v[124:127]
	v_mfma_f32_16x16x32_bf16 v[120:123], v[156:159], v[180:183], v[120:123]
	v_mfma_f32_16x16x32_bf16 v[120:123], v[152:155], v[176:179], v[120:123]
	v_mfma_f32_16x16x32_bf16 v[112:115], v[152:155], v[184:187], v[112:115]
	v_mfma_f32_16x16x32_bf16 v[112:115], v[156:159], v[194:197], v[112:115]
	v_mfma_f32_16x16x32_bf16 v[116:119], v[132:135], v[194:197], v[116:119]
	v_mfma_f32_16x16x32_bf16 v[116:119], v[128:131], v[184:187], v[116:119]
	v_mfma_f32_16x16x32_bf16 v[108:111], v[128:131], v[198:201], v[108:111]
	v_mfma_f32_16x16x32_bf16 v[108:111], v[132:135], v[202:205], v[108:111]
	v_mfma_f32_16x16x32_bf16 v[104:107], v[156:159], v[202:205], v[104:107]
	v_mfma_f32_16x16x32_bf16 v[104:107], v[152:155], v[198:201], v[104:107]
	v_mfma_f32_16x16x32_bf16 v[96:99], v[152:155], v[206:209], v[96:99]
	v_mfma_f32_16x16x32_bf16 v[96:99], v[156:159], v[210:213], v[96:99]
	v_mfma_f32_16x16x32_bf16 v[100:103], v[132:135], v[210:213], v[100:103]
	v_mfma_f32_16x16x32_bf16 v[100:103], v[128:131], v[206:209], v[100:103]
	s_setprio 0
	s_setprio 1
	v_mfma_f32_16x16x32_bf16 v[60:63], v[160:163], v[176:179], v[60:63]
	v_mfma_f32_16x16x32_bf16 v[60:63], v[164:167], v[180:183], v[60:63]
	v_mfma_f32_16x16x32_bf16 v[56:59], v[172:175], v[180:183], v[56:59]
	v_mfma_f32_16x16x32_bf16 v[56:59], v[168:171], v[176:179], v[56:59]
	v_mfma_f32_16x16x32_bf16 v[48:51], v[168:171], v[184:187], v[48:51]
	v_mfma_f32_16x16x32_bf16 v[48:51], v[172:175], v[194:197], v[48:51]
	v_mfma_f32_16x16x32_bf16 v[52:55], v[164:167], v[194:197], v[52:55]
	v_mfma_f32_16x16x32_bf16 v[52:55], v[160:163], v[184:187], v[52:55]
	v_mfma_f32_16x16x32_bf16 v[44:47], v[160:163], v[198:201], v[44:47]
	v_mfma_f32_16x16x32_bf16 v[44:47], v[164:167], v[202:205], v[44:47]
	v_mfma_f32_16x16x32_bf16 v[40:43], v[172:175], v[202:205], v[40:43]
	v_mfma_f32_16x16x32_bf16 v[40:43], v[168:171], v[198:201], v[40:43]
	v_mfma_f32_16x16x32_bf16 v[32:35], v[168:171], v[206:209], v[32:35]
	v_mfma_f32_16x16x32_bf16 v[32:35], v[172:175], v[210:213], v[32:35]
	v_mfma_f32_16x16x32_bf16 v[36:39], v[164:167], v[210:213], v[36:39]
	v_mfma_f32_16x16x32_bf16 v[36:39], v[160:163], v[206:209], v[36:39]
	s_setprio 0
	s_barrier
	s_add_i32 s20, s54, s33
	s_mov_b32 m0, s20
	ds_read_b128 v[176:179], v193 offset:49152
	ds_read_b128 v[180:183], v193 offset:50176
	ds_read_b128 v[184:187], v193 offset:51200
	ds_read_b128 v[194:197], v193 offset:52224
	ds_read_b128 v[198:201], v193 offset:53248
	ds_read_b128 v[202:205], v193 offset:54272
	ds_read_b128 v[206:209], v193 offset:55296
	ds_read_b128 v[210:213], v193 offset:56320
	global_load_lds_dwordx4 v138, s[98:99]
	s_add_i32 m0, s20, 0x2000
	s_add_u32 s20, s24, 0x2b0080
	s_addc_u32 s21, s25, 0
	s_add_i32 s24, s55, s33
	global_load_lds_dwordx4 v142, s[98:99]
	s_mov_b32 m0, s24
	s_nop 0
	global_load_lds_dwordx4 v138, s[20:21]
	s_add_i32 m0, s24, 0x2000
	s_nop 0
	global_load_lds_dwordx4 v142, s[20:21]
	s_mov_b32 m0, s42
	s_nop 0
	global_load_lds_dwordx4 v136, s[100:101]
	s_mov_b32 m0, s43
	s_nop 0
	global_load_lds_dwordx4 v140, s[100:101]
	s_waitcnt vmcnt(8)
	s_waitcnt lgkmcnt(0)
	s_barrier
	s_setprio 1
	s_waitcnt lgkmcnt(0)
	v_mfma_f32_16x16x32_bf16 v[92:95], v[128:131], v[176:179], v[92:95]
	v_mfma_f32_16x16x32_bf16 v[92:95], v[132:135], v[180:183], v[92:95]
	v_mfma_f32_16x16x32_bf16 v[88:91], v[156:159], v[180:183], v[88:91]
	v_mfma_f32_16x16x32_bf16 v[88:91], v[152:155], v[176:179], v[88:91]
	v_mfma_f32_16x16x32_bf16 v[80:83], v[152:155], v[184:187], v[80:83]
	v_mfma_f32_16x16x32_bf16 v[80:83], v[156:159], v[194:197], v[80:83]
	v_mfma_f32_16x16x32_bf16 v[84:87], v[132:135], v[194:197], v[84:87]
	v_mfma_f32_16x16x32_bf16 v[84:87], v[128:131], v[184:187], v[84:87]
	v_mfma_f32_16x16x32_bf16 v[76:79], v[128:131], v[198:201], v[76:79]
	v_mfma_f32_16x16x32_bf16 v[76:79], v[132:135], v[202:205], v[76:79]
	v_mfma_f32_16x16x32_bf16 v[72:75], v[156:159], v[202:205], v[72:75]
	v_mfma_f32_16x16x32_bf16 v[72:75], v[152:155], v[198:201], v[72:75]
	v_mfma_f32_16x16x32_bf16 v[64:67], v[152:155], v[206:209], v[64:67]
	v_mfma_f32_16x16x32_bf16 v[64:67], v[156:159], v[210:213], v[64:67]
	v_mfma_f32_16x16x32_bf16 v[68:71], v[132:135], v[210:213], v[68:71]
	v_mfma_f32_16x16x32_bf16 v[68:71], v[128:131], v[206:209], v[68:71]
	s_setprio 0
	s_setprio 1
	v_mfma_f32_16x16x32_bf16 v[28:31], v[160:163], v[176:179], v[28:31]
	v_mfma_f32_16x16x32_bf16 v[28:31], v[164:167], v[180:183], v[28:31]
	v_mfma_f32_16x16x32_bf16 v[24:27], v[172:175], v[180:183], v[24:27]
	v_mfma_f32_16x16x32_bf16 v[24:27], v[168:171], v[176:179], v[24:27]
	v_mfma_f32_16x16x32_bf16 v[16:19], v[168:171], v[184:187], v[16:19]
	v_mfma_f32_16x16x32_bf16 v[16:19], v[172:175], v[194:197], v[16:19]
	v_mfma_f32_16x16x32_bf16 v[20:23], v[164:167], v[194:197], v[20:23]
	v_mfma_f32_16x16x32_bf16 v[20:23], v[160:163], v[184:187], v[20:23]
	v_mfma_f32_16x16x32_bf16 v[12:15], v[160:163], v[198:201], v[12:15]
	v_mfma_f32_16x16x32_bf16 v[12:15], v[164:167], v[202:205], v[12:15]
	v_mfma_f32_16x16x32_bf16 v[8:11], v[172:175], v[202:205], v[8:11]
	v_mfma_f32_16x16x32_bf16 v[8:11], v[168:171], v[198:201], v[8:11]
	v_mfma_f32_16x16x32_bf16 v[0:3], v[168:171], v[206:209], v[0:3]
	v_mfma_f32_16x16x32_bf16 v[0:3], v[172:175], v[210:213], v[0:3]
	v_mfma_f32_16x16x32_bf16 v[4:7], v[164:167], v[210:213], v[4:7]
	v_mfma_f32_16x16x32_bf16 v[4:7], v[160:163], v[206:209], v[4:7]
	s_setprio 0
	s_barrier
	s_add_i32 s53, s53, 2
	s_add_u32 s51, s51, 0x100
	s_addc_u32 s52, s52, 0
	s_cmpk_gt_u32 s53, 0xa9
	s_mov_b64 s[20:21], s[22:23]
	s_cbranch_scc0 .LBB0_1328
	s_and_b64 vcc, exec, s[14:15]
	s_cbranch_vccz .LBB0_1331
	s_barrier
;     __device__ __forceinline__ void operator()(const f32x4 (&acc)[2][2][4][2], const Unit& u, int wr, int wc, int fr, int fq) const {
;         typedef float f2_ __attribute__((ext_vector_type(2)));
;         const int row0 = u.pm * BM + wr * 64 + fr, col0 = u.pn * BM + wc * 32 + 8 * fq;
;         const float* g = gate + (size_t)(u.pm >> 4) * 24576;
; #pragma unroll
;         for (int bj = 0; bj < 2; ++bj) { const int col = col0 + bj * HALF; const f32x4 g0 = *(const f32x4*)(g + col), g1 = *(const f32x4*)(g + col + 4);
;             const f32x4 a0 = *(const f32x4*)(ln_g + col) * alpha, a1 = *(const f32x4*)(ln_g + col + 4) * alpha, b0 = *(const f32x4*)(ln_b + col) * alpha, b1 = *(const f32x4*)(ln_b + col + 4) * alpha;
; #pragma unroll
;             for (int ai = 0; ai < 2; ++ai)
; #pragma unroll
;                 for (int m = 0; m < 4; ++m) { const size_t row = (size_t)(row0 + ai * HALF + m * 16), off = row * 4096 + col; const f2_ st = *(const f2_*)(stats + 2 * row); const float mean = st.x, rstd = st.y;
;                     const f32x4 x0 = (*(const f32x4*)(r1 + off) - mean) * rstd, x1 = (*(const f32x4*)(r1 + off + 4) - mean) * rstd;
;                     *(f32x4*)(out + off) = x0 * a0 + b0 + g0 * acc[ai][bj][m][0]; *(f32x4*)(out + off + 4) = x1 * a1 + b1 + g1 * acc[ai][bj][m][1]; } }
.LBB0_1331:
	v_lshl_add_u32 v178, s49, 8, v188
	v_lshl_or_b32 v177, s50, 8, v190
	v_readlane_b32 s52, v254, 32
	v_readlane_b32 s56, v254, 36
	v_readlane_b32 s57, v254, 37
	v_readlane_b32 s58, v254, 38
	v_readlane_b32 s59, v254, 39
	v_lshlrev_b32_e32 v176, 3, v178
	v_lshl_add_u32 v178, v178, 12, v177
	v_lshlrev_b32_e32 v177, 2, v177
	v_lshlrev_b32_e32 v168, 2, v178
	s_mov_b64 s[20:21], s[56:57]
	s_mov_b64 s[22:23], s[58:59]
	s_ashr_i32 s20, s49, 4
	s_mul_hi_i32 s21, s20, 0x18000
	s_mul_i32 s20, s20, 0x18000
	s_add_u32 s20, s40, s20
	s_addc_u32 s21, s41, s21
	v_add_u32_e32 v169, 0x40000, v168
	v_add_u32_e32 v170, 0x80000, v168
	v_add_u32_e32 v171, 0xc0000, v168
	v_add_u32_e32 v172, 0x200000, v168
	v_add_u32_e32 v173, 0x240000, v168
	v_add_u32_e32 v174, 0x280000, v168
	v_add_u32_e32 v175, 0x2c0000, v168
	global_load_dwordx4 v[128:131], v177, s[56:57]
	global_load_dwordx4 v[132:135], v177, s[56:57] offset:16
	global_load_dwordx4 v[152:155], v177, s[22:23]
	global_load_dwordx4 v[156:159], v177, s[22:23] offset:16
	global_load_dwordx4 v[160:163], v177, s[20:21]
	global_load_dwordx4 v[164:167], v177, s[20:21] offset:16
	global_load_dwordx2 v[186:187], v176, s[10:11]
	global_load_dwordx4 v[178:181], v168, s[8:9]
	global_load_dwordx4 v[182:185], v168, s[8:9] offset:16
	global_load_dwordx2 v[202:203], v176, s[10:11] offset:128
	global_load_dwordx4 v[194:197], v169, s[8:9]
	global_load_dwordx4 v[198:201], v169, s[8:9] offset:16
	global_load_dwordx2 v[212:213], v176, s[10:11] offset:256
	global_load_dwordx4 v[204:207], v170, s[8:9]
	global_load_dwordx4 v[208:211], v170, s[8:9] offset:16
	global_load_dwordx2 v[222:223], v176, s[10:11] offset:384
	global_load_dwordx4 v[214:217], v171, s[8:9]
	global_load_dwordx4 v[218:221], v171, s[8:9] offset:16
	s_and_b64 vcc, exec, s[2:3]
	s_mov_b64 s[2:3], -1
	v_readlane_b32 s53, v254, 33
	v_readlane_b32 s54, v254, 34
	v_readlane_b32 s55, v254, 35
	v_readlane_b32 s60, v254, 40
	v_readlane_b32 s61, v254, 41
	v_readlane_b32 s62, v254, 42
	v_readlane_b32 s63, v254, 43
	v_readlane_b32 s64, v254, 44
	v_readlane_b32 s65, v254, 45
	v_readlane_b32 s66, v254, 46
	v_readlane_b32 s67, v254, 47
	s_waitcnt vmcnt(12)
	v_pk_mul_f32 v[128:129], v[128:129], s[16:17] op_sel_hi:[1,0]
	v_pk_mul_f32 v[130:131], v[130:131], s[16:17] op_sel_hi:[1,0]
	v_pk_mul_f32 v[132:133], v[132:133], s[16:17] op_sel_hi:[1,0]
	v_pk_mul_f32 v[134:135], v[134:135], s[16:17] op_sel_hi:[1,0]
	v_pk_mul_f32 v[152:153], v[152:153], s[16:17] op_sel_hi:[1,0]
	v_pk_mul_f32 v[154:155], v[154:155], s[16:17] op_sel_hi:[1,0]
	v_pk_mul_f32 v[156:157], v[156:157], s[16:17] op_sel_hi:[1,0]
	v_pk_mul_f32 v[158:159], v[158:159], s[16:17] op_sel_hi:[1,0]
	s_waitcnt vmcnt(9)
	v_sub_f32_e32 v179, v179, v186
	v_sub_f32_e32 v178, v178, v186
	v_sub_f32_e32 v181, v181, v186
	v_sub_f32_e32 v180, v180, v186
	v_sub_f32_e32 v183, v183, v186
	v_sub_f32_e32 v182, v182, v186
	v_sub_f32_e32 v185, v185, v186
	v_sub_f32_e32 v184, v184, v186
	v_pk_mul_f32 v[180:181], v[186:187], v[180:181] op_sel:[1,0]
	v_pk_mul_f32 v[178:179], v[186:187], v[178:179] op_sel:[1,0]
	v_pk_mul_f32 v[184:185], v[186:187], v[184:185] op_sel:[1,0]
	v_pk_mul_f32 v[182:183], v[186:187], v[182:183] op_sel:[1,0]
	v_pk_fma_f32 v[178:179], v[128:129], v[178:179], v[152:153]
	v_pk_fma_f32 v[180:181], v[130:131], v[180:181], v[154:155]
	v_pk_fma_f32 v[182:183], v[132:133], v[182:183], v[156:157]
	v_pk_fma_f32 v[184:185], v[134:135], v[184:185], v[158:159]
	v_pk_fma_f32 v[126:127], v[126:127], v[162:163], v[180:181]
	v_pk_fma_f32 v[124:125], v[124:125], v[160:161], v[178:179]
	v_pk_fma_f32 v[122:123], v[122:123], v[166:167], v[184:185]
	v_pk_fma_f32 v[120:121], v[120:121], v[164:165], v[182:183]
	global_store_dwordx4 v168, v[124:127], s[92:93] nt
	global_store_dwordx4 v168, v[120:123], s[92:93] offset:16 nt
	global_load_dwordx2 v[186:187], v176, s[10:11] offset:1024
	global_load_dwordx4 v[178:181], v172, s[8:9]
	global_load_dwordx4 v[182:185], v172, s[8:9] offset:16
	s_waitcnt vmcnt(11)
	v_sub_f32_e32 v195, v195, v202
	v_sub_f32_e32 v194, v194, v202
	v_sub_f32_e32 v197, v197, v202
	v_sub_f32_e32 v196, v196, v202
	v_sub_f32_e32 v199, v199, v202
	v_sub_f32_e32 v198, v198, v202
	v_sub_f32_e32 v201, v201, v202
	v_sub_f32_e32 v200, v200, v202
	v_pk_mul_f32 v[196:197], v[202:203], v[196:197] op_sel:[1,0]
	v_pk_mul_f32 v[194:195], v[202:203], v[194:195] op_sel:[1,0]
	v_pk_mul_f32 v[200:201], v[202:203], v[200:201] op_sel:[1,0]
	v_pk_mul_f32 v[198:199], v[202:203], v[198:199] op_sel:[1,0]
	v_pk_fma_f32 v[194:195], v[128:129], v[194:195], v[152:153]
	v_pk_fma_f32 v[196:197], v[130:131], v[196:197], v[154:155]
	v_pk_fma_f32 v[198:199], v[132:133], v[198:199], v[156:157]
	v_pk_fma_f32 v[200:201], v[134:135], v[200:201], v[158:159]
	v_pk_fma_f32 v[118:119], v[118:119], v[162:163], v[196:197]
	v_pk_fma_f32 v[116:117], v[116:117], v[160:161], v[194:195]
	v_pk_fma_f32 v[114:115], v[114:115], v[166:167], v[200:201]
	v_pk_fma_f32 v[112:113], v[112:113], v[164:165], v[198:199]
	global_store_dwordx4 v169, v[116:119], s[92:93] nt
	global_store_dwordx4 v169, v[112:115], s[92:93] offset:16 nt
	global_load_dwordx2 v[202:203], v176, s[10:11] offset:1152
	global_load_dwordx4 v[194:197], v173, s[8:9]
	global_load_dwordx4 v[198:201], v173, s[8:9] offset:16
	s_waitcnt vmcnt(13)
;     __device__ __forceinline__ void operator()(const f32x4 (&acc)[2][2][4][2], const Unit& u, int wr, int wc, int fr, int fq) const {
;     ...
;             for (int ai = 0; ai < 2; ++ai)
; #pragma unroll
;                 for (int m = 0; m < 4; ++m) { const size_t row = (size_t)(row0 + ai * HALF + m * 16), off = row * 4096 + col; const f2_ st = *(const f2_*)(stats + 2 * row); const float mean = st.x, rstd = st.y;
;                     const f32x4 x0 = (*(const f32x4*)(r1 + off) - mean) * rstd, x1 = (*(const f32x4*)(r1 + off + 4) - mean) * rstd;
;                     *(f32x4*)(out + off) = x0 * a0 + b0 + g0 * acc[ai][bj][m][0]; *(f32x4*)(out + off + 4) = x1 * a1 + b1 + g1 * acc[ai][bj][m][1]; } }
	v_sub_f32_e32 v205, v205, v212
	v_sub_f32_e32 v204, v204, v212
	v_sub_f32_e32 v207, v207, v212
	v_sub_f32_e32 v206, v206, v212
	v_sub_f32_e32 v209, v209, v212
	v_sub_f32_e32 v208, v208, v212
	v_sub_f32_e32 v211, v211, v212
	v_sub_f32_e32 v210, v210, v212
	v_pk_mul_f32 v[206:207], v[212:213], v[206:207] op_sel:[1,0]
	v_pk_mul_f32 v[204:205], v[212:213], v[204:205] op_sel:[1,0]
	v_pk_mul_f32 v[210:211], v[212:213], v[210:211] op_sel:[1,0]
	v_pk_mul_f32 v[208:209], v[212:213], v[208:209] op_sel:[1,0]
	v_pk_fma_f32 v[204:205], v[128:129], v[204:205], v[152:153]
	v_pk_fma_f32 v[206:207], v[130:131], v[206:207], v[154:155]
	v_pk_fma_f32 v[208:209], v[132:133], v[208:209], v[156:157]
	v_pk_fma_f32 v[210:211], v[134:135], v[210:211], v[158:159]
	v_pk_fma_f32 v[110:111], v[110:111], v[162:163], v[206:207]
	v_pk_fma_f32 v[108:109], v[108:109], v[160:161], v[204:205]
	v_pk_fma_f32 v[106:107], v[106:107], v[166:167], v[210:211]
	v_pk_fma_f32 v[104:105], v[104:105], v[164:165], v[208:209]
	global_store_dwordx4 v170, v[108:111], s[92:93] nt
	global_store_dwordx4 v170, v[104:107], s[92:93] offset:16 nt
	global_load_dwordx2 v[212:213], v176, s[10:11] offset:1280
	global_load_dwordx4 v[204:207], v174, s[8:9]
	global_load_dwordx4 v[208:211], v174, s[8:9] offset:16
	s_waitcnt vmcnt(15)
	v_sub_f32_e32 v215, v215, v222
	v_sub_f32_e32 v214, v214, v222
	v_sub_f32_e32 v217, v217, v222
	v_sub_f32_e32 v216, v216, v222
	v_sub_f32_e32 v219, v219, v222
	v_sub_f32_e32 v218, v218, v222
	v_sub_f32_e32 v221, v221, v222
	v_sub_f32_e32 v220, v220, v222
	v_pk_mul_f32 v[216:217], v[222:223], v[216:217] op_sel:[1,0]
	v_pk_mul_f32 v[214:215], v[222:223], v[214:215] op_sel:[1,0]
	v_pk_mul_f32 v[220:221], v[222:223], v[220:221] op_sel:[1,0]
	v_pk_mul_f32 v[218:219], v[222:223], v[218:219] op_sel:[1,0]
	v_pk_fma_f32 v[214:215], v[128:129], v[214:215], v[152:153]
	v_pk_fma_f32 v[216:217], v[130:131], v[216:217], v[154:155]
	v_pk_fma_f32 v[218:219], v[132:133], v[218:219], v[156:157]
	v_pk_fma_f32 v[220:221], v[134:135], v[220:221], v[158:159]
	v_pk_fma_f32 v[102:103], v[102:103], v[162:163], v[216:217]
	v_pk_fma_f32 v[100:101], v[100:101], v[160:161], v[214:215]
	v_pk_fma_f32 v[98:99], v[98:99], v[166:167], v[220:221]
	v_pk_fma_f32 v[96:97], v[96:97], v[164:165], v[218:219]
	global_store_dwordx4 v171, v[100:103], s[92:93] nt
	global_store_dwordx4 v171, v[96:99], s[92:93] offset:16 nt
	global_load_dwordx2 v[222:223], v176, s[10:11] offset:1408
	global_load_dwordx4 v[214:217], v175, s[8:9]
	global_load_dwordx4 v[218:221], v175, s[8:9] offset:16
	s_waitcnt vmcnt(15)
	v_sub_f32_e32 v179, v179, v186
	v_sub_f32_e32 v178, v178, v186
	v_sub_f32_e32 v181, v181, v186
	v_sub_f32_e32 v180, v180, v186
	v_sub_f32_e32 v183, v183, v186
	v_sub_f32_e32 v182, v182, v186
	v_sub_f32_e32 v185, v185, v186
	v_sub_f32_e32 v184, v184, v186
	v_pk_mul_f32 v[180:181], v[186:187], v[180:181] op_sel:[1,0]
	v_pk_mul_f32 v[178:179], v[186:187], v[178:179] op_sel:[1,0]
	v_pk_mul_f32 v[184:185], v[186:187], v[184:185] op_sel:[1,0]
	v_pk_mul_f32 v[182:183], v[186:187], v[182:183] op_sel:[1,0]
	v_pk_fma_f32 v[178:179], v[128:129], v[178:179], v[152:153]
	v_pk_fma_f32 v[180:181], v[130:131], v[180:181], v[154:155]
	v_pk_fma_f32 v[182:183], v[132:133], v[182:183], v[156:157]
	v_pk_fma_f32 v[184:185], v[134:135], v[184:185], v[158:159]
	v_pk_fma_f32 v[94:95], v[94:95], v[162:163], v[180:181]
	v_pk_fma_f32 v[92:93], v[92:93], v[160:161], v[178:179]
	v_pk_fma_f32 v[90:91], v[90:91], v[166:167], v[184:185]
	v_pk_fma_f32 v[88:89], v[88:89], v[164:165], v[182:183]
	global_store_dwordx4 v172, v[92:95], s[92:93] nt
	global_store_dwordx4 v172, v[88:91], s[92:93] offset:16 nt
	global_load_dwordx2 v[186:187], v176, s[10:11]
	global_load_dwordx4 v[178:181], v168, s[8:9] offset:512
	global_load_dwordx4 v[182:185], v168, s[8:9] offset:528
	s_waitcnt vmcnt(15)
	v_sub_f32_e32 v195, v195, v202
	v_sub_f32_e32 v194, v194, v202
	v_sub_f32_e32 v197, v197, v202
	v_sub_f32_e32 v196, v196, v202
	v_sub_f32_e32 v199, v199, v202
	v_sub_f32_e32 v198, v198, v202
	v_sub_f32_e32 v201, v201, v202
	v_sub_f32_e32 v200, v200, v202
	v_pk_mul_f32 v[196:197], v[202:203], v[196:197] op_sel:[1,0]
	v_pk_mul_f32 v[194:195], v[202:203], v[194:195] op_sel:[1,0]
	v_pk_mul_f32 v[200:201], v[202:203], v[200:201] op_sel:[1,0]
	v_pk_mul_f32 v[198:199], v[202:203], v[198:199] op_sel:[1,0]
	v_pk_fma_f32 v[194:195], v[128:129], v[194:195], v[152:153]
	v_pk_fma_f32 v[196:197], v[130:131], v[196:197], v[154:155]
	v_pk_fma_f32 v[198:199], v[132:133], v[198:199], v[156:157]
	v_pk_fma_f32 v[200:201], v[134:135], v[200:201], v[158:159]
	v_pk_fma_f32 v[86:87], v[86:87], v[162:163], v[196:197]
	v_pk_fma_f32 v[84:85], v[84:85], v[160:161], v[194:195]
	v_pk_fma_f32 v[82:83], v[82:83], v[166:167], v[200:201]
	v_pk_fma_f32 v[80:81], v[80:81], v[164:165], v[198:199]
	global_store_dwordx4 v173, v[84:87], s[92:93] nt
	global_store_dwordx4 v173, v[80:83], s[92:93] offset:16 nt
	global_load_dwordx2 v[202:203], v176, s[10:11] offset:128
	global_load_dwordx4 v[194:197], v169, s[8:9] offset:512
	global_load_dwordx4 v[198:201], v169, s[8:9] offset:528
	s_waitcnt vmcnt(15)
;     __device__ __forceinline__ void operator()(const f32x4 (&acc)[2][2][4][2], const Unit& u, int wr, int wc, int fr, int fq) const {
;     ...
; #pragma unroll
;         for (int bj = 0; bj < 2; ++bj) { const int col = col0 + bj * HALF; const f32x4 g0 = *(const f32x4*)(g + col), g1 = *(const f32x4*)(g + col + 4);
;             const f32x4 a0 = *(const f32x4*)(ln_g + col) * alpha, a1 = *(const f32x4*)(ln_g + col + 4) * alpha, b0 = *(const f32x4*)(ln_b + col) * alpha, b1 = *(const f32x4*)(ln_b + col + 4) * alpha;
; #pragma unroll
;             for (int ai = 0; ai < 2; ++ai)
; #pragma unroll
;                 for (int m = 0; m < 4; ++m) { const size_t row = (size_t)(row0 + ai * HALF + m * 16), off = row * 4096 + col; const f2_ st = *(const f2_*)(stats + 2 * row); const float mean = st.x, rstd = st.y;
;                     const f32x4 x0 = (*(const f32x4*)(r1 + off) - mean) * rstd, x1 = (*(const f32x4*)(r1 + off + 4) - mean) * rstd;
;                     *(f32x4*)(out + off) = x0 * a0 + b0 + g0 * acc[ai][bj][m][0]; *(f32x4*)(out + off + 4) = x1 * a1 + b1 + g1 * acc[ai][bj][m][1]; } }
	v_sub_f32_e32 v205, v205, v212
	v_sub_f32_e32 v204, v204, v212
	v_sub_f32_e32 v207, v207, v212
	v_sub_f32_e32 v206, v206, v212
	v_sub_f32_e32 v209, v209, v212
	v_sub_f32_e32 v208, v208, v212
	v_sub_f32_e32 v211, v211, v212
	v_sub_f32_e32 v210, v210, v212
	v_pk_mul_f32 v[206:207], v[212:213], v[206:207] op_sel:[1,0]
	v_pk_mul_f32 v[204:205], v[212:213], v[204:205] op_sel:[1,0]
	v_pk_mul_f32 v[210:211], v[212:213], v[210:211] op_sel:[1,0]
	v_pk_mul_f32 v[208:209], v[212:213], v[208:209] op_sel:[1,0]
	v_pk_fma_f32 v[204:205], v[128:129], v[204:205], v[152:153]
	v_pk_fma_f32 v[206:207], v[130:131], v[206:207], v[154:155]
	v_pk_fma_f32 v[208:209], v[132:133], v[208:209], v[156:157]
	v_pk_fma_f32 v[210:211], v[134:135], v[210:211], v[158:159]
	v_pk_fma_f32 v[78:79], v[78:79], v[162:163], v[206:207]
	v_pk_fma_f32 v[76:77], v[76:77], v[160:161], v[204:205]
	v_pk_fma_f32 v[74:75], v[74:75], v[166:167], v[210:211]
	v_pk_fma_f32 v[72:73], v[72:73], v[164:165], v[208:209]
	global_store_dwordx4 v174, v[76:79], s[92:93] nt
	global_store_dwordx4 v174, v[72:75], s[92:93] offset:16 nt
	global_load_dwordx2 v[212:213], v176, s[10:11] offset:256
	global_load_dwordx4 v[204:207], v170, s[8:9] offset:512
	global_load_dwordx4 v[208:211], v170, s[8:9] offset:528
	s_waitcnt vmcnt(15)
	v_sub_f32_e32 v215, v215, v222
	v_sub_f32_e32 v214, v214, v222
	v_sub_f32_e32 v217, v217, v222
	v_sub_f32_e32 v216, v216, v222
	v_sub_f32_e32 v219, v219, v222
	v_sub_f32_e32 v218, v218, v222
	v_sub_f32_e32 v221, v221, v222
	v_sub_f32_e32 v220, v220, v222
	v_pk_mul_f32 v[216:217], v[222:223], v[216:217] op_sel:[1,0]
	v_pk_mul_f32 v[214:215], v[222:223], v[214:215] op_sel:[1,0]
	v_pk_mul_f32 v[220:221], v[222:223], v[220:221] op_sel:[1,0]
	v_pk_mul_f32 v[218:219], v[222:223], v[218:219] op_sel:[1,0]
	v_pk_fma_f32 v[214:215], v[128:129], v[214:215], v[152:153]
	v_pk_fma_f32 v[216:217], v[130:131], v[216:217], v[154:155]
	v_pk_fma_f32 v[218:219], v[132:133], v[218:219], v[156:157]
	v_pk_fma_f32 v[220:221], v[134:135], v[220:221], v[158:159]
	v_pk_fma_f32 v[70:71], v[70:71], v[162:163], v[216:217]
	v_pk_fma_f32 v[68:69], v[68:69], v[160:161], v[214:215]
	v_pk_fma_f32 v[66:67], v[66:67], v[166:167], v[220:221]
	v_pk_fma_f32 v[64:65], v[64:65], v[164:165], v[218:219]
	global_store_dwordx4 v175, v[68:71], s[92:93] nt
	global_store_dwordx4 v175, v[64:67], s[92:93] offset:16 nt
	global_load_dwordx4 v[128:131], v177, s[56:57] offset:512
	global_load_dwordx4 v[132:135], v177, s[56:57] offset:528
	global_load_dwordx4 v[152:155], v177, s[22:23] offset:512
	global_load_dwordx4 v[156:159], v177, s[22:23] offset:528
	global_load_dwordx4 v[160:163], v177, s[20:21] offset:512
	global_load_dwordx4 v[164:167], v177, s[20:21] offset:528
	global_load_dwordx2 v[222:223], v176, s[10:11] offset:384
	global_load_dwordx4 v[214:217], v171, s[8:9] offset:512
	global_load_dwordx4 v[218:221], v171, s[8:9] offset:528
	s_waitcnt vmcnt(3)
	v_pk_mul_f32 v[128:129], v[128:129], s[16:17] op_sel_hi:[1,0]
	v_pk_mul_f32 v[130:131], v[130:131], s[16:17] op_sel_hi:[1,0]
	v_pk_mul_f32 v[132:133], v[132:133], s[16:17] op_sel_hi:[1,0]
	v_pk_mul_f32 v[134:135], v[134:135], s[16:17] op_sel_hi:[1,0]
	v_pk_mul_f32 v[152:153], v[152:153], s[16:17] op_sel_hi:[1,0]
	v_pk_mul_f32 v[154:155], v[154:155], s[16:17] op_sel_hi:[1,0]
	v_pk_mul_f32 v[156:157], v[156:157], s[16:17] op_sel_hi:[1,0]
	v_pk_mul_f32 v[158:159], v[158:159], s[16:17] op_sel_hi:[1,0]
	v_sub_f32_e32 v179, v179, v186
	v_sub_f32_e32 v178, v178, v186
	v_sub_f32_e32 v181, v181, v186
	v_sub_f32_e32 v180, v180, v186
	v_sub_f32_e32 v183, v183, v186
	v_sub_f32_e32 v182, v182, v186
	v_sub_f32_e32 v185, v185, v186
	v_sub_f32_e32 v184, v184, v186
	v_pk_mul_f32 v[180:181], v[186:187], v[180:181] op_sel:[1,0]
	v_pk_mul_f32 v[178:179], v[186:187], v[178:179] op_sel:[1,0]
	v_pk_mul_f32 v[184:185], v[186:187], v[184:185] op_sel:[1,0]
	v_pk_mul_f32 v[182:183], v[186:187], v[182:183] op_sel:[1,0]
	v_pk_fma_f32 v[178:179], v[128:129], v[178:179], v[152:153]
	v_pk_fma_f32 v[180:181], v[130:131], v[180:181], v[154:155]
	v_pk_fma_f32 v[182:183], v[132:133], v[182:183], v[156:157]
	v_pk_fma_f32 v[184:185], v[134:135], v[184:185], v[158:159]
	v_pk_fma_f32 v[62:63], v[62:63], v[162:163], v[180:181]
	v_pk_fma_f32 v[60:61], v[60:61], v[160:161], v[178:179]
	v_pk_fma_f32 v[58:59], v[58:59], v[166:167], v[184:185]
	v_pk_fma_f32 v[56:57], v[56:57], v[164:165], v[182:183]
	global_store_dwordx4 v168, v[60:63], s[92:93] offset:512 nt
	global_store_dwordx4 v168, v[56:59], s[92:93] offset:528 nt
	global_load_dwordx2 v[186:187], v176, s[10:11] offset:1024
	global_load_dwordx4 v[178:181], v172, s[8:9] offset:512
	global_load_dwordx4 v[182:185], v172, s[8:9] offset:528
	s_waitcnt vmcnt(21)
	v_sub_f32_e32 v195, v195, v202
	v_sub_f32_e32 v194, v194, v202
	v_sub_f32_e32 v197, v197, v202
	v_sub_f32_e32 v196, v196, v202
	v_sub_f32_e32 v199, v199, v202
	v_sub_f32_e32 v198, v198, v202
	v_sub_f32_e32 v201, v201, v202
	v_sub_f32_e32 v200, v200, v202
	v_pk_mul_f32 v[196:197], v[202:203], v[196:197] op_sel:[1,0]
	v_pk_mul_f32 v[194:195], v[202:203], v[194:195] op_sel:[1,0]
	v_pk_mul_f32 v[200:201], v[202:203], v[200:201] op_sel:[1,0]
	v_pk_mul_f32 v[198:199], v[202:203], v[198:199] op_sel:[1,0]
	v_pk_fma_f32 v[194:195], v[128:129], v[194:195], v[152:153]
	v_pk_fma_f32 v[196:197], v[130:131], v[196:197], v[154:155]
	v_pk_fma_f32 v[198:199], v[132:133], v[198:199], v[156:157]
	v_pk_fma_f32 v[200:201], v[134:135], v[200:201], v[158:159]
	v_pk_fma_f32 v[54:55], v[54:55], v[162:163], v[196:197]
	v_pk_fma_f32 v[52:53], v[52:53], v[160:161], v[194:195]
	v_pk_fma_f32 v[50:51], v[50:51], v[166:167], v[200:201]
	v_pk_fma_f32 v[48:49], v[48:49], v[164:165], v[198:199]
	global_store_dwordx4 v169, v[52:55], s[92:93] offset:512 nt
	global_store_dwordx4 v169, v[48:51], s[92:93] offset:528 nt
	global_load_dwordx2 v[202:203], v176, s[10:11] offset:1152
	global_load_dwordx4 v[194:197], v173, s[8:9] offset:512
	global_load_dwordx4 v[198:201], v173, s[8:9] offset:528
	s_waitcnt vmcnt(21)
;     __device__ __forceinline__ void operator()(const f32x4 (&acc)[2][2][4][2], const Unit& u, int wr, int wc, int fr, int fq) const {
;     ...
;             for (int ai = 0; ai < 2; ++ai)
; #pragma unroll
;                 for (int m = 0; m < 4; ++m) { const size_t row = (size_t)(row0 + ai * HALF + m * 16), off = row * 4096 + col; const f2_ st = *(const f2_*)(stats + 2 * row); const float mean = st.x, rstd = st.y;
;                     const f32x4 x0 = (*(const f32x4*)(r1 + off) - mean) * rstd, x1 = (*(const f32x4*)(r1 + off + 4) - mean) * rstd;
;                     *(f32x4*)(out + off) = x0 * a0 + b0 + g0 * acc[ai][bj][m][0]; *(f32x4*)(out + off + 4) = x1 * a1 + b1 + g1 * acc[ai][bj][m][1]; } }
	v_sub_f32_e32 v205, v205, v212
	v_sub_f32_e32 v204, v204, v212
	v_sub_f32_e32 v207, v207, v212
	v_sub_f32_e32 v206, v206, v212
	v_sub_f32_e32 v209, v209, v212
	v_sub_f32_e32 v208, v208, v212
	v_sub_f32_e32 v211, v211, v212
	v_sub_f32_e32 v210, v210, v212
	v_pk_mul_f32 v[206:207], v[212:213], v[206:207] op_sel:[1,0]
	v_pk_mul_f32 v[204:205], v[212:213], v[204:205] op_sel:[1,0]
	v_pk_mul_f32 v[210:211], v[212:213], v[210:211] op_sel:[1,0]
	v_pk_mul_f32 v[208:209], v[212:213], v[208:209] op_sel:[1,0]
	v_pk_fma_f32 v[204:205], v[128:129], v[204:205], v[152:153]
	v_pk_fma_f32 v[206:207], v[130:131], v[206:207], v[154:155]
	v_pk_fma_f32 v[208:209], v[132:133], v[208:209], v[156:157]
	v_pk_fma_f32 v[210:211], v[134:135], v[210:211], v[158:159]
	v_pk_fma_f32 v[46:47], v[46:47], v[162:163], v[206:207]
	v_pk_fma_f32 v[44:45], v[44:45], v[160:161], v[204:205]
	v_pk_fma_f32 v[42:43], v[42:43], v[166:167], v[210:211]
	v_pk_fma_f32 v[40:41], v[40:41], v[164:165], v[208:209]
	global_store_dwordx4 v170, v[44:47], s[92:93] offset:512 nt
	global_store_dwordx4 v170, v[40:43], s[92:93] offset:528 nt
	global_load_dwordx2 v[212:213], v176, s[10:11] offset:1280
	global_load_dwordx4 v[204:207], v174, s[8:9] offset:512
	global_load_dwordx4 v[208:211], v174, s[8:9] offset:528
	s_waitcnt vmcnt(15)
	v_sub_f32_e32 v215, v215, v222
	v_sub_f32_e32 v214, v214, v222
	v_sub_f32_e32 v217, v217, v222
	v_sub_f32_e32 v216, v216, v222
	v_sub_f32_e32 v219, v219, v222
	v_sub_f32_e32 v218, v218, v222
	v_sub_f32_e32 v221, v221, v222
	v_sub_f32_e32 v220, v220, v222
	v_pk_mul_f32 v[216:217], v[222:223], v[216:217] op_sel:[1,0]
	v_pk_mul_f32 v[214:215], v[222:223], v[214:215] op_sel:[1,0]
	v_pk_mul_f32 v[220:221], v[222:223], v[220:221] op_sel:[1,0]
	v_pk_mul_f32 v[218:219], v[222:223], v[218:219] op_sel:[1,0]
	v_pk_fma_f32 v[214:215], v[128:129], v[214:215], v[152:153]
	v_pk_fma_f32 v[216:217], v[130:131], v[216:217], v[154:155]
	v_pk_fma_f32 v[218:219], v[132:133], v[218:219], v[156:157]
	v_pk_fma_f32 v[220:221], v[134:135], v[220:221], v[158:159]
	v_pk_fma_f32 v[38:39], v[38:39], v[162:163], v[216:217]
	v_pk_fma_f32 v[36:37], v[36:37], v[160:161], v[214:215]
	v_pk_fma_f32 v[34:35], v[34:35], v[166:167], v[220:221]
	v_pk_fma_f32 v[32:33], v[32:33], v[164:165], v[218:219]
	global_store_dwordx4 v171, v[36:39], s[92:93] offset:512 nt
	global_store_dwordx4 v171, v[32:35], s[92:93] offset:528 nt
	global_load_dwordx2 v[222:223], v176, s[10:11] offset:1408
	global_load_dwordx4 v[214:217], v175, s[8:9] offset:512
	global_load_dwordx4 v[218:221], v175, s[8:9] offset:528
	s_waitcnt vmcnt(15)
	v_sub_f32_e32 v179, v179, v186
	v_sub_f32_e32 v178, v178, v186
	v_sub_f32_e32 v181, v181, v186
	v_sub_f32_e32 v180, v180, v186
	v_sub_f32_e32 v183, v183, v186
	v_sub_f32_e32 v182, v182, v186
	v_sub_f32_e32 v185, v185, v186
	v_sub_f32_e32 v184, v184, v186
	v_pk_mul_f32 v[180:181], v[186:187], v[180:181] op_sel:[1,0]
	v_pk_mul_f32 v[178:179], v[186:187], v[178:179] op_sel:[1,0]
	v_pk_mul_f32 v[184:185], v[186:187], v[184:185] op_sel:[1,0]
	v_pk_mul_f32 v[182:183], v[186:187], v[182:183] op_sel:[1,0]
	v_pk_fma_f32 v[178:179], v[128:129], v[178:179], v[152:153]
	v_pk_fma_f32 v[180:181], v[130:131], v[180:181], v[154:155]
	v_pk_fma_f32 v[182:183], v[132:133], v[182:183], v[156:157]
	v_pk_fma_f32 v[184:185], v[134:135], v[184:185], v[158:159]
	v_pk_fma_f32 v[30:31], v[30:31], v[162:163], v[180:181]
	v_pk_fma_f32 v[28:29], v[28:29], v[160:161], v[178:179]
	v_pk_fma_f32 v[26:27], v[26:27], v[166:167], v[184:185]
	v_pk_fma_f32 v[24:25], v[24:25], v[164:165], v[182:183]
	global_store_dwordx4 v172, v[28:31], s[92:93] offset:512 nt
	global_store_dwordx4 v172, v[24:27], s[92:93] offset:528 nt
	s_waitcnt vmcnt(12)
	v_sub_f32_e32 v195, v195, v202
	v_sub_f32_e32 v194, v194, v202
	v_sub_f32_e32 v197, v197, v202
	v_sub_f32_e32 v196, v196, v202
	v_sub_f32_e32 v199, v199, v202
	v_sub_f32_e32 v198, v198, v202
	v_sub_f32_e32 v201, v201, v202
	v_sub_f32_e32 v200, v200, v202
	v_pk_mul_f32 v[196:197], v[202:203], v[196:197] op_sel:[1,0]
	v_pk_mul_f32 v[194:195], v[202:203], v[194:195] op_sel:[1,0]
	v_pk_mul_f32 v[200:201], v[202:203], v[200:201] op_sel:[1,0]
	v_pk_mul_f32 v[198:199], v[202:203], v[198:199] op_sel:[1,0]
	v_pk_fma_f32 v[194:195], v[128:129], v[194:195], v[152:153]
	v_pk_fma_f32 v[196:197], v[130:131], v[196:197], v[154:155]
	v_pk_fma_f32 v[198:199], v[132:133], v[198:199], v[156:157]
	v_pk_fma_f32 v[200:201], v[134:135], v[200:201], v[158:159]
	v_pk_fma_f32 v[22:23], v[22:23], v[162:163], v[196:197]
	v_pk_fma_f32 v[20:21], v[20:21], v[160:161], v[194:195]
	v_pk_fma_f32 v[18:19], v[18:19], v[166:167], v[200:201]
	v_pk_fma_f32 v[16:17], v[16:17], v[164:165], v[198:199]
	global_store_dwordx4 v173, v[20:23], s[92:93] offset:512 nt
	global_store_dwordx4 v173, v[16:19], s[92:93] offset:528 nt
	s_waitcnt vmcnt(9)
	v_sub_f32_e32 v205, v205, v212
	v_sub_f32_e32 v204, v204, v212
	v_sub_f32_e32 v207, v207, v212
	v_sub_f32_e32 v206, v206, v212
	v_sub_f32_e32 v209, v209, v212
	v_sub_f32_e32 v208, v208, v212
	v_sub_f32_e32 v211, v211, v212
	v_sub_f32_e32 v210, v210, v212
	v_pk_mul_f32 v[206:207], v[212:213], v[206:207] op_sel:[1,0]
	v_pk_mul_f32 v[204:205], v[212:213], v[204:205] op_sel:[1,0]
	v_pk_mul_f32 v[210:211], v[212:213], v[210:211] op_sel:[1,0]
	v_pk_mul_f32 v[208:209], v[212:213], v[208:209] op_sel:[1,0]
	v_pk_fma_f32 v[204:205], v[128:129], v[204:205], v[152:153]
	v_pk_fma_f32 v[206:207], v[130:131], v[206:207], v[154:155]
	v_pk_fma_f32 v[208:209], v[132:133], v[208:209], v[156:157]
	v_pk_fma_f32 v[210:211], v[134:135], v[210:211], v[158:159]
	v_pk_fma_f32 v[14:15], v[14:15], v[162:163], v[206:207]
	v_pk_fma_f32 v[12:13], v[12:13], v[160:161], v[204:205]
	v_pk_fma_f32 v[10:11], v[10:11], v[166:167], v[210:211]
	v_pk_fma_f32 v[8:9], v[8:9], v[164:165], v[208:209]
	global_store_dwordx4 v174, v[12:15], s[92:93] offset:512 nt
	global_store_dwordx4 v174, v[8:11], s[92:93] offset:528 nt
	s_waitcnt vmcnt(6)
	v_sub_f32_e32 v215, v215, v222
	v_sub_f32_e32 v214, v214, v222
	v_sub_f32_e32 v217, v217, v222
	v_sub_f32_e32 v216, v216, v222
	v_sub_f32_e32 v219, v219, v222
	v_sub_f32_e32 v218, v218, v222
	v_sub_f32_e32 v221, v221, v222
	v_sub_f32_e32 v220, v220, v222
	v_pk_mul_f32 v[216:217], v[222:223], v[216:217] op_sel:[1,0]
	v_pk_mul_f32 v[214:215], v[222:223], v[214:215] op_sel:[1,0]
	v_pk_mul_f32 v[220:221], v[222:223], v[220:221] op_sel:[1,0]
	v_pk_mul_f32 v[218:219], v[222:223], v[218:219] op_sel:[1,0]
	v_pk_fma_f32 v[214:215], v[128:129], v[214:215], v[152:153]
	v_pk_fma_f32 v[216:217], v[130:131], v[216:217], v[154:155]
	v_pk_fma_f32 v[218:219], v[132:133], v[218:219], v[156:157]
	v_pk_fma_f32 v[220:221], v[134:135], v[220:221], v[158:159]
	v_pk_fma_f32 v[6:7], v[6:7], v[162:163], v[216:217]
	v_pk_fma_f32 v[4:5], v[4:5], v[160:161], v[214:215]
	v_pk_fma_f32 v[2:3], v[2:3], v[166:167], v[220:221]
	v_pk_fma_f32 v[0:1], v[0:1], v[164:165], v[218:219]
	global_store_dwordx4 v175, v[4:7], s[92:93] offset:512 nt
	global_store_dwordx4 v175, v[0:3], s[92:93] offset:528 nt
	s_cbranch_vccnz .LBB0_1316
; #define PG8_BAR __builtin_amdgcn_s_barrier()
; template <class Epi, class Sched, bool ALIGN_EPI = false, bool SP2 = false>
; __device__ __forceinline__ void gemm_phase(PG8_LAS unsigned char* lds, const Gemm g, const Sched& S, const Epi& E, int tid_in) {
;     ...
;         cur = nxt; cA = nA; cB = nB; ++ui;
;         if constexpr (ALIGN_EPI) { if (wr == 1) PG8_BAR; }
;     }
	s_andn2_b64 vcc, exec, s[6:7]
	s_cbranch_vccnz .LBB0_1315
	s_barrier
	s_branch .LBB0_1315
